# GEMM K-loops: the back-to-back s_setprio 0 / s_setprio 1 pair in the middle of each 32-MFMA block removed (priority stays raised across the block)
# baseline (speedup 1.0000x reference)
; #define PG8_STAGE(bufoff, gbase, voff) do { _Pragma("unroll") for (int _i = 0; _i < 2; ++_i) \
;         __builtin_amdgcn_global_load_lds((const unsigned*)((const char*)(gbase) + (voff)[_i]), (PG8_LAS unsigned*)(lds + (bufoff) + ldsw + _i * 8192), 16, 0, 0); } while (0)
; #define PG8_LDA(dst, b, h) do { _Pragma("unroll") for (int m = 0; m < 4; ++m) _Pragma("unroll") for (int k = 0; k < 2; ++k) dst[m][k] = *(const PG8_LAS bf16x8*)(lds + PG8_SA(b, h) + aoff + m * 2048 + k * 1024); } while (0)
; #define PG8_LDB(dst, b, h) do { _Pragma("unroll") for (int n = 0; n < 2; ++n) _Pragma("unroll") for (int k = 0; k < 2; ++k) dst[n][k] = *(const PG8_LAS bf16x8*)(lds + PG8_SB(b, h) + boff + n * 2048 + k * 1024); } while (0)
; #define PG8_MMA(ai, bj, At, Bt) do { __builtin_amdgcn_s_setprio(1); _Pragma("unroll") for (int m = 0; m < 4; ++m) _Pragma("unroll") for (int n = 0; n < 2; ++n) _Pragma("unroll") for (int k = 0; k < 2; ++k) \
;         acc[ai][bj][m][n] = __builtin_amdgcn_mfma_f32_16x16x32_bf16(Bt[n][k], At[m][k], acc[ai][bj][m][n], 0, 0, 0); __builtin_amdgcn_s_setprio(0); } while (0)
; #define PG8_WAIT_V(n) asm volatile("s_waitcnt vmcnt(" #n ")" ::: "memory")
; #define PG8_WAIT_L(n) asm volatile("s_waitcnt lgkmcnt(" #n ")" ::: "memory")
; #define PG8_BAR __builtin_amdgcn_s_barrier()
; #define PG8_SCHED __builtin_amdgcn_sched_barrier(0)
; template <class Epi, class Sched, bool ALIGN_EPI = false, bool SP2 = false>
; __device__ __forceinline__ void gemm_phase(PG8_LAS unsigned char* lds, const Gemm g, const Sched& S, const Epi& E) {
;     ...
;             const char* a2 = last ? nA : cA + (size_t)(t + 2) * kstep; const char* b2 = last ? nB : cB + (size_t)(t + 2) * kstep;
;             const char* a3 = a2 + kstep; const char* b3 = b2 + kstep;
;             if (last && has_next) S.a_ready(nxt);
;             if constexpr (SP2) {
;             PG8_LDB(B0, 0, 0); PG8_LDB(B1, 0, 1); PG8_SCHED; PG8_LDA(At, 0, 0); PG8_STAGE(PG8_SA(1, 1), a1 + hstep, voffA);
;             PG8_WAIT_V(8); PG8_WAIT_L(0); PG8_BAR; PG8_MMA(0, 0, At, B0); PG8_MMA(0, 1, At, B1); PG8_BAR; PG8_SCHED;
;             PG8_LDA(At, 0, 1); PG8_STAGE(PG8_SB(0, 0), b2, voffB); PG8_STAGE(PG8_SB(0, 1), b2 + hstep, voffB); PG8_STAGE(PG8_SA(0, 0), a2, voffA);
;             PG8_WAIT_V(8); PG8_WAIT_L(0); PG8_BAR; PG8_MMA(1, 0, At, B0); PG8_MMA(1, 1, At, B1); PG8_BAR; PG8_SCHED;
.LBB0_499:
	s_add_i32 s22, s17, 2
	s_add_u32 s28, s2, 0x80
	s_addc_u32 s30, s3, 0
	s_add_i32 s33, 0, 0x10000
	s_cmp_eq_u32 s72, s17
	s_cselect_b32 s35, s53, s30
	s_cselect_b32 s34, s52, s28
	v_add_u32_e32 v146, s33, v148
	s_cselect_b32 s31, s55, s16
	s_cselect_b32 s30, s54, s4
	s_add_i32 s17, 0, 0x14000
	ds_read_b128 v[142:145], v146
	ds_read_b128 v[154:157], v146 offset:1024
	ds_read_b128 v[158:161], v146 offset:2048
	ds_read_b128 v[162:165], v146 offset:3072
	v_add_u32_e32 v146, s17, v148
	ds_read_b128 v[166:169], v146
	ds_read_b128 v[170:173], v146 offset:1024
	ds_read_b128 v[174:177], v146 offset:2048
	ds_read_b128 v[178:181], v146 offset:3072
	v_lshl_add_u64 v[146:147], s[2:3], 0, v[138:139]
	s_add_i32 m0, s65, 0xc000
	ds_read_b128 v[182:185], v153
	ds_read_b128 v[186:189], v153 offset:1024
	ds_read_b128 v[190:193], v153 offset:2048
	ds_read_b128 v[208:211], v153 offset:3072
	ds_read_b128 v[212:215], v153 offset:4096
	ds_read_b128 v[216:219], v153 offset:5120
	ds_read_b128 v[220:223], v153 offset:6144
	ds_read_b128 v[228:231], v153 offset:7168
	global_load_lds_dwordx4 v[146:147], off
	v_lshl_add_u64 v[146:147], s[2:3], 0, v[140:141]
	s_add_i32 m0, s65, 0xe000
	s_nop 0
	global_load_lds_dwordx4 v[146:147], off
	s_waitcnt vmcnt(8)
	s_waitcnt lgkmcnt(0)
	s_barrier
	s_setprio 1
	v_mfma_f32_16x16x32_bf16 v[124:127], v[142:145], v[182:185], v[124:127]
	v_mfma_f32_16x16x32_bf16 v[120:123], v[158:161], v[182:185], v[120:123]
	v_mfma_f32_16x16x32_bf16 v[112:115], v[142:145], v[190:193], v[112:115]
	v_mfma_f32_16x16x32_bf16 v[104:107], v[158:161], v[190:193], v[104:107]
	v_mfma_f32_16x16x32_bf16 v[94:97], v[142:145], v[212:215], v[94:97]
	v_mfma_f32_16x16x32_bf16 v[86:89], v[158:161], v[212:215], v[86:89]
	v_mfma_f32_16x16x32_bf16 v[78:81], v[142:145], v[220:223], v[78:81]
	v_mfma_f32_16x16x32_bf16 v[70:73], v[158:161], v[220:223], v[70:73]
	v_mfma_f32_16x16x32_bf16 v[124:127], v[154:157], v[186:189], v[124:127]
	v_mfma_f32_16x16x32_bf16 v[120:123], v[162:165], v[186:189], v[120:123]
	v_mfma_f32_16x16x32_bf16 v[112:115], v[154:157], v[208:211], v[112:115]
	v_mfma_f32_16x16x32_bf16 v[104:107], v[162:165], v[208:211], v[104:107]
	v_mfma_f32_16x16x32_bf16 v[94:97], v[154:157], v[216:219], v[94:97]
	v_mfma_f32_16x16x32_bf16 v[86:89], v[162:165], v[216:219], v[86:89]
	v_mfma_f32_16x16x32_bf16 v[78:81], v[154:157], v[228:231], v[78:81]
	v_mfma_f32_16x16x32_bf16 v[70:73], v[162:165], v[228:231], v[70:73]
	v_mfma_f32_16x16x32_bf16 v[128:131], v[166:169], v[182:185], v[128:131]
	v_mfma_f32_16x16x32_bf16 v[116:119], v[174:177], v[182:185], v[116:119]
	v_mfma_f32_16x16x32_bf16 v[108:111], v[166:169], v[190:193], v[108:111]
	v_mfma_f32_16x16x32_bf16 v[100:103], v[174:177], v[190:193], v[100:103]
	v_mfma_f32_16x16x32_bf16 v[90:93], v[166:169], v[212:215], v[90:93]
	v_mfma_f32_16x16x32_bf16 v[82:85], v[174:177], v[212:215], v[82:85]
	v_mfma_f32_16x16x32_bf16 v[74:77], v[166:169], v[220:223], v[74:77]
	v_mfma_f32_16x16x32_bf16 v[66:69], v[174:177], v[220:223], v[66:69]
	v_mfma_f32_16x16x32_bf16 v[128:131], v[170:173], v[186:189], v[128:131]
	v_mfma_f32_16x16x32_bf16 v[116:119], v[178:181], v[186:189], v[116:119]
	v_mfma_f32_16x16x32_bf16 v[108:111], v[170:173], v[208:211], v[108:111]
	v_mfma_f32_16x16x32_bf16 v[100:103], v[178:181], v[208:211], v[100:103]
	v_mfma_f32_16x16x32_bf16 v[90:93], v[170:173], v[216:219], v[90:93]
	v_mfma_f32_16x16x32_bf16 v[82:85], v[178:181], v[216:219], v[82:85]
	v_mfma_f32_16x16x32_bf16 v[74:77], v[170:173], v[228:231], v[74:77]
	v_mfma_f32_16x16x32_bf16 v[66:69], v[178:181], v[228:231], v[66:69]
	s_setprio 0
	s_barrier
	s_add_i32 s28, s33, s58
	v_lshl_add_u64 v[146:147], s[30:31], 0, v[98:99]
	s_mov_b32 m0, s28
	ds_read_b128 v[182:185], v153 offset:16384
	ds_read_b128 v[186:189], v153 offset:17408
	ds_read_b128 v[190:193], v153 offset:18432
	ds_read_b128 v[208:211], v153 offset:19456
	ds_read_b128 v[212:215], v153 offset:20480
	ds_read_b128 v[216:219], v153 offset:21504
	ds_read_b128 v[220:223], v153 offset:22528
	ds_read_b128 v[228:231], v153 offset:23552
	global_load_lds_dwordx4 v[146:147], off
	s_add_i32 m0, s28, 0x2000
	v_lshl_add_u64 v[224:225], s[30:31], 0, v[132:133]
	s_add_u32 s30, s30, s8
	s_addc_u32 s31, s31, s9
	s_add_i32 s17, s17, s58
	global_load_lds_dwordx4 v[224:225], off
	v_lshl_add_u64 v[232:233], s[30:31], 0, v[98:99]
	s_mov_b32 m0, s17
	v_lshl_add_u64 v[234:235], s[30:31], 0, v[132:133]
	global_load_lds_dwordx4 v[232:233], off
	s_add_i32 m0, s17, 0x2000
	v_lshl_add_u64 v[236:237], s[34:35], 0, v[136:137]
	global_load_lds_dwordx4 v[234:235], off
	s_mov_b32 m0, s65
	v_lshl_add_u64 v[238:239], s[34:35], 0, v[134:135]
	global_load_lds_dwordx4 v[236:237], off
	s_mov_b32 m0, s66
	s_nop 0
	global_load_lds_dwordx4 v[238:239], off
	s_waitcnt vmcnt(8)
	s_waitcnt lgkmcnt(0)
	s_barrier
; #define PG8_STAGE(bufoff, gbase, voff) do { _Pragma("unroll") for (int _i = 0; _i < 2; ++_i) \
;         __builtin_amdgcn_global_load_lds((const unsigned*)((const char*)(gbase) + (voff)[_i]), (PG8_LAS unsigned*)(lds + (bufoff) + ldsw + _i * 8192), 16, 0, 0); } while (0)
; #define PG8_LDA(dst, b, h) do { _Pragma("unroll") for (int m = 0; m < 4; ++m) _Pragma("unroll") for (int k = 0; k < 2; ++k) dst[m][k] = *(const PG8_LAS bf16x8*)(lds + PG8_SA(b, h) + aoff + m * 2048 + k * 1024); } while (0)
; #define PG8_LDB(dst, b, h) do { _Pragma("unroll") for (int n = 0; n < 2; ++n) _Pragma("unroll") for (int k = 0; k < 2; ++k) dst[n][k] = *(const PG8_LAS bf16x8*)(lds + PG8_SB(b, h) + boff + n * 2048 + k * 1024); } while (0)
; #define PG8_MMA(ai, bj, At, Bt) do { __builtin_amdgcn_s_setprio(1); _Pragma("unroll") for (int m = 0; m < 4; ++m) _Pragma("unroll") for (int n = 0; n < 2; ++n) _Pragma("unroll") for (int k = 0; k < 2; ++k) \
;         acc[ai][bj][m][n] = __builtin_amdgcn_mfma_f32_16x16x32_bf16(Bt[n][k], At[m][k], acc[ai][bj][m][n], 0, 0, 0); __builtin_amdgcn_s_setprio(0); } while (0)
; #define PG8_WAIT_V(n) asm volatile("s_waitcnt vmcnt(" #n ")" ::: "memory")
; #define PG8_WAIT_L(n) asm volatile("s_waitcnt lgkmcnt(" #n ")" ::: "memory")
; #define PG8_BAR __builtin_amdgcn_s_barrier()
; #define PG8_SCHED __builtin_amdgcn_sched_barrier(0)
; template <class Epi, class Sched, bool ALIGN_EPI = false, bool SP2 = false>
; __device__ __forceinline__ void gemm_phase(PG8_LAS unsigned char* lds, const Gemm g, const Sched& S, const Epi& E) {
;     ...
;             PG8_WAIT_V(8); PG8_WAIT_L(0); PG8_BAR; PG8_MMA(1, 0, At, B0); PG8_MMA(1, 1, At, B1); PG8_BAR; PG8_SCHED;
;             PG8_LDB(B0, 1, 0); PG8_LDB(B1, 1, 1); PG8_SCHED; PG8_LDA(At, 1, 0); PG8_STAGE(PG8_SA(0, 1), a2 + hstep, voffA);
;             PG8_WAIT_V(8); PG8_WAIT_L(0); PG8_BAR; PG8_MMA(0, 0, At, B0); PG8_MMA(0, 1, At, B1); PG8_BAR; PG8_SCHED;
	s_setprio 1
	v_mfma_f32_16x16x32_bf16 v[62:65], v[142:145], v[182:185], v[62:65]
	v_mfma_f32_16x16x32_bf16 v[54:57], v[158:161], v[182:185], v[54:57]
	v_mfma_f32_16x16x32_bf16 v[46:49], v[142:145], v[190:193], v[46:49]
	v_mfma_f32_16x16x32_bf16 v[38:41], v[158:161], v[190:193], v[38:41]
	v_mfma_f32_16x16x32_bf16 v[30:33], v[142:145], v[212:215], v[30:33]
	v_mfma_f32_16x16x32_bf16 v[22:25], v[158:161], v[212:215], v[22:25]
	v_mfma_f32_16x16x32_bf16 v[14:17], v[142:145], v[220:223], v[14:17]
	v_mfma_f32_16x16x32_bf16 v[6:9], v[158:161], v[220:223], v[6:9]
	v_mfma_f32_16x16x32_bf16 v[62:65], v[154:157], v[186:189], v[62:65]
	v_mfma_f32_16x16x32_bf16 v[54:57], v[162:165], v[186:189], v[54:57]
	v_mfma_f32_16x16x32_bf16 v[46:49], v[154:157], v[208:211], v[46:49]
	v_mfma_f32_16x16x32_bf16 v[38:41], v[162:165], v[208:211], v[38:41]
	v_mfma_f32_16x16x32_bf16 v[30:33], v[154:157], v[216:219], v[30:33]
	v_mfma_f32_16x16x32_bf16 v[22:25], v[162:165], v[216:219], v[22:25]
	v_mfma_f32_16x16x32_bf16 v[14:17], v[154:157], v[228:231], v[14:17]
	v_mfma_f32_16x16x32_bf16 v[6:9], v[162:165], v[228:231], v[6:9]
	v_mfma_f32_16x16x32_bf16 v[58:61], v[166:169], v[182:185], v[58:61]
	v_mfma_f32_16x16x32_bf16 v[50:53], v[174:177], v[182:185], v[50:53]
	v_mfma_f32_16x16x32_bf16 v[42:45], v[166:169], v[190:193], v[42:45]
	v_mfma_f32_16x16x32_bf16 v[34:37], v[174:177], v[190:193], v[34:37]
	v_mfma_f32_16x16x32_bf16 v[26:29], v[166:169], v[212:215], v[26:29]
	v_mfma_f32_16x16x32_bf16 v[18:21], v[174:177], v[212:215], v[18:21]
	v_mfma_f32_16x16x32_bf16 v[10:13], v[166:169], v[220:223], v[10:13]
	v_mfma_f32_16x16x32_bf16 v[2:5], v[174:177], v[220:223], v[2:5]
	v_mfma_f32_16x16x32_bf16 v[58:61], v[170:173], v[186:189], v[58:61]
	v_mfma_f32_16x16x32_bf16 v[50:53], v[178:181], v[186:189], v[50:53]
	v_mfma_f32_16x16x32_bf16 v[42:45], v[170:173], v[208:211], v[42:45]
	v_mfma_f32_16x16x32_bf16 v[34:37], v[178:181], v[208:211], v[34:37]
	v_mfma_f32_16x16x32_bf16 v[26:29], v[170:173], v[216:219], v[26:29]
	v_mfma_f32_16x16x32_bf16 v[18:21], v[178:181], v[216:219], v[18:21]
	v_mfma_f32_16x16x32_bf16 v[10:13], v[170:173], v[228:231], v[10:13]
	v_mfma_f32_16x16x32_bf16 v[2:5], v[178:181], v[228:231], v[2:5]
	s_setprio 0
	s_barrier
	s_add_i32 s17, 0, 0x18000
	s_add_i32 s28, 0, 0x1c000
	v_add_u32_e32 v162, s17, v148
	v_add_u32_e32 v178, s28, v148
	ds_read_b128 v[142:145], v162
	ds_read_b128 v[154:157], v162 offset:1024
	ds_read_b128 v[158:161], v162 offset:2048
	ds_read_b128 v[162:165], v162 offset:3072
	ds_read_b128 v[166:169], v178
	ds_read_b128 v[170:173], v178 offset:1024
	ds_read_b128 v[174:177], v178 offset:2048
	ds_read_b128 v[178:181], v178 offset:3072
	s_add_u32 s30, s34, s8
	s_addc_u32 s31, s35, s9
	s_mov_b32 m0, s67
	v_lshl_add_u64 v[240:241], s[30:31], 0, v[136:137]
	ds_read_b128 v[182:185], v153 offset:32768
	ds_read_b128 v[186:189], v153 offset:33792
	ds_read_b128 v[190:193], v153 offset:34816
	ds_read_b128 v[208:211], v153 offset:35840
	ds_read_b128 v[212:215], v153 offset:36864
	ds_read_b128 v[216:219], v153 offset:37888
	ds_read_b128 v[220:223], v153 offset:38912
	ds_read_b128 v[228:231], v153 offset:39936
	global_load_lds_dwordx4 v[240:241], off
	v_lshl_add_u64 v[240:241], s[30:31], 0, v[134:135]
	s_mov_b32 m0, s68
	s_nop 0
	global_load_lds_dwordx4 v[240:241], off
	s_waitcnt vmcnt(8)
	s_waitcnt lgkmcnt(0)
	s_barrier
	s_setprio 1
	v_mfma_f32_16x16x32_bf16 v[124:127], v[142:145], v[182:185], v[124:127]
	v_mfma_f32_16x16x32_bf16 v[120:123], v[158:161], v[182:185], v[120:123]
	v_mfma_f32_16x16x32_bf16 v[112:115], v[142:145], v[190:193], v[112:115]
	v_mfma_f32_16x16x32_bf16 v[104:107], v[158:161], v[190:193], v[104:107]
	v_mfma_f32_16x16x32_bf16 v[94:97], v[142:145], v[212:215], v[94:97]
	v_mfma_f32_16x16x32_bf16 v[86:89], v[158:161], v[212:215], v[86:89]
	v_mfma_f32_16x16x32_bf16 v[78:81], v[142:145], v[220:223], v[78:81]
	v_mfma_f32_16x16x32_bf16 v[70:73], v[158:161], v[220:223], v[70:73]
	v_mfma_f32_16x16x32_bf16 v[124:127], v[154:157], v[186:189], v[124:127]
	v_mfma_f32_16x16x32_bf16 v[120:123], v[162:165], v[186:189], v[120:123]
	v_mfma_f32_16x16x32_bf16 v[112:115], v[154:157], v[208:211], v[112:115]
	v_mfma_f32_16x16x32_bf16 v[104:107], v[162:165], v[208:211], v[104:107]
	v_mfma_f32_16x16x32_bf16 v[94:97], v[154:157], v[216:219], v[94:97]
	v_mfma_f32_16x16x32_bf16 v[86:89], v[162:165], v[216:219], v[86:89]
	v_mfma_f32_16x16x32_bf16 v[78:81], v[154:157], v[228:231], v[78:81]
	v_mfma_f32_16x16x32_bf16 v[70:73], v[162:165], v[228:231], v[70:73]
	v_mfma_f32_16x16x32_bf16 v[128:131], v[166:169], v[182:185], v[128:131]
	v_mfma_f32_16x16x32_bf16 v[116:119], v[174:177], v[182:185], v[116:119]
	v_mfma_f32_16x16x32_bf16 v[108:111], v[166:169], v[190:193], v[108:111]
	v_mfma_f32_16x16x32_bf16 v[100:103], v[174:177], v[190:193], v[100:103]
	v_mfma_f32_16x16x32_bf16 v[90:93], v[166:169], v[212:215], v[90:93]
	v_mfma_f32_16x16x32_bf16 v[82:85], v[174:177], v[212:215], v[82:85]
	v_mfma_f32_16x16x32_bf16 v[74:77], v[166:169], v[220:223], v[74:77]
	v_mfma_f32_16x16x32_bf16 v[66:69], v[174:177], v[220:223], v[66:69]
	v_mfma_f32_16x16x32_bf16 v[128:131], v[170:173], v[186:189], v[128:131]
	v_mfma_f32_16x16x32_bf16 v[116:119], v[178:181], v[186:189], v[116:119]
	v_mfma_f32_16x16x32_bf16 v[108:111], v[170:173], v[208:211], v[108:111]
	v_mfma_f32_16x16x32_bf16 v[100:103], v[178:181], v[208:211], v[100:103]
	v_mfma_f32_16x16x32_bf16 v[90:93], v[170:173], v[216:219], v[90:93]
	v_mfma_f32_16x16x32_bf16 v[82:85], v[178:181], v[216:219], v[82:85]
	v_mfma_f32_16x16x32_bf16 v[74:77], v[170:173], v[228:231], v[74:77]
	v_mfma_f32_16x16x32_bf16 v[66:69], v[178:181], v[228:231], v[66:69]
	s_setprio 0
	s_barrier
; #define PG8_STAGE(bufoff, gbase, voff) do { _Pragma("unroll") for (int _i = 0; _i < 2; ++_i) \
;         __builtin_amdgcn_global_load_lds((const unsigned*)((const char*)(gbase) + (voff)[_i]), (PG8_LAS unsigned*)(lds + (bufoff) + ldsw + _i * 8192), 16, 0, 0); } while (0)
; #define PG8_LDA(dst, b, h) do { _Pragma("unroll") for (int m = 0; m < 4; ++m) _Pragma("unroll") for (int k = 0; k < 2; ++k) dst[m][k] = *(const PG8_LAS bf16x8*)(lds + PG8_SA(b, h) + aoff + m * 2048 + k * 1024); } while (0)
; #define PG8_MMA(ai, bj, At, Bt) do { __builtin_amdgcn_s_setprio(1); _Pragma("unroll") for (int m = 0; m < 4; ++m) _Pragma("unroll") for (int n = 0; n < 2; ++n) _Pragma("unroll") for (int k = 0; k < 2; ++k) \
;         acc[ai][bj][m][n] = __builtin_amdgcn_mfma_f32_16x16x32_bf16(Bt[n][k], At[m][k], acc[ai][bj][m][n], 0, 0, 0); __builtin_amdgcn_s_setprio(0); } while (0)
; #define PG8_WAIT_V(n) asm volatile("s_waitcnt vmcnt(" #n ")" ::: "memory")
; #define PG8_WAIT_L(n) asm volatile("s_waitcnt lgkmcnt(" #n ")" ::: "memory")
; #define PG8_BAR __builtin_amdgcn_s_barrier()
; #define PG8_SCHED __builtin_amdgcn_sched_barrier(0)
; template <class Epi, class Sched, bool ALIGN_EPI = false, bool SP2 = false>
; __device__ __forceinline__ void gemm_phase(PG8_LAS unsigned char* lds, const Gemm g, const Sched& S, const Epi& E) {
;     ...
;             PG8_LDA(At, 1, 1); PG8_STAGE(PG8_SB(1, 0), b3, voffB); PG8_STAGE(PG8_SB(1, 1), b3 + hstep, voffB); PG8_STAGE(PG8_SA(1, 0), a3, voffA);
;             PG8_WAIT_V(8); PG8_WAIT_L(0); PG8_BAR; PG8_MMA(1, 0, At, B0); PG8_MMA(1, 1, At, B1); PG8_BAR; PG8_SCHED;
	s_add_i32 s17, s17, s58
	v_lshl_add_u64 v[146:147], v[146:147], 0, s[24:25]
	s_mov_b32 m0, s17
	ds_read_b128 v[182:185], v153 offset:49152
	ds_read_b128 v[186:189], v153 offset:50176
	ds_read_b128 v[190:193], v153 offset:51200
	ds_read_b128 v[208:211], v153 offset:52224
	ds_read_b128 v[212:215], v153 offset:53248
	ds_read_b128 v[216:219], v153 offset:54272
	ds_read_b128 v[220:223], v153 offset:55296
	ds_read_b128 v[228:231], v153 offset:56320
	global_load_lds_dwordx4 v[146:147], off
	v_lshl_add_u64 v[146:147], v[224:225], 0, s[24:25]
	s_add_i32 m0, s17, 0x2000
	s_add_i32 s17, s28, s58
	global_load_lds_dwordx4 v[146:147], off
	v_lshl_add_u64 v[146:147], v[232:233], 0, s[24:25]
	s_mov_b32 m0, s17
	s_nop 0
	global_load_lds_dwordx4 v[146:147], off
	v_lshl_add_u64 v[146:147], v[234:235], 0, s[24:25]
	s_add_i32 m0, s17, 0x2000
	s_nop 0
	global_load_lds_dwordx4 v[146:147], off
	v_lshl_add_u64 v[146:147], v[236:237], 0, s[24:25]
	s_mov_b32 m0, s69
	s_nop 0
	global_load_lds_dwordx4 v[146:147], off
	v_lshl_add_u64 v[146:147], v[238:239], 0, s[24:25]
	s_mov_b32 m0, s70
	s_nop 0
	global_load_lds_dwordx4 v[146:147], off
	s_waitcnt vmcnt(8)
	s_waitcnt lgkmcnt(0)
	s_barrier
	s_setprio 1
	v_mfma_f32_16x16x32_bf16 v[62:65], v[142:145], v[182:185], v[62:65]
	v_mfma_f32_16x16x32_bf16 v[54:57], v[158:161], v[182:185], v[54:57]
	v_mfma_f32_16x16x32_bf16 v[46:49], v[142:145], v[190:193], v[46:49]
	v_mfma_f32_16x16x32_bf16 v[38:41], v[158:161], v[190:193], v[38:41]
	v_mfma_f32_16x16x32_bf16 v[30:33], v[142:145], v[212:215], v[30:33]
	v_mfma_f32_16x16x32_bf16 v[22:25], v[158:161], v[212:215], v[22:25]
	v_mfma_f32_16x16x32_bf16 v[14:17], v[142:145], v[220:223], v[14:17]
	v_mfma_f32_16x16x32_bf16 v[6:9], v[158:161], v[220:223], v[6:9]
	v_mfma_f32_16x16x32_bf16 v[62:65], v[154:157], v[186:189], v[62:65]
	v_mfma_f32_16x16x32_bf16 v[54:57], v[162:165], v[186:189], v[54:57]
	v_mfma_f32_16x16x32_bf16 v[46:49], v[154:157], v[208:211], v[46:49]
	v_mfma_f32_16x16x32_bf16 v[38:41], v[162:165], v[208:211], v[38:41]
	v_mfma_f32_16x16x32_bf16 v[30:33], v[154:157], v[216:219], v[30:33]
	v_mfma_f32_16x16x32_bf16 v[22:25], v[162:165], v[216:219], v[22:25]
	v_mfma_f32_16x16x32_bf16 v[14:17], v[154:157], v[228:231], v[14:17]
	v_mfma_f32_16x16x32_bf16 v[6:9], v[162:165], v[228:231], v[6:9]
	v_mfma_f32_16x16x32_bf16 v[58:61], v[166:169], v[182:185], v[58:61]
	v_mfma_f32_16x16x32_bf16 v[50:53], v[174:177], v[182:185], v[50:53]
	v_mfma_f32_16x16x32_bf16 v[42:45], v[166:169], v[190:193], v[42:45]
	v_mfma_f32_16x16x32_bf16 v[34:37], v[174:177], v[190:193], v[34:37]
	v_mfma_f32_16x16x32_bf16 v[26:29], v[166:169], v[212:215], v[26:29]
	v_mfma_f32_16x16x32_bf16 v[18:21], v[174:177], v[212:215], v[18:21]
	v_mfma_f32_16x16x32_bf16 v[10:13], v[166:169], v[220:223], v[10:13]
	v_mfma_f32_16x16x32_bf16 v[2:5], v[174:177], v[220:223], v[2:5]
	v_mfma_f32_16x16x32_bf16 v[58:61], v[170:173], v[186:189], v[58:61]
	v_mfma_f32_16x16x32_bf16 v[50:53], v[178:181], v[186:189], v[50:53]
	v_mfma_f32_16x16x32_bf16 v[42:45], v[170:173], v[208:211], v[42:45]
	v_mfma_f32_16x16x32_bf16 v[34:37], v[178:181], v[208:211], v[34:37]
	v_mfma_f32_16x16x32_bf16 v[26:29], v[170:173], v[216:219], v[26:29]
	v_mfma_f32_16x16x32_bf16 v[18:21], v[178:181], v[216:219], v[18:21]
	v_mfma_f32_16x16x32_bf16 v[10:13], v[170:173], v[228:231], v[10:13]
	v_mfma_f32_16x16x32_bf16 v[2:5], v[178:181], v[228:231], v[2:5]
	s_setprio 0
	s_barrier
	s_add_u32 s2, s2, 0x100
	s_addc_u32 s3, s3, 0
	s_add_u32 s4, s4, 0x100
	s_addc_u32 s16, s16, 0
	s_cmp_ge_i32 s22, s71
	s_mov_b32 s17, s22
	s_cbranch_scc0 .LBB0_499

; #define PG8_STAGE(bufoff, gbase, voff) do { _Pragma("unroll") for (int _i = 0; _i < 2; ++_i) \
;         __builtin_amdgcn_global_load_lds((const unsigned*)((const char*)(gbase) + (voff)[_i]), (PG8_LAS unsigned*)(lds + (bufoff) + ldsw + _i * 8192), 16, 0, 0); } while (0)
; #define PG8_LDA(dst, b, h) do { _Pragma("unroll") for (int m = 0; m < 4; ++m) _Pragma("unroll") for (int k = 0; k < 2; ++k) dst[m][k] = *(const PG8_LAS bf16x8*)(lds + PG8_SA(b, h) + aoff + m * 2048 + k * 1024); } while (0)
; #define PG8_LDB(dst, b, h) do { _Pragma("unroll") for (int n = 0; n < 2; ++n) _Pragma("unroll") for (int k = 0; k < 2; ++k) dst[n][k] = *(const PG8_LAS bf16x8*)(lds + PG8_SB(b, h) + boff + n * 2048 + k * 1024); } while (0)
; #define PG8_MMA(ai, bj, At, Bt) do { __builtin_amdgcn_s_setprio(1); _Pragma("unroll") for (int m = 0; m < 4; ++m) _Pragma("unroll") for (int n = 0; n < 2; ++n) _Pragma("unroll") for (int k = 0; k < 2; ++k) \
;         acc[ai][bj][m][n] = __builtin_amdgcn_mfma_f32_16x16x32_bf16(Bt[n][k], At[m][k], acc[ai][bj][m][n], 0, 0, 0); __builtin_amdgcn_s_setprio(0); } while (0)
; #define PG8_WAIT_V(n) asm volatile("s_waitcnt vmcnt(" #n ")" ::: "memory")
; #define PG8_WAIT_L(n) asm volatile("s_waitcnt lgkmcnt(" #n ")" ::: "memory")
; template <class Epi, class Sched, bool ALIGN_EPI = false, bool SP2 = false>
; __device__ __forceinline__ void gemm_phase(PG8_LAS unsigned char* lds, const Gemm g, const Sched& S, const Epi& E) {
;     ...
;             const bool last = (t == nt - 2);
;             const char* a1 = cA + (size_t)(t + 1) * kstep;
;             const char* a2 = last ? nA : cA + (size_t)(t + 2) * kstep; const char* b2 = last ? nB : cB + (size_t)(t + 2) * kstep;
;             const char* a3 = a2 + kstep; const char* b3 = b2 + kstep;
;             if (last && has_next) S.a_ready(nxt);
;             if constexpr (SP2) {
;             PG8_LDB(B0, 0, 0); PG8_LDB(B1, 0, 1); PG8_SCHED; PG8_LDA(At, 0, 0); PG8_STAGE(PG8_SA(1, 1), a1 + hstep, voffA);
;             PG8_WAIT_V(8); PG8_WAIT_L(0); PG8_BAR; PG8_MMA(0, 0, At, B0); PG8_MMA(0, 1, At, B1); PG8_BAR; PG8_SCHED;
;             PG8_LDA(At, 0, 1); PG8_STAGE(PG8_SB(0, 0), b2, voffB); PG8_STAGE(PG8_SB(0, 1), b2 + hstep, voffB); PG8_STAGE(PG8_SA(0, 0), a2, voffA);
;             PG8_WAIT_V(8); PG8_WAIT_L(0); PG8_BAR; PG8_MMA(1, 0, At, B0); PG8_MMA(1, 1, At, B1); PG8_BAR; PG8_SCHED;
.LBB0_521:
	s_add_i32 s22, s17, 2
	s_add_u32 s28, s34, 0x80
	s_addc_u32 s30, s35, 0
	s_add_i32 s33, 0, 0x10000
	s_cmp_eq_u32 s70, s17
	s_cselect_b32 s37, s3, s30
	s_cselect_b32 s36, s2, s28
	v_add_u32_e32 v145, s33, v142
	s_cselect_b32 s31, s51, s16
	s_cselect_b32 s30, s50, s4
	s_add_i32 s17, 0, 0x14000
	ds_read_b128 v[146:149], v145
	ds_read_b128 v[150:153], v145 offset:1024
	ds_read_b128 v[154:157], v145 offset:2048
	ds_read_b128 v[158:161], v145 offset:3072
	v_add_u32_e32 v145, s17, v142
	ds_read_b128 v[162:165], v145
	ds_read_b128 v[166:169], v145 offset:1024
	ds_read_b128 v[170:173], v145 offset:2048
	ds_read_b128 v[174:177], v145 offset:3072
	v_lshl_add_u64 v[224:225], s[34:35], 0, v[138:139]
	s_add_i32 m0, s61, 0xc000
	ds_read_b128 v[178:181], v144
	ds_read_b128 v[182:185], v144 offset:1024
	ds_read_b128 v[186:189], v144 offset:2048
	ds_read_b128 v[190:193], v144 offset:3072
	ds_read_b128 v[208:211], v144 offset:4096
	ds_read_b128 v[212:215], v144 offset:5120
	ds_read_b128 v[216:219], v144 offset:6144
	ds_read_b128 v[220:223], v144 offset:7168
	global_load_lds_dwordx4 v[224:225], off
	v_lshl_add_u64 v[224:225], s[34:35], 0, v[140:141]
	s_add_i32 m0, s61, 0xe000
	s_nop 0
	global_load_lds_dwordx4 v[224:225], off
	s_waitcnt vmcnt(8)
	s_waitcnt lgkmcnt(0)
	s_barrier
	s_setprio 1
	v_mfma_f32_16x16x32_bf16 v[124:127], v[146:149], v[178:181], v[124:127]
	v_mfma_f32_16x16x32_bf16 v[128:131], v[154:157], v[178:181], v[128:131]
	v_mfma_f32_16x16x32_bf16 v[112:115], v[146:149], v[186:189], v[112:115]
	v_mfma_f32_16x16x32_bf16 v[108:111], v[154:157], v[186:189], v[108:111]
	v_mfma_f32_16x16x32_bf16 v[94:97], v[146:149], v[208:211], v[94:97]
	v_mfma_f32_16x16x32_bf16 v[90:93], v[154:157], v[208:211], v[90:93]
	v_mfma_f32_16x16x32_bf16 v[78:81], v[146:149], v[216:219], v[78:81]
	v_mfma_f32_16x16x32_bf16 v[74:77], v[154:157], v[216:219], v[74:77]
	v_mfma_f32_16x16x32_bf16 v[124:127], v[150:153], v[182:185], v[124:127]
	v_mfma_f32_16x16x32_bf16 v[128:131], v[158:161], v[182:185], v[128:131]
	v_mfma_f32_16x16x32_bf16 v[112:115], v[150:153], v[190:193], v[112:115]
	v_mfma_f32_16x16x32_bf16 v[108:111], v[158:161], v[190:193], v[108:111]
	v_mfma_f32_16x16x32_bf16 v[94:97], v[150:153], v[212:215], v[94:97]
	v_mfma_f32_16x16x32_bf16 v[90:93], v[158:161], v[212:215], v[90:93]
	v_mfma_f32_16x16x32_bf16 v[78:81], v[150:153], v[220:223], v[78:81]
	v_mfma_f32_16x16x32_bf16 v[74:77], v[158:161], v[220:223], v[74:77]
	v_mfma_f32_16x16x32_bf16 v[120:123], v[162:165], v[178:181], v[120:123]
	v_mfma_f32_16x16x32_bf16 v[116:119], v[170:173], v[178:181], v[116:119]
	v_mfma_f32_16x16x32_bf16 v[104:107], v[162:165], v[186:189], v[104:107]
	v_mfma_f32_16x16x32_bf16 v[100:103], v[170:173], v[186:189], v[100:103]
	v_mfma_f32_16x16x32_bf16 v[86:89], v[162:165], v[208:211], v[86:89]
	v_mfma_f32_16x16x32_bf16 v[82:85], v[170:173], v[208:211], v[82:85]
	v_mfma_f32_16x16x32_bf16 v[70:73], v[162:165], v[216:219], v[70:73]
	v_mfma_f32_16x16x32_bf16 v[66:69], v[170:173], v[216:219], v[66:69]
	v_mfma_f32_16x16x32_bf16 v[120:123], v[166:169], v[182:185], v[120:123]
	v_mfma_f32_16x16x32_bf16 v[116:119], v[174:177], v[182:185], v[116:119]
	v_mfma_f32_16x16x32_bf16 v[104:107], v[166:169], v[190:193], v[104:107]
	v_mfma_f32_16x16x32_bf16 v[100:103], v[174:177], v[190:193], v[100:103]
	v_mfma_f32_16x16x32_bf16 v[86:89], v[166:169], v[212:215], v[86:89]
	v_mfma_f32_16x16x32_bf16 v[82:85], v[174:177], v[212:215], v[82:85]
	v_mfma_f32_16x16x32_bf16 v[70:73], v[166:169], v[220:223], v[70:73]
	v_mfma_f32_16x16x32_bf16 v[66:69], v[174:177], v[220:223], v[66:69]
	s_setprio 0
	s_barrier
	s_add_i32 s28, s33, s54
	v_lshl_add_u64 v[224:225], s[30:31], 0, v[98:99]
	s_mov_b32 m0, s28
	ds_read_b128 v[178:181], v144 offset:16384
	ds_read_b128 v[182:185], v144 offset:17408
	ds_read_b128 v[186:189], v144 offset:18432
	ds_read_b128 v[190:193], v144 offset:19456
	ds_read_b128 v[208:211], v144 offset:20480
	ds_read_b128 v[212:215], v144 offset:21504
	ds_read_b128 v[216:219], v144 offset:22528
	ds_read_b128 v[220:223], v144 offset:23552
	global_load_lds_dwordx4 v[224:225], off
	s_add_i32 m0, s28, 0x2000
	v_lshl_add_u64 v[228:229], s[30:31], 0, v[132:133]
	s_add_u32 s30, s30, s10
	s_addc_u32 s31, s31, s11
	s_add_i32 s17, s17, s54
	global_load_lds_dwordx4 v[228:229], off
	v_lshl_add_u64 v[230:231], s[30:31], 0, v[98:99]
	s_mov_b32 m0, s17
	v_lshl_add_u64 v[232:233], s[30:31], 0, v[132:133]
	global_load_lds_dwordx4 v[230:231], off
	s_add_i32 m0, s17, 0x2000
	v_lshl_add_u64 v[234:235], s[36:37], 0, v[136:137]
	global_load_lds_dwordx4 v[232:233], off
	s_mov_b32 m0, s61
	v_lshl_add_u64 v[236:237], s[36:37], 0, v[134:135]
	global_load_lds_dwordx4 v[234:235], off
	s_mov_b32 m0, s62
	s_nop 0
	global_load_lds_dwordx4 v[236:237], off
	s_waitcnt vmcnt(8)
	s_waitcnt lgkmcnt(0)
	s_barrier
; #define PG8_STAGE(bufoff, gbase, voff) do { _Pragma("unroll") for (int _i = 0; _i < 2; ++_i) \
;         __builtin_amdgcn_global_load_lds((const unsigned*)((const char*)(gbase) + (voff)[_i]), (PG8_LAS unsigned*)(lds + (bufoff) + ldsw + _i * 8192), 16, 0, 0); } while (0)
; #define PG8_LDA(dst, b, h) do { _Pragma("unroll") for (int m = 0; m < 4; ++m) _Pragma("unroll") for (int k = 0; k < 2; ++k) dst[m][k] = *(const PG8_LAS bf16x8*)(lds + PG8_SA(b, h) + aoff + m * 2048 + k * 1024); } while (0)
; #define PG8_LDB(dst, b, h) do { _Pragma("unroll") for (int n = 0; n < 2; ++n) _Pragma("unroll") for (int k = 0; k < 2; ++k) dst[n][k] = *(const PG8_LAS bf16x8*)(lds + PG8_SB(b, h) + boff + n * 2048 + k * 1024); } while (0)
; #define PG8_MMA(ai, bj, At, Bt) do { __builtin_amdgcn_s_setprio(1); _Pragma("unroll") for (int m = 0; m < 4; ++m) _Pragma("unroll") for (int n = 0; n < 2; ++n) _Pragma("unroll") for (int k = 0; k < 2; ++k) \
;         acc[ai][bj][m][n] = __builtin_amdgcn_mfma_f32_16x16x32_bf16(Bt[n][k], At[m][k], acc[ai][bj][m][n], 0, 0, 0); __builtin_amdgcn_s_setprio(0); } while (0)
; #define PG8_WAIT_V(n) asm volatile("s_waitcnt vmcnt(" #n ")" ::: "memory")
; #define PG8_WAIT_L(n) asm volatile("s_waitcnt lgkmcnt(" #n ")" ::: "memory")
; #define PG8_BAR __builtin_amdgcn_s_barrier()
; #define PG8_SCHED __builtin_amdgcn_sched_barrier(0)
; template <class Epi, class Sched, bool ALIGN_EPI = false, bool SP2 = false>
; __device__ __forceinline__ void gemm_phase(PG8_LAS unsigned char* lds, const Gemm g, const Sched& S, const Epi& E) {
;     ...
;             PG8_WAIT_V(8); PG8_WAIT_L(0); PG8_BAR; PG8_MMA(1, 0, At, B0); PG8_MMA(1, 1, At, B1); PG8_BAR; PG8_SCHED;
;             PG8_LDB(B0, 1, 0); PG8_LDB(B1, 1, 1); PG8_SCHED; PG8_LDA(At, 1, 0); PG8_STAGE(PG8_SA(0, 1), a2 + hstep, voffA);
;             PG8_WAIT_V(8); PG8_WAIT_L(0); PG8_BAR; PG8_MMA(0, 0, At, B0); PG8_MMA(0, 1, At, B1); PG8_BAR; PG8_SCHED;
	s_setprio 1
	v_mfma_f32_16x16x32_bf16 v[62:65], v[146:149], v[178:181], v[62:65]
	v_mfma_f32_16x16x32_bf16 v[58:61], v[154:157], v[178:181], v[58:61]
	v_mfma_f32_16x16x32_bf16 v[46:49], v[146:149], v[186:189], v[46:49]
	v_mfma_f32_16x16x32_bf16 v[42:45], v[154:157], v[186:189], v[42:45]
	v_mfma_f32_16x16x32_bf16 v[30:33], v[146:149], v[208:211], v[30:33]
	v_mfma_f32_16x16x32_bf16 v[26:29], v[154:157], v[208:211], v[26:29]
	v_mfma_f32_16x16x32_bf16 v[14:17], v[146:149], v[216:219], v[14:17]
	v_mfma_f32_16x16x32_bf16 v[10:13], v[154:157], v[216:219], v[10:13]
	v_mfma_f32_16x16x32_bf16 v[62:65], v[150:153], v[182:185], v[62:65]
	v_mfma_f32_16x16x32_bf16 v[58:61], v[158:161], v[182:185], v[58:61]
	v_mfma_f32_16x16x32_bf16 v[46:49], v[150:153], v[190:193], v[46:49]
	v_mfma_f32_16x16x32_bf16 v[42:45], v[158:161], v[190:193], v[42:45]
	v_mfma_f32_16x16x32_bf16 v[30:33], v[150:153], v[212:215], v[30:33]
	v_mfma_f32_16x16x32_bf16 v[26:29], v[158:161], v[212:215], v[26:29]
	v_mfma_f32_16x16x32_bf16 v[14:17], v[150:153], v[220:223], v[14:17]
	v_mfma_f32_16x16x32_bf16 v[10:13], v[158:161], v[220:223], v[10:13]
	v_mfma_f32_16x16x32_bf16 v[54:57], v[162:165], v[178:181], v[54:57]
	v_mfma_f32_16x16x32_bf16 v[50:53], v[170:173], v[178:181], v[50:53]
	v_mfma_f32_16x16x32_bf16 v[38:41], v[162:165], v[186:189], v[38:41]
	v_mfma_f32_16x16x32_bf16 v[34:37], v[170:173], v[186:189], v[34:37]
	v_mfma_f32_16x16x32_bf16 v[22:25], v[162:165], v[208:211], v[22:25]
	v_mfma_f32_16x16x32_bf16 v[18:21], v[170:173], v[208:211], v[18:21]
	v_mfma_f32_16x16x32_bf16 v[6:9], v[162:165], v[216:219], v[6:9]
	v_mfma_f32_16x16x32_bf16 v[2:5], v[170:173], v[216:219], v[2:5]
	v_mfma_f32_16x16x32_bf16 v[54:57], v[166:169], v[182:185], v[54:57]
	v_mfma_f32_16x16x32_bf16 v[50:53], v[174:177], v[182:185], v[50:53]
	v_mfma_f32_16x16x32_bf16 v[38:41], v[166:169], v[190:193], v[38:41]
	v_mfma_f32_16x16x32_bf16 v[34:37], v[174:177], v[190:193], v[34:37]
	v_mfma_f32_16x16x32_bf16 v[22:25], v[166:169], v[212:215], v[22:25]
	v_mfma_f32_16x16x32_bf16 v[18:21], v[174:177], v[212:215], v[18:21]
	v_mfma_f32_16x16x32_bf16 v[6:9], v[166:169], v[220:223], v[6:9]
	v_mfma_f32_16x16x32_bf16 v[2:5], v[174:177], v[220:223], v[2:5]
	s_setprio 0
	s_barrier
	s_add_i32 s17, 0, 0x18000
	v_add_u32_e32 v145, s17, v142
	s_add_i32 s28, 0, 0x1c000
	ds_read_b128 v[146:149], v145
	ds_read_b128 v[150:153], v145 offset:1024
	ds_read_b128 v[154:157], v145 offset:2048
	ds_read_b128 v[158:161], v145 offset:3072
	v_add_u32_e32 v145, s28, v142
	ds_read_b128 v[162:165], v145
	ds_read_b128 v[166:169], v145 offset:1024
	ds_read_b128 v[170:173], v145 offset:2048
	ds_read_b128 v[174:177], v145 offset:3072
	s_add_u32 s30, s36, s10
	s_addc_u32 s31, s37, s11
	s_mov_b32 m0, s63
	v_lshl_add_u64 v[238:239], s[30:31], 0, v[136:137]
	ds_read_b128 v[178:181], v144 offset:32768
	ds_read_b128 v[182:185], v144 offset:33792
	ds_read_b128 v[186:189], v144 offset:34816
	ds_read_b128 v[190:193], v144 offset:35840
	ds_read_b128 v[208:211], v144 offset:36864
	ds_read_b128 v[212:215], v144 offset:37888
	ds_read_b128 v[216:219], v144 offset:38912
	ds_read_b128 v[220:223], v144 offset:39936
	global_load_lds_dwordx4 v[238:239], off
	v_lshl_add_u64 v[238:239], s[30:31], 0, v[134:135]
	s_mov_b32 m0, s64
	s_nop 0
	global_load_lds_dwordx4 v[238:239], off
	s_waitcnt vmcnt(8)
	s_waitcnt lgkmcnt(0)
	s_barrier
	s_setprio 1
	v_mfma_f32_16x16x32_bf16 v[124:127], v[146:149], v[178:181], v[124:127]
	v_mfma_f32_16x16x32_bf16 v[128:131], v[154:157], v[178:181], v[128:131]
	v_mfma_f32_16x16x32_bf16 v[112:115], v[146:149], v[186:189], v[112:115]
	v_mfma_f32_16x16x32_bf16 v[108:111], v[154:157], v[186:189], v[108:111]
	v_mfma_f32_16x16x32_bf16 v[94:97], v[146:149], v[208:211], v[94:97]
	v_mfma_f32_16x16x32_bf16 v[90:93], v[154:157], v[208:211], v[90:93]
	v_mfma_f32_16x16x32_bf16 v[78:81], v[146:149], v[216:219], v[78:81]
	v_mfma_f32_16x16x32_bf16 v[74:77], v[154:157], v[216:219], v[74:77]
	v_mfma_f32_16x16x32_bf16 v[124:127], v[150:153], v[182:185], v[124:127]
	v_mfma_f32_16x16x32_bf16 v[128:131], v[158:161], v[182:185], v[128:131]
	v_mfma_f32_16x16x32_bf16 v[112:115], v[150:153], v[190:193], v[112:115]
	v_mfma_f32_16x16x32_bf16 v[108:111], v[158:161], v[190:193], v[108:111]
	v_mfma_f32_16x16x32_bf16 v[94:97], v[150:153], v[212:215], v[94:97]
	v_mfma_f32_16x16x32_bf16 v[90:93], v[158:161], v[212:215], v[90:93]
	v_mfma_f32_16x16x32_bf16 v[78:81], v[150:153], v[220:223], v[78:81]
	v_mfma_f32_16x16x32_bf16 v[74:77], v[158:161], v[220:223], v[74:77]
	v_mfma_f32_16x16x32_bf16 v[120:123], v[162:165], v[178:181], v[120:123]
	v_mfma_f32_16x16x32_bf16 v[116:119], v[170:173], v[178:181], v[116:119]
	v_mfma_f32_16x16x32_bf16 v[104:107], v[162:165], v[186:189], v[104:107]
	v_mfma_f32_16x16x32_bf16 v[100:103], v[170:173], v[186:189], v[100:103]
	v_mfma_f32_16x16x32_bf16 v[86:89], v[162:165], v[208:211], v[86:89]
	v_mfma_f32_16x16x32_bf16 v[82:85], v[170:173], v[208:211], v[82:85]
	v_mfma_f32_16x16x32_bf16 v[70:73], v[162:165], v[216:219], v[70:73]
	v_mfma_f32_16x16x32_bf16 v[66:69], v[170:173], v[216:219], v[66:69]
	v_mfma_f32_16x16x32_bf16 v[120:123], v[166:169], v[182:185], v[120:123]
	v_mfma_f32_16x16x32_bf16 v[116:119], v[174:177], v[182:185], v[116:119]
	v_mfma_f32_16x16x32_bf16 v[104:107], v[166:169], v[190:193], v[104:107]
	v_mfma_f32_16x16x32_bf16 v[100:103], v[174:177], v[190:193], v[100:103]
	v_mfma_f32_16x16x32_bf16 v[86:89], v[166:169], v[212:215], v[86:89]
	v_mfma_f32_16x16x32_bf16 v[82:85], v[174:177], v[212:215], v[82:85]
	v_mfma_f32_16x16x32_bf16 v[70:73], v[166:169], v[220:223], v[70:73]
	v_mfma_f32_16x16x32_bf16 v[66:69], v[174:177], v[220:223], v[66:69]
	s_setprio 0
	s_barrier
; #define PG8_STAGE(bufoff, gbase, voff) do { _Pragma("unroll") for (int _i = 0; _i < 2; ++_i) \
;         __builtin_amdgcn_global_load_lds((const unsigned*)((const char*)(gbase) + (voff)[_i]), (PG8_LAS unsigned*)(lds + (bufoff) + ldsw + _i * 8192), 16, 0, 0); } while (0)
; #define PG8_LDA(dst, b, h) do { _Pragma("unroll") for (int m = 0; m < 4; ++m) _Pragma("unroll") for (int k = 0; k < 2; ++k) dst[m][k] = *(const PG8_LAS bf16x8*)(lds + PG8_SA(b, h) + aoff + m * 2048 + k * 1024); } while (0)
; #define PG8_MMA(ai, bj, At, Bt) do { __builtin_amdgcn_s_setprio(1); _Pragma("unroll") for (int m = 0; m < 4; ++m) _Pragma("unroll") for (int n = 0; n < 2; ++n) _Pragma("unroll") for (int k = 0; k < 2; ++k) \
;         acc[ai][bj][m][n] = __builtin_amdgcn_mfma_f32_16x16x32_bf16(Bt[n][k], At[m][k], acc[ai][bj][m][n], 0, 0, 0); __builtin_amdgcn_s_setprio(0); } while (0)
; #define PG8_WAIT_V(n) asm volatile("s_waitcnt vmcnt(" #n ")" ::: "memory")
; #define PG8_WAIT_L(n) asm volatile("s_waitcnt lgkmcnt(" #n ")" ::: "memory")
; #define PG8_BAR __builtin_amdgcn_s_barrier()
; #define PG8_SCHED __builtin_amdgcn_sched_barrier(0)
; template <class Epi, class Sched, bool ALIGN_EPI = false, bool SP2 = false>
; __device__ __forceinline__ void gemm_phase(PG8_LAS unsigned char* lds, const Gemm g, const Sched& S, const Epi& E) {
;     ...
;             PG8_LDA(At, 1, 1); PG8_STAGE(PG8_SB(1, 0), b3, voffB); PG8_STAGE(PG8_SB(1, 1), b3 + hstep, voffB); PG8_STAGE(PG8_SA(1, 0), a3, voffA);
;             PG8_WAIT_V(8); PG8_WAIT_L(0); PG8_BAR; PG8_MMA(1, 0, At, B0); PG8_MMA(1, 1, At, B1); PG8_BAR; PG8_SCHED;
	s_add_i32 s17, s17, s54
	v_lshl_add_u64 v[224:225], v[224:225], 0, s[24:25]
	s_mov_b32 m0, s17
	ds_read_b128 v[178:181], v144 offset:49152
	ds_read_b128 v[182:185], v144 offset:50176
	ds_read_b128 v[186:189], v144 offset:51200
	ds_read_b128 v[190:193], v144 offset:52224
	ds_read_b128 v[208:211], v144 offset:53248
	ds_read_b128 v[212:215], v144 offset:54272
	ds_read_b128 v[216:219], v144 offset:55296
	ds_read_b128 v[220:223], v144 offset:56320
	global_load_lds_dwordx4 v[224:225], off
	v_lshl_add_u64 v[224:225], v[228:229], 0, s[24:25]
	s_add_i32 m0, s17, 0x2000
	s_add_i32 s17, s28, s54
	global_load_lds_dwordx4 v[224:225], off
	v_lshl_add_u64 v[224:225], v[230:231], 0, s[24:25]
	s_mov_b32 m0, s17
	s_nop 0
	global_load_lds_dwordx4 v[224:225], off
	v_lshl_add_u64 v[224:225], v[232:233], 0, s[24:25]
	s_add_i32 m0, s17, 0x2000
	s_nop 0
	global_load_lds_dwordx4 v[224:225], off
	v_lshl_add_u64 v[224:225], v[234:235], 0, s[24:25]
	s_mov_b32 m0, s68
	s_nop 0
	global_load_lds_dwordx4 v[224:225], off
	v_lshl_add_u64 v[224:225], v[236:237], 0, s[24:25]
	s_mov_b32 m0, s69
	s_nop 0
	global_load_lds_dwordx4 v[224:225], off
	s_waitcnt vmcnt(8)
	s_waitcnt lgkmcnt(0)
	s_barrier
	s_setprio 1
	v_mfma_f32_16x16x32_bf16 v[62:65], v[146:149], v[178:181], v[62:65]
	v_mfma_f32_16x16x32_bf16 v[58:61], v[154:157], v[178:181], v[58:61]
	v_mfma_f32_16x16x32_bf16 v[46:49], v[146:149], v[186:189], v[46:49]
	v_mfma_f32_16x16x32_bf16 v[42:45], v[154:157], v[186:189], v[42:45]
	v_mfma_f32_16x16x32_bf16 v[30:33], v[146:149], v[208:211], v[30:33]
	v_mfma_f32_16x16x32_bf16 v[26:29], v[154:157], v[208:211], v[26:29]
	v_mfma_f32_16x16x32_bf16 v[14:17], v[146:149], v[216:219], v[14:17]
	v_mfma_f32_16x16x32_bf16 v[10:13], v[154:157], v[216:219], v[10:13]
	v_mfma_f32_16x16x32_bf16 v[62:65], v[150:153], v[182:185], v[62:65]
	v_mfma_f32_16x16x32_bf16 v[58:61], v[158:161], v[182:185], v[58:61]
	v_mfma_f32_16x16x32_bf16 v[46:49], v[150:153], v[190:193], v[46:49]
	v_mfma_f32_16x16x32_bf16 v[42:45], v[158:161], v[190:193], v[42:45]
	v_mfma_f32_16x16x32_bf16 v[30:33], v[150:153], v[212:215], v[30:33]
	v_mfma_f32_16x16x32_bf16 v[26:29], v[158:161], v[212:215], v[26:29]
	v_mfma_f32_16x16x32_bf16 v[14:17], v[150:153], v[220:223], v[14:17]
	v_mfma_f32_16x16x32_bf16 v[10:13], v[158:161], v[220:223], v[10:13]
	v_mfma_f32_16x16x32_bf16 v[54:57], v[162:165], v[178:181], v[54:57]
	v_mfma_f32_16x16x32_bf16 v[50:53], v[170:173], v[178:181], v[50:53]
	v_mfma_f32_16x16x32_bf16 v[38:41], v[162:165], v[186:189], v[38:41]
	v_mfma_f32_16x16x32_bf16 v[34:37], v[170:173], v[186:189], v[34:37]
	v_mfma_f32_16x16x32_bf16 v[22:25], v[162:165], v[208:211], v[22:25]
	v_mfma_f32_16x16x32_bf16 v[18:21], v[170:173], v[208:211], v[18:21]
	v_mfma_f32_16x16x32_bf16 v[6:9], v[162:165], v[216:219], v[6:9]
	v_mfma_f32_16x16x32_bf16 v[2:5], v[170:173], v[216:219], v[2:5]
	v_mfma_f32_16x16x32_bf16 v[54:57], v[166:169], v[182:185], v[54:57]
	v_mfma_f32_16x16x32_bf16 v[50:53], v[174:177], v[182:185], v[50:53]
	v_mfma_f32_16x16x32_bf16 v[38:41], v[166:169], v[190:193], v[38:41]
	v_mfma_f32_16x16x32_bf16 v[34:37], v[174:177], v[190:193], v[34:37]
	v_mfma_f32_16x16x32_bf16 v[22:25], v[166:169], v[212:215], v[22:25]
	v_mfma_f32_16x16x32_bf16 v[18:21], v[174:177], v[212:215], v[18:21]
	v_mfma_f32_16x16x32_bf16 v[6:9], v[166:169], v[220:223], v[6:9]
	v_mfma_f32_16x16x32_bf16 v[2:5], v[174:177], v[220:223], v[2:5]
	s_setprio 0
	s_barrier
	s_add_u32 s34, s34, 0x100
	s_addc_u32 s35, s35, 0
	s_add_u32 s4, s4, 0x100
	s_addc_u32 s16, s16, 0
	s_cmp_ge_i32 s22, s65
	s_mov_b32 s17, s22
	s_cbranch_scc0 .LBB0_521

; #define PG8_STAGE(bufoff, gbase, voff) do { _Pragma("unroll") for (int _i = 0; _i < 2; ++_i) \
;         __builtin_amdgcn_global_load_lds((const unsigned*)((const char*)(gbase) + (voff)[_i]), (PG8_LAS unsigned*)(lds + (bufoff) + ldsw + _i * 8192), 16, 0, 0); } while (0)
; #define PG8_LDA(dst, b, h) do { _Pragma("unroll") for (int m = 0; m < 4; ++m) _Pragma("unroll") for (int k = 0; k < 2; ++k) dst[m][k] = *(const PG8_LAS bf16x8*)(lds + PG8_SA(b, h) + aoff + m * 2048 + k * 1024); } while (0)
; #define PG8_LDB(dst, b, h) do { _Pragma("unroll") for (int n = 0; n < 2; ++n) _Pragma("unroll") for (int k = 0; k < 2; ++k) dst[n][k] = *(const PG8_LAS bf16x8*)(lds + PG8_SB(b, h) + boff + n * 2048 + k * 1024); } while (0)
; #define PG8_MMA(ai, bj, At, Bt) do { __builtin_amdgcn_s_setprio(1); _Pragma("unroll") for (int m = 0; m < 4; ++m) _Pragma("unroll") for (int n = 0; n < 2; ++n) _Pragma("unroll") for (int k = 0; k < 2; ++k) \
;         acc[ai][bj][m][n] = __builtin_amdgcn_mfma_f32_16x16x32_bf16(Bt[n][k], At[m][k], acc[ai][bj][m][n], 0, 0, 0); __builtin_amdgcn_s_setprio(0); } while (0)
; #define PG8_WAIT_V(n) asm volatile("s_waitcnt vmcnt(" #n ")" ::: "memory")
; #define PG8_WAIT_L(n) asm volatile("s_waitcnt lgkmcnt(" #n ")" ::: "memory")
; template <class Epi, class Sched, bool ALIGN_EPI = false, bool SP2 = false>
; __device__ __forceinline__ void gemm_phase(PG8_LAS unsigned char* lds, const Gemm g, const Sched& S, const Epi& E) {
;     ...
;             const bool last = (t == nt - 2);
;             const char* a1 = cA + (size_t)(t + 1) * kstep;
;             const char* a2 = last ? nA : cA + (size_t)(t + 2) * kstep; const char* b2 = last ? nB : cB + (size_t)(t + 2) * kstep;
;             const char* a3 = a2 + kstep; const char* b3 = b2 + kstep;
;             if (last && has_next) S.a_ready(nxt);
;             if constexpr (SP2) {
;             PG8_LDB(B0, 0, 0); PG8_LDB(B1, 0, 1); PG8_SCHED; PG8_LDA(At, 0, 0); PG8_STAGE(PG8_SA(1, 1), a1 + hstep, voffA);
;             PG8_WAIT_V(8); PG8_WAIT_L(0); PG8_BAR; PG8_MMA(0, 0, At, B0); PG8_MMA(0, 1, At, B1); PG8_BAR; PG8_SCHED;
;             PG8_LDA(At, 0, 1); PG8_STAGE(PG8_SB(0, 0), b2, voffB); PG8_STAGE(PG8_SB(0, 1), b2 + hstep, voffB); PG8_STAGE(PG8_SA(0, 0), a2, voffA);
;             PG8_WAIT_V(8); PG8_WAIT_L(0); PG8_BAR; PG8_MMA(1, 0, At, B0); PG8_MMA(1, 1, At, B1); PG8_BAR; PG8_SCHED;
.LBB0_544:
	s_add_i32 s22, s17, 2
	s_add_u32 s28, s34, 0x80
	s_addc_u32 s30, s35, 0
	s_add_i32 s33, 0, 0x10000
	s_cmp_eq_u32 s71, s17
	s_cselect_b32 s37, s3, s30
	s_cselect_b32 s36, s2, s28
	v_add_u32_e32 v145, s33, v142
	s_cselect_b32 s31, s51, s16
	s_cselect_b32 s30, s50, s4
	s_add_i32 s17, 0, 0x14000
	ds_read_b128 v[146:149], v145
	ds_read_b128 v[150:153], v145 offset:1024
	ds_read_b128 v[154:157], v145 offset:2048
	ds_read_b128 v[158:161], v145 offset:3072
	v_add_u32_e32 v145, s17, v142
	ds_read_b128 v[162:165], v145
	ds_read_b128 v[166:169], v145 offset:1024
	ds_read_b128 v[170:173], v145 offset:2048
	ds_read_b128 v[174:177], v145 offset:3072
	v_lshl_add_u64 v[224:225], s[34:35], 0, v[138:139]
	s_add_i32 m0, s62, 0xc000
	ds_read_b128 v[178:181], v144
	ds_read_b128 v[182:185], v144 offset:1024
	ds_read_b128 v[186:189], v144 offset:2048
	ds_read_b128 v[190:193], v144 offset:3072
	ds_read_b128 v[208:211], v144 offset:4096
	ds_read_b128 v[212:215], v144 offset:5120
	ds_read_b128 v[216:219], v144 offset:6144
	ds_read_b128 v[220:223], v144 offset:7168
	global_load_lds_dwordx4 v[224:225], off
	v_lshl_add_u64 v[224:225], s[34:35], 0, v[140:141]
	s_add_i32 m0, s62, 0xe000
	s_nop 0
	global_load_lds_dwordx4 v[224:225], off
	s_waitcnt vmcnt(8)
	s_waitcnt lgkmcnt(0)
	s_barrier
	s_setprio 1
	v_mfma_f32_16x16x32_bf16 v[124:127], v[146:149], v[178:181], v[124:127]
	v_mfma_f32_16x16x32_bf16 v[128:131], v[154:157], v[178:181], v[128:131]
	v_mfma_f32_16x16x32_bf16 v[112:115], v[146:149], v[186:189], v[112:115]
	v_mfma_f32_16x16x32_bf16 v[108:111], v[154:157], v[186:189], v[108:111]
	v_mfma_f32_16x16x32_bf16 v[94:97], v[146:149], v[208:211], v[94:97]
	v_mfma_f32_16x16x32_bf16 v[90:93], v[154:157], v[208:211], v[90:93]
	v_mfma_f32_16x16x32_bf16 v[78:81], v[146:149], v[216:219], v[78:81]
	v_mfma_f32_16x16x32_bf16 v[74:77], v[154:157], v[216:219], v[74:77]
	v_mfma_f32_16x16x32_bf16 v[124:127], v[150:153], v[182:185], v[124:127]
	v_mfma_f32_16x16x32_bf16 v[128:131], v[158:161], v[182:185], v[128:131]
	v_mfma_f32_16x16x32_bf16 v[112:115], v[150:153], v[190:193], v[112:115]
	v_mfma_f32_16x16x32_bf16 v[108:111], v[158:161], v[190:193], v[108:111]
	v_mfma_f32_16x16x32_bf16 v[94:97], v[150:153], v[212:215], v[94:97]
	v_mfma_f32_16x16x32_bf16 v[90:93], v[158:161], v[212:215], v[90:93]
	v_mfma_f32_16x16x32_bf16 v[78:81], v[150:153], v[220:223], v[78:81]
	v_mfma_f32_16x16x32_bf16 v[74:77], v[158:161], v[220:223], v[74:77]
	v_mfma_f32_16x16x32_bf16 v[120:123], v[162:165], v[178:181], v[120:123]
	v_mfma_f32_16x16x32_bf16 v[116:119], v[170:173], v[178:181], v[116:119]
	v_mfma_f32_16x16x32_bf16 v[104:107], v[162:165], v[186:189], v[104:107]
	v_mfma_f32_16x16x32_bf16 v[100:103], v[170:173], v[186:189], v[100:103]
	v_mfma_f32_16x16x32_bf16 v[86:89], v[162:165], v[208:211], v[86:89]
	v_mfma_f32_16x16x32_bf16 v[82:85], v[170:173], v[208:211], v[82:85]
	v_mfma_f32_16x16x32_bf16 v[70:73], v[162:165], v[216:219], v[70:73]
	v_mfma_f32_16x16x32_bf16 v[66:69], v[170:173], v[216:219], v[66:69]
	v_mfma_f32_16x16x32_bf16 v[120:123], v[166:169], v[182:185], v[120:123]
	v_mfma_f32_16x16x32_bf16 v[116:119], v[174:177], v[182:185], v[116:119]
	v_mfma_f32_16x16x32_bf16 v[104:107], v[166:169], v[190:193], v[104:107]
	v_mfma_f32_16x16x32_bf16 v[100:103], v[174:177], v[190:193], v[100:103]
	v_mfma_f32_16x16x32_bf16 v[86:89], v[166:169], v[212:215], v[86:89]
	v_mfma_f32_16x16x32_bf16 v[82:85], v[174:177], v[212:215], v[82:85]
	v_mfma_f32_16x16x32_bf16 v[70:73], v[166:169], v[220:223], v[70:73]
	v_mfma_f32_16x16x32_bf16 v[66:69], v[174:177], v[220:223], v[66:69]
	s_setprio 0
	s_barrier
	s_add_i32 s28, s33, s55
	v_lshl_add_u64 v[224:225], s[30:31], 0, v[98:99]
	s_mov_b32 m0, s28
	ds_read_b128 v[178:181], v144 offset:16384
	ds_read_b128 v[182:185], v144 offset:17408
	ds_read_b128 v[186:189], v144 offset:18432
	ds_read_b128 v[190:193], v144 offset:19456
	ds_read_b128 v[208:211], v144 offset:20480
	ds_read_b128 v[212:215], v144 offset:21504
	ds_read_b128 v[216:219], v144 offset:22528
	ds_read_b128 v[220:223], v144 offset:23552
	global_load_lds_dwordx4 v[224:225], off
	s_add_i32 m0, s28, 0x2000
	v_lshl_add_u64 v[228:229], s[30:31], 0, v[132:133]
	s_add_u32 s30, s30, s10
	s_addc_u32 s31, s31, s11
	s_add_i32 s17, s17, s55
	global_load_lds_dwordx4 v[228:229], off
	v_lshl_add_u64 v[230:231], s[30:31], 0, v[98:99]
	s_mov_b32 m0, s17
	v_lshl_add_u64 v[232:233], s[30:31], 0, v[132:133]
	global_load_lds_dwordx4 v[230:231], off
	s_add_i32 m0, s17, 0x2000
	v_lshl_add_u64 v[234:235], s[36:37], 0, v[136:137]
	global_load_lds_dwordx4 v[232:233], off
	s_mov_b32 m0, s62
	v_lshl_add_u64 v[236:237], s[36:37], 0, v[134:135]
	global_load_lds_dwordx4 v[234:235], off
	s_mov_b32 m0, s63
	s_nop 0
	global_load_lds_dwordx4 v[236:237], off
	s_waitcnt vmcnt(8)
	s_waitcnt lgkmcnt(0)
	s_barrier
; #define PG8_STAGE(bufoff, gbase, voff) do { _Pragma("unroll") for (int _i = 0; _i < 2; ++_i) \
;         __builtin_amdgcn_global_load_lds((const unsigned*)((const char*)(gbase) + (voff)[_i]), (PG8_LAS unsigned*)(lds + (bufoff) + ldsw + _i * 8192), 16, 0, 0); } while (0)
; #define PG8_LDA(dst, b, h) do { _Pragma("unroll") for (int m = 0; m < 4; ++m) _Pragma("unroll") for (int k = 0; k < 2; ++k) dst[m][k] = *(const PG8_LAS bf16x8*)(lds + PG8_SA(b, h) + aoff + m * 2048 + k * 1024); } while (0)
; #define PG8_LDB(dst, b, h) do { _Pragma("unroll") for (int n = 0; n < 2; ++n) _Pragma("unroll") for (int k = 0; k < 2; ++k) dst[n][k] = *(const PG8_LAS bf16x8*)(lds + PG8_SB(b, h) + boff + n * 2048 + k * 1024); } while (0)
; #define PG8_MMA(ai, bj, At, Bt) do { __builtin_amdgcn_s_setprio(1); _Pragma("unroll") for (int m = 0; m < 4; ++m) _Pragma("unroll") for (int n = 0; n < 2; ++n) _Pragma("unroll") for (int k = 0; k < 2; ++k) \
;         acc[ai][bj][m][n] = __builtin_amdgcn_mfma_f32_16x16x32_bf16(Bt[n][k], At[m][k], acc[ai][bj][m][n], 0, 0, 0); __builtin_amdgcn_s_setprio(0); } while (0)
; #define PG8_WAIT_V(n) asm volatile("s_waitcnt vmcnt(" #n ")" ::: "memory")
; #define PG8_WAIT_L(n) asm volatile("s_waitcnt lgkmcnt(" #n ")" ::: "memory")
; #define PG8_BAR __builtin_amdgcn_s_barrier()
; #define PG8_SCHED __builtin_amdgcn_sched_barrier(0)
; template <class Epi, class Sched, bool ALIGN_EPI = false, bool SP2 = false>
; __device__ __forceinline__ void gemm_phase(PG8_LAS unsigned char* lds, const Gemm g, const Sched& S, const Epi& E) {
;     ...
;             PG8_WAIT_V(8); PG8_WAIT_L(0); PG8_BAR; PG8_MMA(1, 0, At, B0); PG8_MMA(1, 1, At, B1); PG8_BAR; PG8_SCHED;
;             PG8_LDB(B0, 1, 0); PG8_LDB(B1, 1, 1); PG8_SCHED; PG8_LDA(At, 1, 0); PG8_STAGE(PG8_SA(0, 1), a2 + hstep, voffA);
;             PG8_WAIT_V(8); PG8_WAIT_L(0); PG8_BAR; PG8_MMA(0, 0, At, B0); PG8_MMA(0, 1, At, B1); PG8_BAR; PG8_SCHED;
	s_setprio 1
	v_mfma_f32_16x16x32_bf16 v[62:65], v[146:149], v[178:181], v[62:65]
	v_mfma_f32_16x16x32_bf16 v[58:61], v[154:157], v[178:181], v[58:61]
	v_mfma_f32_16x16x32_bf16 v[46:49], v[146:149], v[186:189], v[46:49]
	v_mfma_f32_16x16x32_bf16 v[42:45], v[154:157], v[186:189], v[42:45]
	v_mfma_f32_16x16x32_bf16 v[30:33], v[146:149], v[208:211], v[30:33]
	v_mfma_f32_16x16x32_bf16 v[26:29], v[154:157], v[208:211], v[26:29]
	v_mfma_f32_16x16x32_bf16 v[14:17], v[146:149], v[216:219], v[14:17]
	v_mfma_f32_16x16x32_bf16 v[10:13], v[154:157], v[216:219], v[10:13]
	v_mfma_f32_16x16x32_bf16 v[62:65], v[150:153], v[182:185], v[62:65]
	v_mfma_f32_16x16x32_bf16 v[58:61], v[158:161], v[182:185], v[58:61]
	v_mfma_f32_16x16x32_bf16 v[46:49], v[150:153], v[190:193], v[46:49]
	v_mfma_f32_16x16x32_bf16 v[42:45], v[158:161], v[190:193], v[42:45]
	v_mfma_f32_16x16x32_bf16 v[30:33], v[150:153], v[212:215], v[30:33]
	v_mfma_f32_16x16x32_bf16 v[26:29], v[158:161], v[212:215], v[26:29]
	v_mfma_f32_16x16x32_bf16 v[14:17], v[150:153], v[220:223], v[14:17]
	v_mfma_f32_16x16x32_bf16 v[10:13], v[158:161], v[220:223], v[10:13]
	v_mfma_f32_16x16x32_bf16 v[54:57], v[162:165], v[178:181], v[54:57]
	v_mfma_f32_16x16x32_bf16 v[50:53], v[170:173], v[178:181], v[50:53]
	v_mfma_f32_16x16x32_bf16 v[38:41], v[162:165], v[186:189], v[38:41]
	v_mfma_f32_16x16x32_bf16 v[34:37], v[170:173], v[186:189], v[34:37]
	v_mfma_f32_16x16x32_bf16 v[22:25], v[162:165], v[208:211], v[22:25]
	v_mfma_f32_16x16x32_bf16 v[18:21], v[170:173], v[208:211], v[18:21]
	v_mfma_f32_16x16x32_bf16 v[6:9], v[162:165], v[216:219], v[6:9]
	v_mfma_f32_16x16x32_bf16 v[2:5], v[170:173], v[216:219], v[2:5]
	v_mfma_f32_16x16x32_bf16 v[54:57], v[166:169], v[182:185], v[54:57]
	v_mfma_f32_16x16x32_bf16 v[50:53], v[174:177], v[182:185], v[50:53]
	v_mfma_f32_16x16x32_bf16 v[38:41], v[166:169], v[190:193], v[38:41]
	v_mfma_f32_16x16x32_bf16 v[34:37], v[174:177], v[190:193], v[34:37]
	v_mfma_f32_16x16x32_bf16 v[22:25], v[166:169], v[212:215], v[22:25]
	v_mfma_f32_16x16x32_bf16 v[18:21], v[174:177], v[212:215], v[18:21]
	v_mfma_f32_16x16x32_bf16 v[6:9], v[166:169], v[220:223], v[6:9]
	v_mfma_f32_16x16x32_bf16 v[2:5], v[174:177], v[220:223], v[2:5]
	s_setprio 0
	s_barrier
	s_add_i32 s17, 0, 0x18000
	v_add_u32_e32 v145, s17, v142
	s_add_i32 s28, 0, 0x1c000
	ds_read_b128 v[146:149], v145
	ds_read_b128 v[150:153], v145 offset:1024
	ds_read_b128 v[154:157], v145 offset:2048
	ds_read_b128 v[158:161], v145 offset:3072
	v_add_u32_e32 v145, s28, v142
	ds_read_b128 v[162:165], v145
	ds_read_b128 v[166:169], v145 offset:1024
	ds_read_b128 v[170:173], v145 offset:2048
	ds_read_b128 v[174:177], v145 offset:3072
	s_add_u32 s30, s36, s10
	s_addc_u32 s31, s37, s11
	s_mov_b32 m0, s64
	v_lshl_add_u64 v[238:239], s[30:31], 0, v[136:137]
	ds_read_b128 v[178:181], v144 offset:32768
	ds_read_b128 v[182:185], v144 offset:33792
	ds_read_b128 v[186:189], v144 offset:34816
	ds_read_b128 v[190:193], v144 offset:35840
	ds_read_b128 v[208:211], v144 offset:36864
	ds_read_b128 v[212:215], v144 offset:37888
	ds_read_b128 v[216:219], v144 offset:38912
	ds_read_b128 v[220:223], v144 offset:39936
	global_load_lds_dwordx4 v[238:239], off
	v_lshl_add_u64 v[238:239], s[30:31], 0, v[134:135]
	s_mov_b32 m0, s65
	s_nop 0
	global_load_lds_dwordx4 v[238:239], off
	s_waitcnt vmcnt(8)
	s_waitcnt lgkmcnt(0)
	s_barrier
	s_setprio 1
	v_mfma_f32_16x16x32_bf16 v[124:127], v[146:149], v[178:181], v[124:127]
	v_mfma_f32_16x16x32_bf16 v[128:131], v[154:157], v[178:181], v[128:131]
	v_mfma_f32_16x16x32_bf16 v[112:115], v[146:149], v[186:189], v[112:115]
	v_mfma_f32_16x16x32_bf16 v[108:111], v[154:157], v[186:189], v[108:111]
	v_mfma_f32_16x16x32_bf16 v[94:97], v[146:149], v[208:211], v[94:97]
	v_mfma_f32_16x16x32_bf16 v[90:93], v[154:157], v[208:211], v[90:93]
	v_mfma_f32_16x16x32_bf16 v[78:81], v[146:149], v[216:219], v[78:81]
	v_mfma_f32_16x16x32_bf16 v[74:77], v[154:157], v[216:219], v[74:77]
	v_mfma_f32_16x16x32_bf16 v[124:127], v[150:153], v[182:185], v[124:127]
	v_mfma_f32_16x16x32_bf16 v[128:131], v[158:161], v[182:185], v[128:131]
	v_mfma_f32_16x16x32_bf16 v[112:115], v[150:153], v[190:193], v[112:115]
	v_mfma_f32_16x16x32_bf16 v[108:111], v[158:161], v[190:193], v[108:111]
	v_mfma_f32_16x16x32_bf16 v[94:97], v[150:153], v[212:215], v[94:97]
	v_mfma_f32_16x16x32_bf16 v[90:93], v[158:161], v[212:215], v[90:93]
	v_mfma_f32_16x16x32_bf16 v[78:81], v[150:153], v[220:223], v[78:81]
	v_mfma_f32_16x16x32_bf16 v[74:77], v[158:161], v[220:223], v[74:77]
	v_mfma_f32_16x16x32_bf16 v[120:123], v[162:165], v[178:181], v[120:123]
	v_mfma_f32_16x16x32_bf16 v[116:119], v[170:173], v[178:181], v[116:119]
	v_mfma_f32_16x16x32_bf16 v[104:107], v[162:165], v[186:189], v[104:107]
	v_mfma_f32_16x16x32_bf16 v[100:103], v[170:173], v[186:189], v[100:103]
	v_mfma_f32_16x16x32_bf16 v[86:89], v[162:165], v[208:211], v[86:89]
	v_mfma_f32_16x16x32_bf16 v[82:85], v[170:173], v[208:211], v[82:85]
	v_mfma_f32_16x16x32_bf16 v[70:73], v[162:165], v[216:219], v[70:73]
	v_mfma_f32_16x16x32_bf16 v[66:69], v[170:173], v[216:219], v[66:69]
	v_mfma_f32_16x16x32_bf16 v[120:123], v[166:169], v[182:185], v[120:123]
	v_mfma_f32_16x16x32_bf16 v[116:119], v[174:177], v[182:185], v[116:119]
	v_mfma_f32_16x16x32_bf16 v[104:107], v[166:169], v[190:193], v[104:107]
	v_mfma_f32_16x16x32_bf16 v[100:103], v[174:177], v[190:193], v[100:103]
	v_mfma_f32_16x16x32_bf16 v[86:89], v[166:169], v[212:215], v[86:89]
	v_mfma_f32_16x16x32_bf16 v[82:85], v[174:177], v[212:215], v[82:85]
	v_mfma_f32_16x16x32_bf16 v[70:73], v[166:169], v[220:223], v[70:73]
	v_mfma_f32_16x16x32_bf16 v[66:69], v[174:177], v[220:223], v[66:69]
	s_setprio 0
	s_barrier
; #define PG8_STAGE(bufoff, gbase, voff) do { _Pragma("unroll") for (int _i = 0; _i < 2; ++_i) \
;         __builtin_amdgcn_global_load_lds((const unsigned*)((const char*)(gbase) + (voff)[_i]), (PG8_LAS unsigned*)(lds + (bufoff) + ldsw + _i * 8192), 16, 0, 0); } while (0)
; #define PG8_LDA(dst, b, h) do { _Pragma("unroll") for (int m = 0; m < 4; ++m) _Pragma("unroll") for (int k = 0; k < 2; ++k) dst[m][k] = *(const PG8_LAS bf16x8*)(lds + PG8_SA(b, h) + aoff + m * 2048 + k * 1024); } while (0)
; #define PG8_MMA(ai, bj, At, Bt) do { __builtin_amdgcn_s_setprio(1); _Pragma("unroll") for (int m = 0; m < 4; ++m) _Pragma("unroll") for (int n = 0; n < 2; ++n) _Pragma("unroll") for (int k = 0; k < 2; ++k) \
;         acc[ai][bj][m][n] = __builtin_amdgcn_mfma_f32_16x16x32_bf16(Bt[n][k], At[m][k], acc[ai][bj][m][n], 0, 0, 0); __builtin_amdgcn_s_setprio(0); } while (0)
; #define PG8_WAIT_V(n) asm volatile("s_waitcnt vmcnt(" #n ")" ::: "memory")
; #define PG8_WAIT_L(n) asm volatile("s_waitcnt lgkmcnt(" #n ")" ::: "memory")
; #define PG8_BAR __builtin_amdgcn_s_barrier()
; #define PG8_SCHED __builtin_amdgcn_sched_barrier(0)
; template <class Epi, class Sched, bool ALIGN_EPI = false, bool SP2 = false>
; __device__ __forceinline__ void gemm_phase(PG8_LAS unsigned char* lds, const Gemm g, const Sched& S, const Epi& E) {
;     ...
;             PG8_LDA(At, 1, 1); PG8_STAGE(PG8_SB(1, 0), b3, voffB); PG8_STAGE(PG8_SB(1, 1), b3 + hstep, voffB); PG8_STAGE(PG8_SA(1, 0), a3, voffA);
;             PG8_WAIT_V(8); PG8_WAIT_L(0); PG8_BAR; PG8_MMA(1, 0, At, B0); PG8_MMA(1, 1, At, B1); PG8_BAR; PG8_SCHED;
	s_add_i32 s17, s17, s55
	v_lshl_add_u64 v[224:225], v[224:225], 0, s[24:25]
	s_mov_b32 m0, s17
	ds_read_b128 v[178:181], v144 offset:49152
	ds_read_b128 v[182:185], v144 offset:50176
	ds_read_b128 v[186:189], v144 offset:51200
	ds_read_b128 v[190:193], v144 offset:52224
	ds_read_b128 v[208:211], v144 offset:53248
	ds_read_b128 v[212:215], v144 offset:54272
	ds_read_b128 v[216:219], v144 offset:55296
	ds_read_b128 v[220:223], v144 offset:56320
	global_load_lds_dwordx4 v[224:225], off
	v_lshl_add_u64 v[224:225], v[228:229], 0, s[24:25]
	s_add_i32 m0, s17, 0x2000
	s_add_i32 s17, s28, s55
	global_load_lds_dwordx4 v[224:225], off
	v_lshl_add_u64 v[224:225], v[230:231], 0, s[24:25]
	s_mov_b32 m0, s17
	s_nop 0
	global_load_lds_dwordx4 v[224:225], off
	v_lshl_add_u64 v[224:225], v[232:233], 0, s[24:25]
	s_add_i32 m0, s17, 0x2000
	s_nop 0
	global_load_lds_dwordx4 v[224:225], off
	v_lshl_add_u64 v[224:225], v[234:235], 0, s[24:25]
	s_mov_b32 m0, s69
	s_nop 0
	global_load_lds_dwordx4 v[224:225], off
	v_lshl_add_u64 v[224:225], v[236:237], 0, s[24:25]
	s_mov_b32 m0, s70
	s_nop 0
	global_load_lds_dwordx4 v[224:225], off
	s_waitcnt vmcnt(8)
	s_waitcnt lgkmcnt(0)
	s_barrier
	s_setprio 1
	v_mfma_f32_16x16x32_bf16 v[62:65], v[146:149], v[178:181], v[62:65]
	v_mfma_f32_16x16x32_bf16 v[58:61], v[154:157], v[178:181], v[58:61]
	v_mfma_f32_16x16x32_bf16 v[46:49], v[146:149], v[186:189], v[46:49]
	v_mfma_f32_16x16x32_bf16 v[42:45], v[154:157], v[186:189], v[42:45]
	v_mfma_f32_16x16x32_bf16 v[30:33], v[146:149], v[208:211], v[30:33]
	v_mfma_f32_16x16x32_bf16 v[26:29], v[154:157], v[208:211], v[26:29]
	v_mfma_f32_16x16x32_bf16 v[14:17], v[146:149], v[216:219], v[14:17]
	v_mfma_f32_16x16x32_bf16 v[10:13], v[154:157], v[216:219], v[10:13]
	v_mfma_f32_16x16x32_bf16 v[62:65], v[150:153], v[182:185], v[62:65]
	v_mfma_f32_16x16x32_bf16 v[58:61], v[158:161], v[182:185], v[58:61]
	v_mfma_f32_16x16x32_bf16 v[46:49], v[150:153], v[190:193], v[46:49]
	v_mfma_f32_16x16x32_bf16 v[42:45], v[158:161], v[190:193], v[42:45]
	v_mfma_f32_16x16x32_bf16 v[30:33], v[150:153], v[212:215], v[30:33]
	v_mfma_f32_16x16x32_bf16 v[26:29], v[158:161], v[212:215], v[26:29]
	v_mfma_f32_16x16x32_bf16 v[14:17], v[150:153], v[220:223], v[14:17]
	v_mfma_f32_16x16x32_bf16 v[10:13], v[158:161], v[220:223], v[10:13]
	v_mfma_f32_16x16x32_bf16 v[54:57], v[162:165], v[178:181], v[54:57]
	v_mfma_f32_16x16x32_bf16 v[50:53], v[170:173], v[178:181], v[50:53]
	v_mfma_f32_16x16x32_bf16 v[38:41], v[162:165], v[186:189], v[38:41]
	v_mfma_f32_16x16x32_bf16 v[34:37], v[170:173], v[186:189], v[34:37]
	v_mfma_f32_16x16x32_bf16 v[22:25], v[162:165], v[208:211], v[22:25]
	v_mfma_f32_16x16x32_bf16 v[18:21], v[170:173], v[208:211], v[18:21]
	v_mfma_f32_16x16x32_bf16 v[6:9], v[162:165], v[216:219], v[6:9]
	v_mfma_f32_16x16x32_bf16 v[2:5], v[170:173], v[216:219], v[2:5]
	v_mfma_f32_16x16x32_bf16 v[54:57], v[166:169], v[182:185], v[54:57]
	v_mfma_f32_16x16x32_bf16 v[50:53], v[174:177], v[182:185], v[50:53]
	v_mfma_f32_16x16x32_bf16 v[38:41], v[166:169], v[190:193], v[38:41]
	v_mfma_f32_16x16x32_bf16 v[34:37], v[174:177], v[190:193], v[34:37]
	v_mfma_f32_16x16x32_bf16 v[22:25], v[166:169], v[212:215], v[22:25]
	v_mfma_f32_16x16x32_bf16 v[18:21], v[174:177], v[212:215], v[18:21]
	v_mfma_f32_16x16x32_bf16 v[6:9], v[166:169], v[220:223], v[6:9]
	v_mfma_f32_16x16x32_bf16 v[2:5], v[174:177], v[220:223], v[2:5]
	s_setprio 0
	s_barrier
	s_add_u32 s34, s34, 0x100
	s_addc_u32 s35, s35, 0
	s_add_u32 s4, s4, 0x100
	s_addc_u32 s16, s16, 0
	s_cmp_ge_i32 s22, s66
	s_mov_b32 s17, s22
	s_cbranch_scc0 .LBB0_544

; #define PG8_STAGE(bufoff, gbase, voff) do { _Pragma("unroll") for (int _i = 0; _i < 2; ++_i) \
;         __builtin_amdgcn_global_load_lds((const unsigned*)((const char*)(gbase) + (voff)[_i]), (PG8_LAS unsigned*)(lds + (bufoff) + ldsw + _i * 8192), 16, 0, 0); } while (0)
; #define PG8_LDA(dst, b, h) do { _Pragma("unroll") for (int m = 0; m < 4; ++m) _Pragma("unroll") for (int k = 0; k < 2; ++k) dst[m][k] = *(const PG8_LAS bf16x8*)(lds + PG8_SA(b, h) + aoff + m * 2048 + k * 1024); } while (0)
; #define PG8_LDB(dst, b, h) do { _Pragma("unroll") for (int n = 0; n < 2; ++n) _Pragma("unroll") for (int k = 0; k < 2; ++k) dst[n][k] = *(const PG8_LAS bf16x8*)(lds + PG8_SB(b, h) + boff + n * 2048 + k * 1024); } while (0)
; #define PG8_MMA(ai, bj, At, Bt) do { __builtin_amdgcn_s_setprio(1); _Pragma("unroll") for (int m = 0; m < 4; ++m) _Pragma("unroll") for (int n = 0; n < 2; ++n) _Pragma("unroll") for (int k = 0; k < 2; ++k) \
;         acc[ai][bj][m][n] = __builtin_amdgcn_mfma_f32_16x16x32_bf16(Bt[n][k], At[m][k], acc[ai][bj][m][n], 0, 0, 0); __builtin_amdgcn_s_setprio(0); } while (0)
; #define PG8_WAIT_V(n) asm volatile("s_waitcnt vmcnt(" #n ")" ::: "memory")
; #define PG8_WAIT_L(n) asm volatile("s_waitcnt lgkmcnt(" #n ")" ::: "memory")
; template <class Epi, class Sched, bool ALIGN_EPI = false, bool SP2 = false>
; __device__ __forceinline__ void gemm_phase(PG8_LAS unsigned char* lds, const Gemm g, const Sched& S, const Epi& E) {
;     ...
;             const bool last = (t == nt - 2);
;             const char* a1 = cA + (size_t)(t + 1) * kstep;
;             const char* a2 = last ? nA : cA + (size_t)(t + 2) * kstep; const char* b2 = last ? nB : cB + (size_t)(t + 2) * kstep;
;             const char* a3 = a2 + kstep; const char* b3 = b2 + kstep;
;             if (last && has_next) S.a_ready(nxt);
;             if constexpr (SP2) {
;             PG8_LDB(B0, 0, 0); PG8_LDB(B1, 0, 1); PG8_SCHED; PG8_LDA(At, 0, 0); PG8_STAGE(PG8_SA(1, 1), a1 + hstep, voffA);
;             PG8_WAIT_V(8); PG8_WAIT_L(0); PG8_BAR; PG8_MMA(0, 0, At, B0); PG8_MMA(0, 1, At, B1); PG8_BAR; PG8_SCHED;
;             PG8_LDA(At, 0, 1); PG8_STAGE(PG8_SB(0, 0), b2, voffB); PG8_STAGE(PG8_SB(0, 1), b2 + hstep, voffB); PG8_STAGE(PG8_SA(0, 0), a2, voffA);
;             PG8_WAIT_V(8); PG8_WAIT_L(0); PG8_BAR; PG8_MMA(1, 0, At, B0); PG8_MMA(1, 1, At, B1); PG8_BAR; PG8_SCHED;
.LBB0_876:
	s_add_i32 s22, s17, 2
	s_add_u32 s28, s34, 0x80
	s_addc_u32 s30, s35, 0
	s_add_i32 s33, 0, 0x10000
	s_cmp_eq_u32 s67, s17
	s_cselect_b32 s37, s3, s30
	s_cselect_b32 s36, s2, s28
	v_add_u32_e32 v149, s33, v146
	s_cselect_b32 s31, s55, s16
	s_cselect_b32 s30, s54, s4
	s_add_i32 s17, 0, 0x14000
	ds_read_b128 v[142:145], v149
	ds_read_b128 v[150:153], v149 offset:1024
	ds_read_b128 v[154:157], v149 offset:2048
	ds_read_b128 v[158:161], v149 offset:3072
	v_add_u32_e32 v149, s17, v146
	ds_read_b128 v[162:165], v149
	ds_read_b128 v[166:169], v149 offset:1024
	ds_read_b128 v[170:173], v149 offset:2048
	ds_read_b128 v[174:177], v149 offset:3072
	v_lshl_add_u64 v[224:225], s[34:35], 0, v[138:139]
	s_add_i32 m0, s60, 0xc000
	ds_read_b128 v[178:181], v148
	ds_read_b128 v[182:185], v148 offset:1024
	ds_read_b128 v[186:189], v148 offset:2048
	ds_read_b128 v[190:193], v148 offset:3072
	ds_read_b128 v[208:211], v148 offset:4096
	ds_read_b128 v[212:215], v148 offset:5120
	ds_read_b128 v[216:219], v148 offset:6144
	ds_read_b128 v[220:223], v148 offset:7168
	global_load_lds_dwordx4 v[224:225], off
	v_lshl_add_u64 v[224:225], s[34:35], 0, v[140:141]
	s_add_i32 m0, s60, 0xe000
	s_nop 0
	global_load_lds_dwordx4 v[224:225], off
	s_waitcnt vmcnt(8)
	s_waitcnt lgkmcnt(0)
	s_barrier
	s_setprio 1
	v_mfma_f32_16x16x32_bf16 v[128:131], v[142:145], v[178:181], v[128:131]
	v_mfma_f32_16x16x32_bf16 v[124:127], v[154:157], v[178:181], v[124:127]
	v_mfma_f32_16x16x32_bf16 v[112:115], v[142:145], v[186:189], v[112:115]
	v_mfma_f32_16x16x32_bf16 v[108:111], v[154:157], v[186:189], v[108:111]
	v_mfma_f32_16x16x32_bf16 v[94:97], v[142:145], v[208:211], v[94:97]
	v_mfma_f32_16x16x32_bf16 v[90:93], v[154:157], v[208:211], v[90:93]
	v_mfma_f32_16x16x32_bf16 v[78:81], v[142:145], v[216:219], v[78:81]
	v_mfma_f32_16x16x32_bf16 v[74:77], v[154:157], v[216:219], v[74:77]
	v_mfma_f32_16x16x32_bf16 v[128:131], v[150:153], v[182:185], v[128:131]
	v_mfma_f32_16x16x32_bf16 v[124:127], v[158:161], v[182:185], v[124:127]
	v_mfma_f32_16x16x32_bf16 v[112:115], v[150:153], v[190:193], v[112:115]
	v_mfma_f32_16x16x32_bf16 v[108:111], v[158:161], v[190:193], v[108:111]
	v_mfma_f32_16x16x32_bf16 v[94:97], v[150:153], v[212:215], v[94:97]
	v_mfma_f32_16x16x32_bf16 v[90:93], v[158:161], v[212:215], v[90:93]
	v_mfma_f32_16x16x32_bf16 v[78:81], v[150:153], v[220:223], v[78:81]
	v_mfma_f32_16x16x32_bf16 v[74:77], v[158:161], v[220:223], v[74:77]
	v_mfma_f32_16x16x32_bf16 v[120:123], v[162:165], v[178:181], v[120:123]
	v_mfma_f32_16x16x32_bf16 v[116:119], v[170:173], v[178:181], v[116:119]
	v_mfma_f32_16x16x32_bf16 v[104:107], v[162:165], v[186:189], v[104:107]
	v_mfma_f32_16x16x32_bf16 v[100:103], v[170:173], v[186:189], v[100:103]
	v_mfma_f32_16x16x32_bf16 v[86:89], v[162:165], v[208:211], v[86:89]
	v_mfma_f32_16x16x32_bf16 v[82:85], v[170:173], v[208:211], v[82:85]
	v_mfma_f32_16x16x32_bf16 v[70:73], v[162:165], v[216:219], v[70:73]
	v_mfma_f32_16x16x32_bf16 v[66:69], v[170:173], v[216:219], v[66:69]
	v_mfma_f32_16x16x32_bf16 v[120:123], v[166:169], v[182:185], v[120:123]
	v_mfma_f32_16x16x32_bf16 v[116:119], v[174:177], v[182:185], v[116:119]
	v_mfma_f32_16x16x32_bf16 v[104:107], v[166:169], v[190:193], v[104:107]
	v_mfma_f32_16x16x32_bf16 v[100:103], v[174:177], v[190:193], v[100:103]
	v_mfma_f32_16x16x32_bf16 v[86:89], v[166:169], v[212:215], v[86:89]
	v_mfma_f32_16x16x32_bf16 v[82:85], v[174:177], v[212:215], v[82:85]
	v_mfma_f32_16x16x32_bf16 v[70:73], v[166:169], v[220:223], v[70:73]
	v_mfma_f32_16x16x32_bf16 v[66:69], v[174:177], v[220:223], v[66:69]
	s_setprio 0
	s_barrier
	s_add_i32 s28, s33, s59
	v_lshl_add_u64 v[224:225], s[30:31], 0, v[98:99]
	s_mov_b32 m0, s28
	ds_read_b128 v[178:181], v148 offset:16384
	ds_read_b128 v[182:185], v148 offset:17408
	ds_read_b128 v[186:189], v148 offset:18432
	ds_read_b128 v[190:193], v148 offset:19456
	ds_read_b128 v[208:211], v148 offset:20480
	ds_read_b128 v[212:215], v148 offset:21504
	ds_read_b128 v[216:219], v148 offset:22528
	ds_read_b128 v[220:223], v148 offset:23552
	global_load_lds_dwordx4 v[224:225], off
	s_add_i32 m0, s28, 0x2000
	v_lshl_add_u64 v[228:229], s[30:31], 0, v[136:137]
	s_add_u32 s30, s30, s8
	s_addc_u32 s31, s31, s9
	s_add_i32 s17, s17, s59
	global_load_lds_dwordx4 v[228:229], off
	v_lshl_add_u64 v[230:231], s[30:31], 0, v[98:99]
	s_mov_b32 m0, s17
	v_lshl_add_u64 v[232:233], s[30:31], 0, v[136:137]
	global_load_lds_dwordx4 v[230:231], off
	s_add_i32 m0, s17, 0x2000
	v_lshl_add_u64 v[234:235], s[36:37], 0, v[132:133]
	global_load_lds_dwordx4 v[232:233], off
	s_mov_b32 m0, s60
	v_lshl_add_u64 v[236:237], s[36:37], 0, v[134:135]
	global_load_lds_dwordx4 v[234:235], off
	s_mov_b32 m0, s61
	s_nop 0
	global_load_lds_dwordx4 v[236:237], off
	s_waitcnt vmcnt(8)
	s_waitcnt lgkmcnt(0)
	s_barrier
; #define PG8_STAGE(bufoff, gbase, voff) do { _Pragma("unroll") for (int _i = 0; _i < 2; ++_i) \
;         __builtin_amdgcn_global_load_lds((const unsigned*)((const char*)(gbase) + (voff)[_i]), (PG8_LAS unsigned*)(lds + (bufoff) + ldsw + _i * 8192), 16, 0, 0); } while (0)
; #define PG8_LDA(dst, b, h) do { _Pragma("unroll") for (int m = 0; m < 4; ++m) _Pragma("unroll") for (int k = 0; k < 2; ++k) dst[m][k] = *(const PG8_LAS bf16x8*)(lds + PG8_SA(b, h) + aoff + m * 2048 + k * 1024); } while (0)
; #define PG8_LDB(dst, b, h) do { _Pragma("unroll") for (int n = 0; n < 2; ++n) _Pragma("unroll") for (int k = 0; k < 2; ++k) dst[n][k] = *(const PG8_LAS bf16x8*)(lds + PG8_SB(b, h) + boff + n * 2048 + k * 1024); } while (0)
; #define PG8_MMA(ai, bj, At, Bt) do { __builtin_amdgcn_s_setprio(1); _Pragma("unroll") for (int m = 0; m < 4; ++m) _Pragma("unroll") for (int n = 0; n < 2; ++n) _Pragma("unroll") for (int k = 0; k < 2; ++k) \
;         acc[ai][bj][m][n] = __builtin_amdgcn_mfma_f32_16x16x32_bf16(Bt[n][k], At[m][k], acc[ai][bj][m][n], 0, 0, 0); __builtin_amdgcn_s_setprio(0); } while (0)
; #define PG8_WAIT_V(n) asm volatile("s_waitcnt vmcnt(" #n ")" ::: "memory")
; #define PG8_WAIT_L(n) asm volatile("s_waitcnt lgkmcnt(" #n ")" ::: "memory")
; #define PG8_BAR __builtin_amdgcn_s_barrier()
; #define PG8_SCHED __builtin_amdgcn_sched_barrier(0)
; template <class Epi, class Sched, bool ALIGN_EPI = false, bool SP2 = false>
; __device__ __forceinline__ void gemm_phase(PG8_LAS unsigned char* lds, const Gemm g, const Sched& S, const Epi& E) {
;     ...
;             PG8_WAIT_V(8); PG8_WAIT_L(0); PG8_BAR; PG8_MMA(1, 0, At, B0); PG8_MMA(1, 1, At, B1); PG8_BAR; PG8_SCHED;
;             PG8_LDB(B0, 1, 0); PG8_LDB(B1, 1, 1); PG8_SCHED; PG8_LDA(At, 1, 0); PG8_STAGE(PG8_SA(0, 1), a2 + hstep, voffA);
;             PG8_WAIT_V(8); PG8_WAIT_L(0); PG8_BAR; PG8_MMA(0, 0, At, B0); PG8_MMA(0, 1, At, B1); PG8_BAR; PG8_SCHED;
	s_setprio 1
	v_mfma_f32_16x16x32_bf16 v[62:65], v[142:145], v[178:181], v[62:65]
	v_mfma_f32_16x16x32_bf16 v[58:61], v[154:157], v[178:181], v[58:61]
	v_mfma_f32_16x16x32_bf16 v[46:49], v[142:145], v[186:189], v[46:49]
	v_mfma_f32_16x16x32_bf16 v[42:45], v[154:157], v[186:189], v[42:45]
	v_mfma_f32_16x16x32_bf16 v[30:33], v[142:145], v[208:211], v[30:33]
	v_mfma_f32_16x16x32_bf16 v[26:29], v[154:157], v[208:211], v[26:29]
	v_mfma_f32_16x16x32_bf16 v[14:17], v[142:145], v[216:219], v[14:17]
	v_mfma_f32_16x16x32_bf16 v[10:13], v[154:157], v[216:219], v[10:13]
	v_mfma_f32_16x16x32_bf16 v[62:65], v[150:153], v[182:185], v[62:65]
	v_mfma_f32_16x16x32_bf16 v[58:61], v[158:161], v[182:185], v[58:61]
	v_mfma_f32_16x16x32_bf16 v[46:49], v[150:153], v[190:193], v[46:49]
	v_mfma_f32_16x16x32_bf16 v[42:45], v[158:161], v[190:193], v[42:45]
	v_mfma_f32_16x16x32_bf16 v[30:33], v[150:153], v[212:215], v[30:33]
	v_mfma_f32_16x16x32_bf16 v[26:29], v[158:161], v[212:215], v[26:29]
	v_mfma_f32_16x16x32_bf16 v[14:17], v[150:153], v[220:223], v[14:17]
	v_mfma_f32_16x16x32_bf16 v[10:13], v[158:161], v[220:223], v[10:13]
	v_mfma_f32_16x16x32_bf16 v[54:57], v[162:165], v[178:181], v[54:57]
	v_mfma_f32_16x16x32_bf16 v[50:53], v[170:173], v[178:181], v[50:53]
	v_mfma_f32_16x16x32_bf16 v[38:41], v[162:165], v[186:189], v[38:41]
	v_mfma_f32_16x16x32_bf16 v[34:37], v[170:173], v[186:189], v[34:37]
	v_mfma_f32_16x16x32_bf16 v[22:25], v[162:165], v[208:211], v[22:25]
	v_mfma_f32_16x16x32_bf16 v[18:21], v[170:173], v[208:211], v[18:21]
	v_mfma_f32_16x16x32_bf16 v[6:9], v[162:165], v[216:219], v[6:9]
	v_mfma_f32_16x16x32_bf16 v[2:5], v[170:173], v[216:219], v[2:5]
	v_mfma_f32_16x16x32_bf16 v[54:57], v[166:169], v[182:185], v[54:57]
	v_mfma_f32_16x16x32_bf16 v[50:53], v[174:177], v[182:185], v[50:53]
	v_mfma_f32_16x16x32_bf16 v[38:41], v[166:169], v[190:193], v[38:41]
	v_mfma_f32_16x16x32_bf16 v[34:37], v[174:177], v[190:193], v[34:37]
	v_mfma_f32_16x16x32_bf16 v[22:25], v[166:169], v[212:215], v[22:25]
	v_mfma_f32_16x16x32_bf16 v[18:21], v[174:177], v[212:215], v[18:21]
	v_mfma_f32_16x16x32_bf16 v[6:9], v[166:169], v[220:223], v[6:9]
	v_mfma_f32_16x16x32_bf16 v[2:5], v[174:177], v[220:223], v[2:5]
	s_setprio 0
	s_barrier
	s_add_i32 s17, 0, 0x18000
	v_add_u32_e32 v149, s17, v146
	s_add_i32 s28, 0, 0x1c000
	ds_read_b128 v[142:145], v149
	ds_read_b128 v[150:153], v149 offset:1024
	ds_read_b128 v[154:157], v149 offset:2048
	ds_read_b128 v[158:161], v149 offset:3072
	v_add_u32_e32 v149, s28, v146
	ds_read_b128 v[162:165], v149
	ds_read_b128 v[166:169], v149 offset:1024
	ds_read_b128 v[170:173], v149 offset:2048
	ds_read_b128 v[174:177], v149 offset:3072
	s_add_u32 s30, s36, s8
	s_addc_u32 s31, s37, s9
	s_mov_b32 m0, s62
	v_lshl_add_u64 v[238:239], s[30:31], 0, v[132:133]
	ds_read_b128 v[178:181], v148 offset:32768
	ds_read_b128 v[182:185], v148 offset:33792
	ds_read_b128 v[186:189], v148 offset:34816
	ds_read_b128 v[190:193], v148 offset:35840
	ds_read_b128 v[208:211], v148 offset:36864
	ds_read_b128 v[212:215], v148 offset:37888
	ds_read_b128 v[216:219], v148 offset:38912
	ds_read_b128 v[220:223], v148 offset:39936
	global_load_lds_dwordx4 v[238:239], off
	v_lshl_add_u64 v[238:239], s[30:31], 0, v[134:135]
	s_mov_b32 m0, s63
	s_nop 0
	global_load_lds_dwordx4 v[238:239], off
	s_waitcnt vmcnt(8)
	s_waitcnt lgkmcnt(0)
	s_barrier
	s_setprio 1
	v_mfma_f32_16x16x32_bf16 v[128:131], v[142:145], v[178:181], v[128:131]
	v_mfma_f32_16x16x32_bf16 v[124:127], v[154:157], v[178:181], v[124:127]
	v_mfma_f32_16x16x32_bf16 v[112:115], v[142:145], v[186:189], v[112:115]
	v_mfma_f32_16x16x32_bf16 v[108:111], v[154:157], v[186:189], v[108:111]
	v_mfma_f32_16x16x32_bf16 v[94:97], v[142:145], v[208:211], v[94:97]
	v_mfma_f32_16x16x32_bf16 v[90:93], v[154:157], v[208:211], v[90:93]
	v_mfma_f32_16x16x32_bf16 v[78:81], v[142:145], v[216:219], v[78:81]
	v_mfma_f32_16x16x32_bf16 v[74:77], v[154:157], v[216:219], v[74:77]
	v_mfma_f32_16x16x32_bf16 v[128:131], v[150:153], v[182:185], v[128:131]
	v_mfma_f32_16x16x32_bf16 v[124:127], v[158:161], v[182:185], v[124:127]
	v_mfma_f32_16x16x32_bf16 v[112:115], v[150:153], v[190:193], v[112:115]
	v_mfma_f32_16x16x32_bf16 v[108:111], v[158:161], v[190:193], v[108:111]
	v_mfma_f32_16x16x32_bf16 v[94:97], v[150:153], v[212:215], v[94:97]
	v_mfma_f32_16x16x32_bf16 v[90:93], v[158:161], v[212:215], v[90:93]
	v_mfma_f32_16x16x32_bf16 v[78:81], v[150:153], v[220:223], v[78:81]
	v_mfma_f32_16x16x32_bf16 v[74:77], v[158:161], v[220:223], v[74:77]
	v_mfma_f32_16x16x32_bf16 v[120:123], v[162:165], v[178:181], v[120:123]
	v_mfma_f32_16x16x32_bf16 v[116:119], v[170:173], v[178:181], v[116:119]
	v_mfma_f32_16x16x32_bf16 v[104:107], v[162:165], v[186:189], v[104:107]
	v_mfma_f32_16x16x32_bf16 v[100:103], v[170:173], v[186:189], v[100:103]
	v_mfma_f32_16x16x32_bf16 v[86:89], v[162:165], v[208:211], v[86:89]
	v_mfma_f32_16x16x32_bf16 v[82:85], v[170:173], v[208:211], v[82:85]
	v_mfma_f32_16x16x32_bf16 v[70:73], v[162:165], v[216:219], v[70:73]
	v_mfma_f32_16x16x32_bf16 v[66:69], v[170:173], v[216:219], v[66:69]
	v_mfma_f32_16x16x32_bf16 v[120:123], v[166:169], v[182:185], v[120:123]
	v_mfma_f32_16x16x32_bf16 v[116:119], v[174:177], v[182:185], v[116:119]
	v_mfma_f32_16x16x32_bf16 v[104:107], v[166:169], v[190:193], v[104:107]
	v_mfma_f32_16x16x32_bf16 v[100:103], v[174:177], v[190:193], v[100:103]
	v_mfma_f32_16x16x32_bf16 v[86:89], v[166:169], v[212:215], v[86:89]
	v_mfma_f32_16x16x32_bf16 v[82:85], v[174:177], v[212:215], v[82:85]
	v_mfma_f32_16x16x32_bf16 v[70:73], v[166:169], v[220:223], v[70:73]
	v_mfma_f32_16x16x32_bf16 v[66:69], v[174:177], v[220:223], v[66:69]
	s_setprio 0
	s_barrier
; #define PG8_STAGE(bufoff, gbase, voff) do { _Pragma("unroll") for (int _i = 0; _i < 2; ++_i) \
;         __builtin_amdgcn_global_load_lds((const unsigned*)((const char*)(gbase) + (voff)[_i]), (PG8_LAS unsigned*)(lds + (bufoff) + ldsw + _i * 8192), 16, 0, 0); } while (0)
; #define PG8_LDA(dst, b, h) do { _Pragma("unroll") for (int m = 0; m < 4; ++m) _Pragma("unroll") for (int k = 0; k < 2; ++k) dst[m][k] = *(const PG8_LAS bf16x8*)(lds + PG8_SA(b, h) + aoff + m * 2048 + k * 1024); } while (0)
; #define PG8_MMA(ai, bj, At, Bt) do { __builtin_amdgcn_s_setprio(1); _Pragma("unroll") for (int m = 0; m < 4; ++m) _Pragma("unroll") for (int n = 0; n < 2; ++n) _Pragma("unroll") for (int k = 0; k < 2; ++k) \
;         acc[ai][bj][m][n] = __builtin_amdgcn_mfma_f32_16x16x32_bf16(Bt[n][k], At[m][k], acc[ai][bj][m][n], 0, 0, 0); __builtin_amdgcn_s_setprio(0); } while (0)
; #define PG8_WAIT_V(n) asm volatile("s_waitcnt vmcnt(" #n ")" ::: "memory")
; #define PG8_WAIT_L(n) asm volatile("s_waitcnt lgkmcnt(" #n ")" ::: "memory")
; #define PG8_BAR __builtin_amdgcn_s_barrier()
; #define PG8_SCHED __builtin_amdgcn_sched_barrier(0)
; template <class Epi, class Sched, bool ALIGN_EPI = false, bool SP2 = false>
; __device__ __forceinline__ void gemm_phase(PG8_LAS unsigned char* lds, const Gemm g, const Sched& S, const Epi& E) {
;     ...
;             PG8_LDA(At, 1, 1); PG8_STAGE(PG8_SB(1, 0), b3, voffB); PG8_STAGE(PG8_SB(1, 1), b3 + hstep, voffB); PG8_STAGE(PG8_SA(1, 0), a3, voffA);
;             PG8_WAIT_V(8); PG8_WAIT_L(0); PG8_BAR; PG8_MMA(1, 0, At, B0); PG8_MMA(1, 1, At, B1); PG8_BAR; PG8_SCHED;
	s_add_i32 s17, s17, s59
	v_lshl_add_u64 v[224:225], v[224:225], 0, s[24:25]
	s_mov_b32 m0, s17
	ds_read_b128 v[178:181], v148 offset:49152
	ds_read_b128 v[182:185], v148 offset:50176
	ds_read_b128 v[186:189], v148 offset:51200
	ds_read_b128 v[190:193], v148 offset:52224
	ds_read_b128 v[208:211], v148 offset:53248
	ds_read_b128 v[212:215], v148 offset:54272
	ds_read_b128 v[216:219], v148 offset:55296
	ds_read_b128 v[220:223], v148 offset:56320
	global_load_lds_dwordx4 v[224:225], off
	v_lshl_add_u64 v[224:225], v[228:229], 0, s[24:25]
	s_add_i32 m0, s17, 0x2000
	s_add_i32 s17, s28, s59
	global_load_lds_dwordx4 v[224:225], off
	v_lshl_add_u64 v[224:225], v[230:231], 0, s[24:25]
	s_mov_b32 m0, s17
	s_nop 0
	global_load_lds_dwordx4 v[224:225], off
	v_lshl_add_u64 v[224:225], v[232:233], 0, s[24:25]
	s_add_i32 m0, s17, 0x2000
	s_nop 0
	global_load_lds_dwordx4 v[224:225], off
	v_lshl_add_u64 v[224:225], v[234:235], 0, s[24:25]
	s_mov_b32 m0, s65
	s_nop 0
	global_load_lds_dwordx4 v[224:225], off
	v_lshl_add_u64 v[224:225], v[236:237], 0, s[24:25]
	s_mov_b32 m0, s66
	s_nop 0
	global_load_lds_dwordx4 v[224:225], off
	s_waitcnt vmcnt(8)
	s_waitcnt lgkmcnt(0)
	s_barrier
	s_setprio 1
	v_mfma_f32_16x16x32_bf16 v[62:65], v[142:145], v[178:181], v[62:65]
	v_mfma_f32_16x16x32_bf16 v[58:61], v[154:157], v[178:181], v[58:61]
	v_mfma_f32_16x16x32_bf16 v[46:49], v[142:145], v[186:189], v[46:49]
	v_mfma_f32_16x16x32_bf16 v[42:45], v[154:157], v[186:189], v[42:45]
	v_mfma_f32_16x16x32_bf16 v[30:33], v[142:145], v[208:211], v[30:33]
	v_mfma_f32_16x16x32_bf16 v[26:29], v[154:157], v[208:211], v[26:29]
	v_mfma_f32_16x16x32_bf16 v[14:17], v[142:145], v[216:219], v[14:17]
	v_mfma_f32_16x16x32_bf16 v[10:13], v[154:157], v[216:219], v[10:13]
	v_mfma_f32_16x16x32_bf16 v[62:65], v[150:153], v[182:185], v[62:65]
	v_mfma_f32_16x16x32_bf16 v[58:61], v[158:161], v[182:185], v[58:61]
	v_mfma_f32_16x16x32_bf16 v[46:49], v[150:153], v[190:193], v[46:49]
	v_mfma_f32_16x16x32_bf16 v[42:45], v[158:161], v[190:193], v[42:45]
	v_mfma_f32_16x16x32_bf16 v[30:33], v[150:153], v[212:215], v[30:33]
	v_mfma_f32_16x16x32_bf16 v[26:29], v[158:161], v[212:215], v[26:29]
	v_mfma_f32_16x16x32_bf16 v[14:17], v[150:153], v[220:223], v[14:17]
	v_mfma_f32_16x16x32_bf16 v[10:13], v[158:161], v[220:223], v[10:13]
	v_mfma_f32_16x16x32_bf16 v[54:57], v[162:165], v[178:181], v[54:57]
	v_mfma_f32_16x16x32_bf16 v[50:53], v[170:173], v[178:181], v[50:53]
	v_mfma_f32_16x16x32_bf16 v[38:41], v[162:165], v[186:189], v[38:41]
	v_mfma_f32_16x16x32_bf16 v[34:37], v[170:173], v[186:189], v[34:37]
	v_mfma_f32_16x16x32_bf16 v[22:25], v[162:165], v[208:211], v[22:25]
	v_mfma_f32_16x16x32_bf16 v[18:21], v[170:173], v[208:211], v[18:21]
	v_mfma_f32_16x16x32_bf16 v[6:9], v[162:165], v[216:219], v[6:9]
	v_mfma_f32_16x16x32_bf16 v[2:5], v[170:173], v[216:219], v[2:5]
	v_mfma_f32_16x16x32_bf16 v[54:57], v[166:169], v[182:185], v[54:57]
	v_mfma_f32_16x16x32_bf16 v[50:53], v[174:177], v[182:185], v[50:53]
	v_mfma_f32_16x16x32_bf16 v[38:41], v[166:169], v[190:193], v[38:41]
	v_mfma_f32_16x16x32_bf16 v[34:37], v[174:177], v[190:193], v[34:37]
	v_mfma_f32_16x16x32_bf16 v[22:25], v[166:169], v[212:215], v[22:25]
	v_mfma_f32_16x16x32_bf16 v[18:21], v[174:177], v[212:215], v[18:21]
	v_mfma_f32_16x16x32_bf16 v[6:9], v[166:169], v[220:223], v[6:9]
	v_mfma_f32_16x16x32_bf16 v[2:5], v[174:177], v[220:223], v[2:5]
	s_setprio 0
	s_barrier
	s_add_u32 s34, s34, 0x100
	s_addc_u32 s35, s35, 0
	s_add_u32 s4, s4, 0x100
	s_addc_u32 s16, s16, 0
	s_cmp_ge_i32 s22, s64
	s_mov_b32 s17, s22
	s_cbranch_scc0 .LBB0_876

; #define PG8_STAGE(bufoff, gbase, voff) do { _Pragma("unroll") for (int _i = 0; _i < 2; ++_i) \
;         __builtin_amdgcn_global_load_lds((const unsigned*)((const char*)(gbase) + (voff)[_i]), (PG8_LAS unsigned*)(lds + (bufoff) + ldsw + _i * 8192), 16, 0, 0); } while (0)
; #define PG8_LDA(dst, b, h) do { _Pragma("unroll") for (int m = 0; m < 4; ++m) _Pragma("unroll") for (int k = 0; k < 2; ++k) dst[m][k] = *(const PG8_LAS bf16x8*)(lds + PG8_SA(b, h) + aoff + m * 2048 + k * 1024); } while (0)
; #define PG8_LDB(dst, b, h) do { _Pragma("unroll") for (int n = 0; n < 2; ++n) _Pragma("unroll") for (int k = 0; k < 2; ++k) dst[n][k] = *(const PG8_LAS bf16x8*)(lds + PG8_SB(b, h) + boff + n * 2048 + k * 1024); } while (0)
; #define PG8_MMA(ai, bj, At, Bt) do { __builtin_amdgcn_s_setprio(1); _Pragma("unroll") for (int m = 0; m < 4; ++m) _Pragma("unroll") for (int n = 0; n < 2; ++n) _Pragma("unroll") for (int k = 0; k < 2; ++k) \
;         acc[ai][bj][m][n] = __builtin_amdgcn_mfma_f32_16x16x32_bf16(Bt[n][k], At[m][k], acc[ai][bj][m][n], 0, 0, 0); __builtin_amdgcn_s_setprio(0); } while (0)
; #define PG8_WAIT_V(n) asm volatile("s_waitcnt vmcnt(" #n ")" ::: "memory")
; #define PG8_WAIT_L(n) asm volatile("s_waitcnt lgkmcnt(" #n ")" ::: "memory")
; template <class Epi, class Sched, bool ALIGN_EPI = false, bool SP2 = false>
; __device__ __forceinline__ void gemm_phase(PG8_LAS unsigned char* lds, const Gemm g, const Sched& S, const Epi& E) {
;     ...
;             const bool last = (t == nt - 2);
;             const char* a1 = cA + (size_t)(t + 1) * kstep;
;             const char* a2 = last ? nA : cA + (size_t)(t + 2) * kstep; const char* b2 = last ? nB : cB + (size_t)(t + 2) * kstep;
;             const char* a3 = a2 + kstep; const char* b3 = b2 + kstep;
;             if (last && has_next) S.a_ready(nxt);
;             if constexpr (SP2) {
;             PG8_LDB(B0, 0, 0); PG8_LDB(B1, 0, 1); PG8_SCHED; PG8_LDA(At, 0, 0); PG8_STAGE(PG8_SA(1, 1), a1 + hstep, voffA);
;             PG8_WAIT_V(8); PG8_WAIT_L(0); PG8_BAR; PG8_MMA(0, 0, At, B0); PG8_MMA(0, 1, At, B1); PG8_BAR; PG8_SCHED;
;             PG8_LDA(At, 0, 1); PG8_STAGE(PG8_SB(0, 0), b2, voffB); PG8_STAGE(PG8_SB(0, 1), b2 + hstep, voffB); PG8_STAGE(PG8_SA(0, 0), a2, voffA);
;             PG8_WAIT_V(8); PG8_WAIT_L(0); PG8_BAR; PG8_MMA(1, 0, At, B0); PG8_MMA(1, 1, At, B1); PG8_BAR; PG8_SCHED;
.LBB0_967:
	s_add_i32 s22, s17, 2
	s_add_u32 s28, s34, 0x80
	s_addc_u32 s30, s35, 0
	s_add_i32 s33, 0, 0x10000
	s_cmp_eq_u32 s88, s17
	s_cselect_b32 s37, s3, s30
	s_cselect_b32 s36, s2, s28
	v_add_u32_e32 v98, s33, v145
	s_cselect_b32 s31, s59, s16
	s_cselect_b32 s30, s58, s4
	s_add_i32 s17, 0, 0x14000
	ds_read_b128 v[132:135], v98
	ds_read_b128 v[156:159], v98 offset:1024
	ds_read_b128 v[160:163], v98 offset:2048
	ds_read_b128 v[164:167], v98 offset:3072
	v_add_u32_e32 v98, s17, v145
	ds_read_b128 v[168:171], v98
	ds_read_b128 v[172:175], v98 offset:1024
	ds_read_b128 v[180:183], v98 offset:2048
	ds_read_b128 v[184:187], v98 offset:3072
	v_lshl_add_u64 v[176:177], s[34:35], 0, v[150:151]
	s_add_i32 m0, s70, 0xc000
	ds_read_b128 v[188:191], v178
	ds_read_b128 v[208:211], v178 offset:1024
	ds_read_b128 v[212:215], v178 offset:2048
	ds_read_b128 v[216:219], v178 offset:3072
	ds_read_b128 v[220:223], v178 offset:4096
	ds_read_b128 v[228:231], v178 offset:5120
	ds_read_b128 v[232:235], v178 offset:6144
	ds_read_b128 v[236:239], v178 offset:7168
	global_load_lds_dwordx4 v[176:177], off
	v_lshl_add_u64 v[176:177], s[34:35], 0, v[152:153]
	s_add_i32 m0, s70, 0xe000
	s_nop 0
	global_load_lds_dwordx4 v[176:177], off
	s_waitcnt vmcnt(8)
	s_waitcnt lgkmcnt(0)
	s_barrier
	s_setprio 1
	v_mfma_f32_16x16x32_bf16 v[128:131], v[132:135], v[188:191], v[128:131]
	v_mfma_f32_16x16x32_bf16 v[124:127], v[160:163], v[188:191], v[124:127]
	v_mfma_f32_16x16x32_bf16 v[112:115], v[132:135], v[212:215], v[112:115]
	v_mfma_f32_16x16x32_bf16 v[108:111], v[160:163], v[212:215], v[108:111]
	v_mfma_f32_16x16x32_bf16 v[94:97], v[132:135], v[220:223], v[94:97]
	v_mfma_f32_16x16x32_bf16 v[90:93], v[160:163], v[220:223], v[90:93]
	v_mfma_f32_16x16x32_bf16 v[78:81], v[132:135], v[232:235], v[78:81]
	v_mfma_f32_16x16x32_bf16 v[74:77], v[160:163], v[232:235], v[74:77]
	v_mfma_f32_16x16x32_bf16 v[128:131], v[156:159], v[208:211], v[128:131]
	v_mfma_f32_16x16x32_bf16 v[124:127], v[164:167], v[208:211], v[124:127]
	v_mfma_f32_16x16x32_bf16 v[112:115], v[156:159], v[216:219], v[112:115]
	v_mfma_f32_16x16x32_bf16 v[108:111], v[164:167], v[216:219], v[108:111]
	v_mfma_f32_16x16x32_bf16 v[94:97], v[156:159], v[228:231], v[94:97]
	v_mfma_f32_16x16x32_bf16 v[90:93], v[164:167], v[228:231], v[90:93]
	v_mfma_f32_16x16x32_bf16 v[78:81], v[156:159], v[236:239], v[78:81]
	v_mfma_f32_16x16x32_bf16 v[74:77], v[164:167], v[236:239], v[74:77]
	v_mfma_f32_16x16x32_bf16 v[120:123], v[168:171], v[188:191], v[120:123]
	v_mfma_f32_16x16x32_bf16 v[116:119], v[180:183], v[188:191], v[116:119]
	v_mfma_f32_16x16x32_bf16 v[104:107], v[168:171], v[212:215], v[104:107]
	v_mfma_f32_16x16x32_bf16 v[100:103], v[180:183], v[212:215], v[100:103]
	v_mfma_f32_16x16x32_bf16 v[86:89], v[168:171], v[220:223], v[86:89]
	v_mfma_f32_16x16x32_bf16 v[82:85], v[180:183], v[220:223], v[82:85]
	v_mfma_f32_16x16x32_bf16 v[70:73], v[168:171], v[232:235], v[70:73]
	v_mfma_f32_16x16x32_bf16 v[66:69], v[180:183], v[232:235], v[66:69]
	v_mfma_f32_16x16x32_bf16 v[120:123], v[172:175], v[208:211], v[120:123]
	v_mfma_f32_16x16x32_bf16 v[116:119], v[184:187], v[208:211], v[116:119]
	v_mfma_f32_16x16x32_bf16 v[104:107], v[172:175], v[216:219], v[104:107]
	v_mfma_f32_16x16x32_bf16 v[100:103], v[184:187], v[216:219], v[100:103]
	v_mfma_f32_16x16x32_bf16 v[86:89], v[172:175], v[228:231], v[86:89]
	v_mfma_f32_16x16x32_bf16 v[82:85], v[184:187], v[228:231], v[82:85]
	v_mfma_f32_16x16x32_bf16 v[70:73], v[172:175], v[236:239], v[70:73]
	v_mfma_f32_16x16x32_bf16 v[66:69], v[184:187], v[236:239], v[66:69]
	s_setprio 0
	s_barrier
	s_add_i32 s28, s33, s69
	v_lshl_add_u64 v[176:177], s[30:31], 0, v[138:139]
	s_mov_b32 m0, s28
	ds_read_b128 v[188:191], v178 offset:16384
	ds_read_b128 v[208:211], v178 offset:17408
	ds_read_b128 v[212:215], v178 offset:18432
	ds_read_b128 v[216:219], v178 offset:19456
	ds_read_b128 v[220:223], v178 offset:20480
	ds_read_b128 v[228:231], v178 offset:21504
	ds_read_b128 v[232:235], v178 offset:22528
	ds_read_b128 v[236:239], v178 offset:23552
	global_load_lds_dwordx4 v[176:177], off
	s_add_i32 m0, s28, 0x2000
	v_lshl_add_u64 v[192:193], s[30:31], 0, v[142:143]
	s_add_u32 s30, s30, s40
	s_addc_u32 s31, s31, s41
	s_add_i32 s17, s17, s69
	global_load_lds_dwordx4 v[192:193], off
	v_lshl_add_u64 v[224:225], s[30:31], 0, v[138:139]
	s_mov_b32 m0, s17
	v_lshl_add_u64 v[240:241], s[30:31], 0, v[142:143]
	global_load_lds_dwordx4 v[224:225], off
	s_add_i32 m0, s17, 0x2000
	v_lshl_add_u64 v[242:243], s[36:37], 0, v[136:137]
	global_load_lds_dwordx4 v[240:241], off
	s_mov_b32 m0, s70
	v_lshl_add_u64 v[244:245], s[36:37], 0, v[140:141]
	global_load_lds_dwordx4 v[242:243], off
	s_mov_b32 m0, s71
	s_nop 0
	global_load_lds_dwordx4 v[244:245], off
	s_waitcnt vmcnt(8)
	s_waitcnt lgkmcnt(0)
	s_barrier
; #define PG8_STAGE(bufoff, gbase, voff) do { _Pragma("unroll") for (int _i = 0; _i < 2; ++_i) \
;         __builtin_amdgcn_global_load_lds((const unsigned*)((const char*)(gbase) + (voff)[_i]), (PG8_LAS unsigned*)(lds + (bufoff) + ldsw + _i * 8192), 16, 0, 0); } while (0)
; #define PG8_LDA(dst, b, h) do { _Pragma("unroll") for (int m = 0; m < 4; ++m) _Pragma("unroll") for (int k = 0; k < 2; ++k) dst[m][k] = *(const PG8_LAS bf16x8*)(lds + PG8_SA(b, h) + aoff + m * 2048 + k * 1024); } while (0)
; #define PG8_LDB(dst, b, h) do { _Pragma("unroll") for (int n = 0; n < 2; ++n) _Pragma("unroll") for (int k = 0; k < 2; ++k) dst[n][k] = *(const PG8_LAS bf16x8*)(lds + PG8_SB(b, h) + boff + n * 2048 + k * 1024); } while (0)
; #define PG8_MMA(ai, bj, At, Bt) do { __builtin_amdgcn_s_setprio(1); _Pragma("unroll") for (int m = 0; m < 4; ++m) _Pragma("unroll") for (int n = 0; n < 2; ++n) _Pragma("unroll") for (int k = 0; k < 2; ++k) \
;         acc[ai][bj][m][n] = __builtin_amdgcn_mfma_f32_16x16x32_bf16(Bt[n][k], At[m][k], acc[ai][bj][m][n], 0, 0, 0); __builtin_amdgcn_s_setprio(0); } while (0)
; #define PG8_WAIT_V(n) asm volatile("s_waitcnt vmcnt(" #n ")" ::: "memory")
; #define PG8_WAIT_L(n) asm volatile("s_waitcnt lgkmcnt(" #n ")" ::: "memory")
; #define PG8_BAR __builtin_amdgcn_s_barrier()
; #define PG8_SCHED __builtin_amdgcn_sched_barrier(0)
; template <class Epi, class Sched, bool ALIGN_EPI = false, bool SP2 = false>
; __device__ __forceinline__ void gemm_phase(PG8_LAS unsigned char* lds, const Gemm g, const Sched& S, const Epi& E) {
;     ...
;             PG8_WAIT_V(8); PG8_WAIT_L(0); PG8_BAR; PG8_MMA(1, 0, At, B0); PG8_MMA(1, 1, At, B1); PG8_BAR; PG8_SCHED;
;             PG8_LDB(B0, 1, 0); PG8_LDB(B1, 1, 1); PG8_SCHED; PG8_LDA(At, 1, 0); PG8_STAGE(PG8_SA(0, 1), a2 + hstep, voffA);
;             PG8_WAIT_V(8); PG8_WAIT_L(0); PG8_BAR; PG8_MMA(0, 0, At, B0); PG8_MMA(0, 1, At, B1); PG8_BAR; PG8_SCHED;
	s_setprio 1
	v_mfma_f32_16x16x32_bf16 v[62:65], v[132:135], v[188:191], v[62:65]
	v_mfma_f32_16x16x32_bf16 v[58:61], v[160:163], v[188:191], v[58:61]
	v_mfma_f32_16x16x32_bf16 v[46:49], v[132:135], v[212:215], v[46:49]
	v_mfma_f32_16x16x32_bf16 v[42:45], v[160:163], v[212:215], v[42:45]
	v_mfma_f32_16x16x32_bf16 v[30:33], v[132:135], v[220:223], v[30:33]
	v_mfma_f32_16x16x32_bf16 v[26:29], v[160:163], v[220:223], v[26:29]
	v_mfma_f32_16x16x32_bf16 v[14:17], v[132:135], v[232:235], v[14:17]
	v_mfma_f32_16x16x32_bf16 v[10:13], v[160:163], v[232:235], v[10:13]
	v_mfma_f32_16x16x32_bf16 v[62:65], v[156:159], v[208:211], v[62:65]
	v_mfma_f32_16x16x32_bf16 v[58:61], v[164:167], v[208:211], v[58:61]
	v_mfma_f32_16x16x32_bf16 v[46:49], v[156:159], v[216:219], v[46:49]
	v_mfma_f32_16x16x32_bf16 v[42:45], v[164:167], v[216:219], v[42:45]
	v_mfma_f32_16x16x32_bf16 v[30:33], v[156:159], v[228:231], v[30:33]
	v_mfma_f32_16x16x32_bf16 v[26:29], v[164:167], v[228:231], v[26:29]
	v_mfma_f32_16x16x32_bf16 v[14:17], v[156:159], v[236:239], v[14:17]
	v_mfma_f32_16x16x32_bf16 v[10:13], v[164:167], v[236:239], v[10:13]
	v_mfma_f32_16x16x32_bf16 v[54:57], v[168:171], v[188:191], v[54:57]
	v_mfma_f32_16x16x32_bf16 v[50:53], v[180:183], v[188:191], v[50:53]
	v_mfma_f32_16x16x32_bf16 v[38:41], v[168:171], v[212:215], v[38:41]
	v_mfma_f32_16x16x32_bf16 v[34:37], v[180:183], v[212:215], v[34:37]
	v_mfma_f32_16x16x32_bf16 v[22:25], v[168:171], v[220:223], v[22:25]
	v_mfma_f32_16x16x32_bf16 v[18:21], v[180:183], v[220:223], v[18:21]
	v_mfma_f32_16x16x32_bf16 v[6:9], v[168:171], v[232:235], v[6:9]
	v_mfma_f32_16x16x32_bf16 v[2:5], v[180:183], v[232:235], v[2:5]
	v_mfma_f32_16x16x32_bf16 v[54:57], v[172:175], v[208:211], v[54:57]
	v_mfma_f32_16x16x32_bf16 v[50:53], v[184:187], v[208:211], v[50:53]
	v_mfma_f32_16x16x32_bf16 v[38:41], v[172:175], v[216:219], v[38:41]
	v_mfma_f32_16x16x32_bf16 v[34:37], v[184:187], v[216:219], v[34:37]
	v_mfma_f32_16x16x32_bf16 v[22:25], v[172:175], v[228:231], v[22:25]
	v_mfma_f32_16x16x32_bf16 v[18:21], v[184:187], v[228:231], v[18:21]
	v_mfma_f32_16x16x32_bf16 v[6:9], v[172:175], v[236:239], v[6:9]
	v_mfma_f32_16x16x32_bf16 v[2:5], v[184:187], v[236:239], v[2:5]
	s_setprio 0
	s_barrier
	s_add_i32 s17, 0, 0x18000
	v_add_u32_e32 v98, s17, v145
	s_add_i32 s28, 0, 0x1c000
	ds_read_b128 v[132:135], v98
	ds_read_b128 v[156:159], v98 offset:1024
	ds_read_b128 v[160:163], v98 offset:2048
	ds_read_b128 v[164:167], v98 offset:3072
	v_add_u32_e32 v98, s28, v145
	ds_read_b128 v[168:171], v98
	ds_read_b128 v[172:175], v98 offset:1024
	ds_read_b128 v[180:183], v98 offset:2048
	ds_read_b128 v[184:187], v98 offset:3072
	s_add_u32 s30, s36, s40
	s_addc_u32 s31, s37, s41
	s_mov_b32 m0, s72
	v_lshl_add_u64 v[246:247], s[30:31], 0, v[136:137]
	ds_read_b128 v[188:191], v178 offset:32768
	ds_read_b128 v[208:211], v178 offset:33792
	ds_read_b128 v[212:215], v178 offset:34816
	ds_read_b128 v[216:219], v178 offset:35840
	ds_read_b128 v[220:223], v178 offset:36864
	ds_read_b128 v[228:231], v178 offset:37888
	ds_read_b128 v[232:235], v178 offset:38912
	ds_read_b128 v[236:239], v178 offset:39936
	global_load_lds_dwordx4 v[246:247], off
	v_lshl_add_u64 v[246:247], s[30:31], 0, v[140:141]
	s_mov_b32 m0, s73
	s_nop 0
	global_load_lds_dwordx4 v[246:247], off
	s_waitcnt vmcnt(8)
	s_waitcnt lgkmcnt(0)
	s_barrier
	s_setprio 1
	v_mfma_f32_16x16x32_bf16 v[128:131], v[132:135], v[188:191], v[128:131]
	v_mfma_f32_16x16x32_bf16 v[124:127], v[160:163], v[188:191], v[124:127]
	v_mfma_f32_16x16x32_bf16 v[112:115], v[132:135], v[212:215], v[112:115]
	v_mfma_f32_16x16x32_bf16 v[108:111], v[160:163], v[212:215], v[108:111]
	v_mfma_f32_16x16x32_bf16 v[94:97], v[132:135], v[220:223], v[94:97]
	v_mfma_f32_16x16x32_bf16 v[90:93], v[160:163], v[220:223], v[90:93]
	v_mfma_f32_16x16x32_bf16 v[78:81], v[132:135], v[232:235], v[78:81]
	v_mfma_f32_16x16x32_bf16 v[74:77], v[160:163], v[232:235], v[74:77]
	v_mfma_f32_16x16x32_bf16 v[128:131], v[156:159], v[208:211], v[128:131]
	v_mfma_f32_16x16x32_bf16 v[124:127], v[164:167], v[208:211], v[124:127]
	v_mfma_f32_16x16x32_bf16 v[112:115], v[156:159], v[216:219], v[112:115]
	v_mfma_f32_16x16x32_bf16 v[108:111], v[164:167], v[216:219], v[108:111]
	v_mfma_f32_16x16x32_bf16 v[94:97], v[156:159], v[228:231], v[94:97]
	v_mfma_f32_16x16x32_bf16 v[90:93], v[164:167], v[228:231], v[90:93]
	v_mfma_f32_16x16x32_bf16 v[78:81], v[156:159], v[236:239], v[78:81]
	v_mfma_f32_16x16x32_bf16 v[74:77], v[164:167], v[236:239], v[74:77]
	v_mfma_f32_16x16x32_bf16 v[120:123], v[168:171], v[188:191], v[120:123]
	v_mfma_f32_16x16x32_bf16 v[116:119], v[180:183], v[188:191], v[116:119]
	v_mfma_f32_16x16x32_bf16 v[104:107], v[168:171], v[212:215], v[104:107]
	v_mfma_f32_16x16x32_bf16 v[100:103], v[180:183], v[212:215], v[100:103]
	v_mfma_f32_16x16x32_bf16 v[86:89], v[168:171], v[220:223], v[86:89]
	v_mfma_f32_16x16x32_bf16 v[82:85], v[180:183], v[220:223], v[82:85]
	v_mfma_f32_16x16x32_bf16 v[70:73], v[168:171], v[232:235], v[70:73]
	v_mfma_f32_16x16x32_bf16 v[66:69], v[180:183], v[232:235], v[66:69]
	v_mfma_f32_16x16x32_bf16 v[120:123], v[172:175], v[208:211], v[120:123]
	v_mfma_f32_16x16x32_bf16 v[116:119], v[184:187], v[208:211], v[116:119]
	v_mfma_f32_16x16x32_bf16 v[104:107], v[172:175], v[216:219], v[104:107]
	v_mfma_f32_16x16x32_bf16 v[100:103], v[184:187], v[216:219], v[100:103]
	v_mfma_f32_16x16x32_bf16 v[86:89], v[172:175], v[228:231], v[86:89]
	v_mfma_f32_16x16x32_bf16 v[82:85], v[184:187], v[228:231], v[82:85]
	v_mfma_f32_16x16x32_bf16 v[70:73], v[172:175], v[236:239], v[70:73]
	v_mfma_f32_16x16x32_bf16 v[66:69], v[184:187], v[236:239], v[66:69]
	s_setprio 0
	s_barrier
; #define PG8_STAGE(bufoff, gbase, voff) do { _Pragma("unroll") for (int _i = 0; _i < 2; ++_i) \
;         __builtin_amdgcn_global_load_lds((const unsigned*)((const char*)(gbase) + (voff)[_i]), (PG8_LAS unsigned*)(lds + (bufoff) + ldsw + _i * 8192), 16, 0, 0); } while (0)
; #define PG8_LDA(dst, b, h) do { _Pragma("unroll") for (int m = 0; m < 4; ++m) _Pragma("unroll") for (int k = 0; k < 2; ++k) dst[m][k] = *(const PG8_LAS bf16x8*)(lds + PG8_SA(b, h) + aoff + m * 2048 + k * 1024); } while (0)
; #define PG8_MMA(ai, bj, At, Bt) do { __builtin_amdgcn_s_setprio(1); _Pragma("unroll") for (int m = 0; m < 4; ++m) _Pragma("unroll") for (int n = 0; n < 2; ++n) _Pragma("unroll") for (int k = 0; k < 2; ++k) \
;         acc[ai][bj][m][n] = __builtin_amdgcn_mfma_f32_16x16x32_bf16(Bt[n][k], At[m][k], acc[ai][bj][m][n], 0, 0, 0); __builtin_amdgcn_s_setprio(0); } while (0)
; #define PG8_WAIT_V(n) asm volatile("s_waitcnt vmcnt(" #n ")" ::: "memory")
; #define PG8_WAIT_L(n) asm volatile("s_waitcnt lgkmcnt(" #n ")" ::: "memory")
; #define PG8_BAR __builtin_amdgcn_s_barrier()
; #define PG8_SCHED __builtin_amdgcn_sched_barrier(0)
; template <class Epi, class Sched, bool ALIGN_EPI = false, bool SP2 = false>
; __device__ __forceinline__ void gemm_phase(PG8_LAS unsigned char* lds, const Gemm g, const Sched& S, const Epi& E) {
;     ...
;             PG8_LDA(At, 1, 1); PG8_STAGE(PG8_SB(1, 0), b3, voffB); PG8_STAGE(PG8_SB(1, 1), b3 + hstep, voffB); PG8_STAGE(PG8_SA(1, 0), a3, voffA);
;             PG8_WAIT_V(8); PG8_WAIT_L(0); PG8_BAR; PG8_MMA(1, 0, At, B0); PG8_MMA(1, 1, At, B1); PG8_BAR; PG8_SCHED;
	s_add_i32 s17, s17, s69
	v_lshl_add_u64 v[176:177], v[176:177], 0, s[24:25]
	s_mov_b32 m0, s17
	ds_read_b128 v[188:191], v178 offset:49152
	ds_read_b128 v[208:211], v178 offset:50176
	ds_read_b128 v[212:215], v178 offset:51200
	ds_read_b128 v[216:219], v178 offset:52224
	ds_read_b128 v[220:223], v178 offset:53248
	ds_read_b128 v[228:231], v178 offset:54272
	ds_read_b128 v[232:235], v178 offset:55296
	ds_read_b128 v[236:239], v178 offset:56320
	global_load_lds_dwordx4 v[176:177], off
	v_lshl_add_u64 v[176:177], v[192:193], 0, s[24:25]
	s_add_i32 m0, s17, 0x2000
	s_add_i32 s17, s28, s69
	global_load_lds_dwordx4 v[176:177], off
	v_lshl_add_u64 v[176:177], v[224:225], 0, s[24:25]
	s_mov_b32 m0, s17
	s_nop 0
	global_load_lds_dwordx4 v[176:177], off
	v_lshl_add_u64 v[176:177], v[240:241], 0, s[24:25]
	s_add_i32 m0, s17, 0x2000
	s_nop 0
	global_load_lds_dwordx4 v[176:177], off
	v_lshl_add_u64 v[176:177], v[242:243], 0, s[24:25]
	s_mov_b32 m0, s86
	s_nop 0
	global_load_lds_dwordx4 v[176:177], off
	v_lshl_add_u64 v[176:177], v[244:245], 0, s[24:25]
	s_mov_b32 m0, s87
	s_nop 0
	global_load_lds_dwordx4 v[176:177], off
	s_waitcnt vmcnt(8)
	s_waitcnt lgkmcnt(0)
	s_barrier
	s_setprio 1
	v_mfma_f32_16x16x32_bf16 v[62:65], v[132:135], v[188:191], v[62:65]
	v_mfma_f32_16x16x32_bf16 v[58:61], v[160:163], v[188:191], v[58:61]
	v_mfma_f32_16x16x32_bf16 v[46:49], v[132:135], v[212:215], v[46:49]
	v_mfma_f32_16x16x32_bf16 v[42:45], v[160:163], v[212:215], v[42:45]
	v_mfma_f32_16x16x32_bf16 v[30:33], v[132:135], v[220:223], v[30:33]
	v_mfma_f32_16x16x32_bf16 v[26:29], v[160:163], v[220:223], v[26:29]
	v_mfma_f32_16x16x32_bf16 v[14:17], v[132:135], v[232:235], v[14:17]
	v_mfma_f32_16x16x32_bf16 v[10:13], v[160:163], v[232:235], v[10:13]
	v_mfma_f32_16x16x32_bf16 v[62:65], v[156:159], v[208:211], v[62:65]
	v_mfma_f32_16x16x32_bf16 v[58:61], v[164:167], v[208:211], v[58:61]
	v_mfma_f32_16x16x32_bf16 v[46:49], v[156:159], v[216:219], v[46:49]
	v_mfma_f32_16x16x32_bf16 v[42:45], v[164:167], v[216:219], v[42:45]
	v_mfma_f32_16x16x32_bf16 v[30:33], v[156:159], v[228:231], v[30:33]
	v_mfma_f32_16x16x32_bf16 v[26:29], v[164:167], v[228:231], v[26:29]
	v_mfma_f32_16x16x32_bf16 v[14:17], v[156:159], v[236:239], v[14:17]
	v_mfma_f32_16x16x32_bf16 v[10:13], v[164:167], v[236:239], v[10:13]
	v_mfma_f32_16x16x32_bf16 v[54:57], v[168:171], v[188:191], v[54:57]
	v_mfma_f32_16x16x32_bf16 v[50:53], v[180:183], v[188:191], v[50:53]
	v_mfma_f32_16x16x32_bf16 v[38:41], v[168:171], v[212:215], v[38:41]
	v_mfma_f32_16x16x32_bf16 v[34:37], v[180:183], v[212:215], v[34:37]
	v_mfma_f32_16x16x32_bf16 v[22:25], v[168:171], v[220:223], v[22:25]
	v_mfma_f32_16x16x32_bf16 v[18:21], v[180:183], v[220:223], v[18:21]
	v_mfma_f32_16x16x32_bf16 v[6:9], v[168:171], v[232:235], v[6:9]
	v_mfma_f32_16x16x32_bf16 v[2:5], v[180:183], v[232:235], v[2:5]
	v_mfma_f32_16x16x32_bf16 v[54:57], v[172:175], v[208:211], v[54:57]
	v_mfma_f32_16x16x32_bf16 v[50:53], v[184:187], v[208:211], v[50:53]
	v_mfma_f32_16x16x32_bf16 v[38:41], v[172:175], v[216:219], v[38:41]
	v_mfma_f32_16x16x32_bf16 v[34:37], v[184:187], v[216:219], v[34:37]
	v_mfma_f32_16x16x32_bf16 v[22:25], v[172:175], v[228:231], v[22:25]
	v_mfma_f32_16x16x32_bf16 v[18:21], v[184:187], v[228:231], v[18:21]
	v_mfma_f32_16x16x32_bf16 v[6:9], v[172:175], v[236:239], v[6:9]
	v_mfma_f32_16x16x32_bf16 v[2:5], v[184:187], v[236:239], v[2:5]
	s_setprio 0
	s_barrier
	s_add_u32 s34, s34, 0x100
	s_addc_u32 s35, s35, 0
	s_add_u32 s4, s4, 0x100
	s_addc_u32 s16, s16, 0
	s_cmp_ge_i32 s22, s84
	s_mov_b32 s17, s22
	s_cbranch_scc0 .LBB0_967

; #define PG8_STAGE(bufoff, gbase, voff) do { _Pragma("unroll") for (int _i = 0; _i < 2; ++_i) \
;         __builtin_amdgcn_global_load_lds((const unsigned*)((const char*)(gbase) + (voff)[_i]), (PG8_LAS unsigned*)(lds + (bufoff) + ldsw + _i * 8192), 16, 0, 0); } while (0)
; #define PG8_LDA(dst, b, h) do { _Pragma("unroll") for (int m = 0; m < 4; ++m) _Pragma("unroll") for (int k = 0; k < 2; ++k) dst[m][k] = *(const PG8_LAS bf16x8*)(lds + PG8_SA(b, h) + aoff + m * 2048 + k * 1024); } while (0)
; #define PG8_LDB(dst, b, h) do { _Pragma("unroll") for (int n = 0; n < 2; ++n) _Pragma("unroll") for (int k = 0; k < 2; ++k) dst[n][k] = *(const PG8_LAS bf16x8*)(lds + PG8_SB(b, h) + boff + n * 2048 + k * 1024); } while (0)
; #define PG8_MMA(ai, bj, At, Bt) do { __builtin_amdgcn_s_setprio(1); _Pragma("unroll") for (int m = 0; m < 4; ++m) _Pragma("unroll") for (int n = 0; n < 2; ++n) _Pragma("unroll") for (int k = 0; k < 2; ++k) \
;         acc[ai][bj][m][n] = __builtin_amdgcn_mfma_f32_16x16x32_bf16(Bt[n][k], At[m][k], acc[ai][bj][m][n], 0, 0, 0); __builtin_amdgcn_s_setprio(0); } while (0)
; #define PG8_WAIT_V(n) asm volatile("s_waitcnt vmcnt(" #n ")" ::: "memory")
; #define PG8_WAIT_L(n) asm volatile("s_waitcnt lgkmcnt(" #n ")" ::: "memory")
; template <class Epi, class Sched, bool ALIGN_EPI = false, bool SP2 = false>
; __device__ __forceinline__ void gemm_phase(PG8_LAS unsigned char* lds, const Gemm g, const Sched& S, const Epi& E) {
;     ...
;             const bool last = (t == nt - 2);
;             const char* a1 = cA + (size_t)(t + 1) * kstep;
;             const char* a2 = last ? nA : cA + (size_t)(t + 2) * kstep; const char* b2 = last ? nB : cB + (size_t)(t + 2) * kstep;
;             const char* a3 = a2 + kstep; const char* b3 = b2 + kstep;
;             if (last && has_next) S.a_ready(nxt);
;             if constexpr (SP2) {
;             PG8_LDB(B0, 0, 0); PG8_LDB(B1, 0, 1); PG8_SCHED; PG8_LDA(At, 0, 0); PG8_STAGE(PG8_SA(1, 1), a1 + hstep, voffA);
;             PG8_WAIT_V(8); PG8_WAIT_L(0); PG8_BAR; PG8_MMA(0, 0, At, B0); PG8_MMA(0, 1, At, B1); PG8_BAR; PG8_SCHED;
;             PG8_LDA(At, 0, 1); PG8_STAGE(PG8_SB(0, 0), b2, voffB); PG8_STAGE(PG8_SB(0, 1), b2 + hstep, voffB); PG8_STAGE(PG8_SA(0, 0), a2, voffA);
;             PG8_WAIT_V(8); PG8_WAIT_L(0); PG8_BAR; PG8_MMA(1, 0, At, B0); PG8_MMA(1, 1, At, B1); PG8_BAR; PG8_SCHED;
.LBB0_1052:
	s_add_i32 s22, s17, 2
	s_add_u32 s28, s2, 0x80
	s_addc_u32 s30, s3, 0
	s_add_i32 s33, 0, 0x10000
	s_cmp_eq_u32 s78, s17
	s_cselect_b32 s35, s55, s30
	s_cselect_b32 s34, s54, s28
	v_add_u32_e32 v98, s33, v166
	s_cselect_b32 s31, s57, s16
	s_cselect_b32 s30, s56, s4
	s_add_i32 s17, 0, 0x14000
	ds_read_b128 v[132:135], v98
	ds_read_b128 v[136:139], v98 offset:1024
	ds_read_b128 v[140:143], v98 offset:2048
	ds_read_b128 v[156:159], v98 offset:3072
	v_add_u32_e32 v98, s17, v166
	ds_read_b128 v[160:163], v98
	ds_read_b128 v[170:173], v98 offset:1024
	ds_read_b128 v[174:177], v98 offset:2048
	ds_read_b128 v[178:181], v98 offset:3072
	v_lshl_add_u64 v[164:165], s[2:3], 0, v[152:153]
	s_add_i32 m0, s72, 0xc000
	ds_read_b128 v[182:185], v168
	ds_read_b128 v[186:189], v168 offset:1024
	ds_read_b128 v[190:193], v168 offset:2048
	ds_read_b128 v[208:211], v168 offset:3072
	ds_read_b128 v[212:215], v168 offset:4096
	ds_read_b128 v[216:219], v168 offset:5120
	ds_read_b128 v[220:223], v168 offset:6144
	ds_read_b128 v[228:231], v168 offset:7168
	global_load_lds_dwordx4 v[164:165], off
	v_lshl_add_u64 v[164:165], s[2:3], 0, v[154:155]
	s_add_i32 m0, s72, 0xe000
	s_nop 0
	global_load_lds_dwordx4 v[164:165], off
	s_waitcnt vmcnt(8)
	s_waitcnt lgkmcnt(0)
	s_barrier
	s_setprio 1
	v_mfma_f32_16x16x32_bf16 v[128:131], v[132:135], v[182:185], v[128:131]
	v_mfma_f32_16x16x32_bf16 v[124:127], v[140:143], v[182:185], v[124:127]
	v_mfma_f32_16x16x32_bf16 v[120:123], v[132:135], v[190:193], v[120:123]
	v_mfma_f32_16x16x32_bf16 v[116:119], v[140:143], v[190:193], v[116:119]
	v_mfma_f32_16x16x32_bf16 v[112:115], v[132:135], v[212:215], v[112:115]
	v_mfma_f32_16x16x32_bf16 v[108:111], v[140:143], v[212:215], v[108:111]
	v_mfma_f32_16x16x32_bf16 v[104:107], v[132:135], v[220:223], v[104:107]
	v_mfma_f32_16x16x32_bf16 v[100:103], v[140:143], v[220:223], v[100:103]
	v_mfma_f32_16x16x32_bf16 v[128:131], v[136:139], v[186:189], v[128:131]
	v_mfma_f32_16x16x32_bf16 v[124:127], v[156:159], v[186:189], v[124:127]
	v_mfma_f32_16x16x32_bf16 v[120:123], v[136:139], v[208:211], v[120:123]
	v_mfma_f32_16x16x32_bf16 v[116:119], v[156:159], v[208:211], v[116:119]
	v_mfma_f32_16x16x32_bf16 v[112:115], v[136:139], v[216:219], v[112:115]
	v_mfma_f32_16x16x32_bf16 v[108:111], v[156:159], v[216:219], v[108:111]
	v_mfma_f32_16x16x32_bf16 v[104:107], v[136:139], v[228:231], v[104:107]
	v_mfma_f32_16x16x32_bf16 v[100:103], v[156:159], v[228:231], v[100:103]
	v_mfma_f32_16x16x32_bf16 v[62:65], v[160:163], v[182:185], v[62:65]
	v_mfma_f32_16x16x32_bf16 v[58:61], v[174:177], v[182:185], v[58:61]
	v_mfma_f32_16x16x32_bf16 v[54:57], v[160:163], v[190:193], v[54:57]
	v_mfma_f32_16x16x32_bf16 v[50:53], v[174:177], v[190:193], v[50:53]
	v_mfma_f32_16x16x32_bf16 v[46:49], v[160:163], v[212:215], v[46:49]
	v_mfma_f32_16x16x32_bf16 v[42:45], v[174:177], v[212:215], v[42:45]
	v_mfma_f32_16x16x32_bf16 v[38:41], v[160:163], v[220:223], v[38:41]
	v_mfma_f32_16x16x32_bf16 v[34:37], v[174:177], v[220:223], v[34:37]
	v_mfma_f32_16x16x32_bf16 v[62:65], v[170:173], v[186:189], v[62:65]
	v_mfma_f32_16x16x32_bf16 v[58:61], v[178:181], v[186:189], v[58:61]
	v_mfma_f32_16x16x32_bf16 v[54:57], v[170:173], v[208:211], v[54:57]
	v_mfma_f32_16x16x32_bf16 v[50:53], v[178:181], v[208:211], v[50:53]
	v_mfma_f32_16x16x32_bf16 v[46:49], v[170:173], v[216:219], v[46:49]
	v_mfma_f32_16x16x32_bf16 v[42:45], v[178:181], v[216:219], v[42:45]
	v_mfma_f32_16x16x32_bf16 v[38:41], v[170:173], v[228:231], v[38:41]
	v_mfma_f32_16x16x32_bf16 v[34:37], v[178:181], v[228:231], v[34:37]
	s_setprio 0
	s_barrier
	s_add_i32 s28, s33, s67
	v_lshl_add_u64 v[164:165], s[30:31], 0, v[146:147]
	s_mov_b32 m0, s28
	ds_read_b128 v[182:185], v168 offset:16384
	ds_read_b128 v[186:189], v168 offset:17408
	ds_read_b128 v[190:193], v168 offset:18432
	ds_read_b128 v[208:211], v168 offset:19456
	ds_read_b128 v[212:215], v168 offset:20480
	ds_read_b128 v[216:219], v168 offset:21504
	ds_read_b128 v[220:223], v168 offset:22528
	ds_read_b128 v[228:231], v168 offset:23552
	global_load_lds_dwordx4 v[164:165], off
	s_add_i32 m0, s28, 0x2000
	v_lshl_add_u64 v[224:225], s[30:31], 0, v[150:151]
	s_add_u32 s30, s30, s14
	s_addc_u32 s31, s31, s15
	s_add_i32 s17, s17, s67
	global_load_lds_dwordx4 v[224:225], off
	v_lshl_add_u64 v[232:233], s[30:31], 0, v[146:147]
	s_mov_b32 m0, s17
	v_lshl_add_u64 v[234:235], s[30:31], 0, v[150:151]
	global_load_lds_dwordx4 v[232:233], off
	s_add_i32 m0, s17, 0x2000
	v_lshl_add_u64 v[236:237], s[34:35], 0, v[144:145]
	global_load_lds_dwordx4 v[234:235], off
	s_mov_b32 m0, s72
	v_lshl_add_u64 v[238:239], s[34:35], 0, v[148:149]
	global_load_lds_dwordx4 v[236:237], off
	s_mov_b32 m0, s73
	s_nop 0
	global_load_lds_dwordx4 v[238:239], off
	s_waitcnt vmcnt(8)
	s_waitcnt lgkmcnt(0)
	s_barrier
; #define PG8_STAGE(bufoff, gbase, voff) do { _Pragma("unroll") for (int _i = 0; _i < 2; ++_i) \
;         __builtin_amdgcn_global_load_lds((const unsigned*)((const char*)(gbase) + (voff)[_i]), (PG8_LAS unsigned*)(lds + (bufoff) + ldsw + _i * 8192), 16, 0, 0); } while (0)
; #define PG8_LDA(dst, b, h) do { _Pragma("unroll") for (int m = 0; m < 4; ++m) _Pragma("unroll") for (int k = 0; k < 2; ++k) dst[m][k] = *(const PG8_LAS bf16x8*)(lds + PG8_SA(b, h) + aoff + m * 2048 + k * 1024); } while (0)
; #define PG8_LDB(dst, b, h) do { _Pragma("unroll") for (int n = 0; n < 2; ++n) _Pragma("unroll") for (int k = 0; k < 2; ++k) dst[n][k] = *(const PG8_LAS bf16x8*)(lds + PG8_SB(b, h) + boff + n * 2048 + k * 1024); } while (0)
; #define PG8_MMA(ai, bj, At, Bt) do { __builtin_amdgcn_s_setprio(1); _Pragma("unroll") for (int m = 0; m < 4; ++m) _Pragma("unroll") for (int n = 0; n < 2; ++n) _Pragma("unroll") for (int k = 0; k < 2; ++k) \
;         acc[ai][bj][m][n] = __builtin_amdgcn_mfma_f32_16x16x32_bf16(Bt[n][k], At[m][k], acc[ai][bj][m][n], 0, 0, 0); __builtin_amdgcn_s_setprio(0); } while (0)
; #define PG8_WAIT_V(n) asm volatile("s_waitcnt vmcnt(" #n ")" ::: "memory")
; #define PG8_WAIT_L(n) asm volatile("s_waitcnt lgkmcnt(" #n ")" ::: "memory")
; #define PG8_BAR __builtin_amdgcn_s_barrier()
; #define PG8_SCHED __builtin_amdgcn_sched_barrier(0)
; template <class Epi, class Sched, bool ALIGN_EPI = false, bool SP2 = false>
; __device__ __forceinline__ void gemm_phase(PG8_LAS unsigned char* lds, const Gemm g, const Sched& S, const Epi& E) {
;     ...
;             PG8_WAIT_V(8); PG8_WAIT_L(0); PG8_BAR; PG8_MMA(1, 0, At, B0); PG8_MMA(1, 1, At, B1); PG8_BAR; PG8_SCHED;
;             PG8_LDB(B0, 1, 0); PG8_LDB(B1, 1, 1); PG8_SCHED; PG8_LDA(At, 1, 0); PG8_STAGE(PG8_SA(0, 1), a2 + hstep, voffA);
;             PG8_WAIT_V(8); PG8_WAIT_L(0); PG8_BAR; PG8_MMA(0, 0, At, B0); PG8_MMA(0, 1, At, B1); PG8_BAR; PG8_SCHED;
	s_setprio 1
	v_mfma_f32_16x16x32_bf16 v[94:97], v[132:135], v[182:185], v[94:97]
	v_mfma_f32_16x16x32_bf16 v[90:93], v[140:143], v[182:185], v[90:93]
	v_mfma_f32_16x16x32_bf16 v[86:89], v[132:135], v[190:193], v[86:89]
	v_mfma_f32_16x16x32_bf16 v[82:85], v[140:143], v[190:193], v[82:85]
	v_mfma_f32_16x16x32_bf16 v[78:81], v[132:135], v[212:215], v[78:81]
	v_mfma_f32_16x16x32_bf16 v[74:77], v[140:143], v[212:215], v[74:77]
	v_mfma_f32_16x16x32_bf16 v[70:73], v[132:135], v[220:223], v[70:73]
	v_mfma_f32_16x16x32_bf16 v[66:69], v[140:143], v[220:223], v[66:69]
	v_mfma_f32_16x16x32_bf16 v[94:97], v[136:139], v[186:189], v[94:97]
	v_mfma_f32_16x16x32_bf16 v[90:93], v[156:159], v[186:189], v[90:93]
	v_mfma_f32_16x16x32_bf16 v[86:89], v[136:139], v[208:211], v[86:89]
	v_mfma_f32_16x16x32_bf16 v[82:85], v[156:159], v[208:211], v[82:85]
	v_mfma_f32_16x16x32_bf16 v[78:81], v[136:139], v[216:219], v[78:81]
	v_mfma_f32_16x16x32_bf16 v[74:77], v[156:159], v[216:219], v[74:77]
	v_mfma_f32_16x16x32_bf16 v[70:73], v[136:139], v[228:231], v[70:73]
	v_mfma_f32_16x16x32_bf16 v[66:69], v[156:159], v[228:231], v[66:69]
	v_mfma_f32_16x16x32_bf16 v[30:33], v[160:163], v[182:185], v[30:33]
	v_mfma_f32_16x16x32_bf16 v[26:29], v[174:177], v[182:185], v[26:29]
	v_mfma_f32_16x16x32_bf16 v[22:25], v[160:163], v[190:193], v[22:25]
	v_mfma_f32_16x16x32_bf16 v[18:21], v[174:177], v[190:193], v[18:21]
	v_mfma_f32_16x16x32_bf16 v[14:17], v[160:163], v[212:215], v[14:17]
	v_mfma_f32_16x16x32_bf16 v[10:13], v[174:177], v[212:215], v[10:13]
	v_mfma_f32_16x16x32_bf16 v[6:9], v[160:163], v[220:223], v[6:9]
	v_mfma_f32_16x16x32_bf16 v[2:5], v[174:177], v[220:223], v[2:5]
	v_mfma_f32_16x16x32_bf16 v[30:33], v[170:173], v[186:189], v[30:33]
	v_mfma_f32_16x16x32_bf16 v[26:29], v[178:181], v[186:189], v[26:29]
	v_mfma_f32_16x16x32_bf16 v[22:25], v[170:173], v[208:211], v[22:25]
	v_mfma_f32_16x16x32_bf16 v[18:21], v[178:181], v[208:211], v[18:21]
	v_mfma_f32_16x16x32_bf16 v[14:17], v[170:173], v[216:219], v[14:17]
	v_mfma_f32_16x16x32_bf16 v[10:13], v[178:181], v[216:219], v[10:13]
	v_mfma_f32_16x16x32_bf16 v[6:9], v[170:173], v[228:231], v[6:9]
	v_mfma_f32_16x16x32_bf16 v[2:5], v[178:181], v[228:231], v[2:5]
	s_setprio 0
	s_barrier
	s_add_i32 s17, 0, 0x18000
	v_add_u32_e32 v98, s17, v166
	s_add_i32 s28, 0, 0x1c000
	ds_read_b128 v[132:135], v98
	ds_read_b128 v[136:139], v98 offset:1024
	ds_read_b128 v[140:143], v98 offset:2048
	ds_read_b128 v[156:159], v98 offset:3072
	v_add_u32_e32 v98, s28, v166
	ds_read_b128 v[160:163], v98
	ds_read_b128 v[170:173], v98 offset:1024
	ds_read_b128 v[174:177], v98 offset:2048
	ds_read_b128 v[178:181], v98 offset:3072
	s_add_u32 s30, s34, s14
	s_addc_u32 s31, s35, s15
	s_mov_b32 m0, s74
	v_lshl_add_u64 v[240:241], s[30:31], 0, v[144:145]
	ds_read_b128 v[182:185], v168 offset:32768
	ds_read_b128 v[186:189], v168 offset:33792
	ds_read_b128 v[190:193], v168 offset:34816
	ds_read_b128 v[208:211], v168 offset:35840
	ds_read_b128 v[212:215], v168 offset:36864
	ds_read_b128 v[216:219], v168 offset:37888
	ds_read_b128 v[220:223], v168 offset:38912
	ds_read_b128 v[228:231], v168 offset:39936
	global_load_lds_dwordx4 v[240:241], off
	v_lshl_add_u64 v[240:241], s[30:31], 0, v[148:149]
	s_mov_b32 m0, s75
	s_nop 0
	global_load_lds_dwordx4 v[240:241], off
	s_waitcnt vmcnt(8)
	s_waitcnt lgkmcnt(0)
	s_barrier
	s_setprio 1
	v_mfma_f32_16x16x32_bf16 v[128:131], v[132:135], v[182:185], v[128:131]
	v_mfma_f32_16x16x32_bf16 v[124:127], v[140:143], v[182:185], v[124:127]
	v_mfma_f32_16x16x32_bf16 v[120:123], v[132:135], v[190:193], v[120:123]
	v_mfma_f32_16x16x32_bf16 v[116:119], v[140:143], v[190:193], v[116:119]
	v_mfma_f32_16x16x32_bf16 v[112:115], v[132:135], v[212:215], v[112:115]
	v_mfma_f32_16x16x32_bf16 v[108:111], v[140:143], v[212:215], v[108:111]
	v_mfma_f32_16x16x32_bf16 v[104:107], v[132:135], v[220:223], v[104:107]
	v_mfma_f32_16x16x32_bf16 v[100:103], v[140:143], v[220:223], v[100:103]
	v_mfma_f32_16x16x32_bf16 v[128:131], v[136:139], v[186:189], v[128:131]
	v_mfma_f32_16x16x32_bf16 v[124:127], v[156:159], v[186:189], v[124:127]
	v_mfma_f32_16x16x32_bf16 v[120:123], v[136:139], v[208:211], v[120:123]
	v_mfma_f32_16x16x32_bf16 v[116:119], v[156:159], v[208:211], v[116:119]
	v_mfma_f32_16x16x32_bf16 v[112:115], v[136:139], v[216:219], v[112:115]
	v_mfma_f32_16x16x32_bf16 v[108:111], v[156:159], v[216:219], v[108:111]
	v_mfma_f32_16x16x32_bf16 v[104:107], v[136:139], v[228:231], v[104:107]
	v_mfma_f32_16x16x32_bf16 v[100:103], v[156:159], v[228:231], v[100:103]
	v_mfma_f32_16x16x32_bf16 v[62:65], v[160:163], v[182:185], v[62:65]
	v_mfma_f32_16x16x32_bf16 v[58:61], v[174:177], v[182:185], v[58:61]
	v_mfma_f32_16x16x32_bf16 v[54:57], v[160:163], v[190:193], v[54:57]
	v_mfma_f32_16x16x32_bf16 v[50:53], v[174:177], v[190:193], v[50:53]
	v_mfma_f32_16x16x32_bf16 v[46:49], v[160:163], v[212:215], v[46:49]
	v_mfma_f32_16x16x32_bf16 v[42:45], v[174:177], v[212:215], v[42:45]
	v_mfma_f32_16x16x32_bf16 v[38:41], v[160:163], v[220:223], v[38:41]
	v_mfma_f32_16x16x32_bf16 v[34:37], v[174:177], v[220:223], v[34:37]
	v_mfma_f32_16x16x32_bf16 v[62:65], v[170:173], v[186:189], v[62:65]
	v_mfma_f32_16x16x32_bf16 v[58:61], v[178:181], v[186:189], v[58:61]
	v_mfma_f32_16x16x32_bf16 v[54:57], v[170:173], v[208:211], v[54:57]
	v_mfma_f32_16x16x32_bf16 v[50:53], v[178:181], v[208:211], v[50:53]
	v_mfma_f32_16x16x32_bf16 v[46:49], v[170:173], v[216:219], v[46:49]
	v_mfma_f32_16x16x32_bf16 v[42:45], v[178:181], v[216:219], v[42:45]
	v_mfma_f32_16x16x32_bf16 v[38:41], v[170:173], v[228:231], v[38:41]
	v_mfma_f32_16x16x32_bf16 v[34:37], v[178:181], v[228:231], v[34:37]
	s_setprio 0
	s_barrier
; #define PG8_STAGE(bufoff, gbase, voff) do { _Pragma("unroll") for (int _i = 0; _i < 2; ++_i) \
;         __builtin_amdgcn_global_load_lds((const unsigned*)((const char*)(gbase) + (voff)[_i]), (PG8_LAS unsigned*)(lds + (bufoff) + ldsw + _i * 8192), 16, 0, 0); } while (0)
; #define PG8_LDA(dst, b, h) do { _Pragma("unroll") for (int m = 0; m < 4; ++m) _Pragma("unroll") for (int k = 0; k < 2; ++k) dst[m][k] = *(const PG8_LAS bf16x8*)(lds + PG8_SA(b, h) + aoff + m * 2048 + k * 1024); } while (0)
; #define PG8_MMA(ai, bj, At, Bt) do { __builtin_amdgcn_s_setprio(1); _Pragma("unroll") for (int m = 0; m < 4; ++m) _Pragma("unroll") for (int n = 0; n < 2; ++n) _Pragma("unroll") for (int k = 0; k < 2; ++k) \
;         acc[ai][bj][m][n] = __builtin_amdgcn_mfma_f32_16x16x32_bf16(Bt[n][k], At[m][k], acc[ai][bj][m][n], 0, 0, 0); __builtin_amdgcn_s_setprio(0); } while (0)
; #define PG8_WAIT_V(n) asm volatile("s_waitcnt vmcnt(" #n ")" ::: "memory")
; #define PG8_WAIT_L(n) asm volatile("s_waitcnt lgkmcnt(" #n ")" ::: "memory")
; #define PG8_BAR __builtin_amdgcn_s_barrier()
; #define PG8_SCHED __builtin_amdgcn_sched_barrier(0)
; template <class Epi, class Sched, bool ALIGN_EPI = false, bool SP2 = false>
; __device__ __forceinline__ void gemm_phase(PG8_LAS unsigned char* lds, const Gemm g, const Sched& S, const Epi& E) {
;     ...
;             PG8_LDA(At, 1, 1); PG8_STAGE(PG8_SB(1, 0), b3, voffB); PG8_STAGE(PG8_SB(1, 1), b3 + hstep, voffB); PG8_STAGE(PG8_SA(1, 0), a3, voffA);
;             PG8_WAIT_V(8); PG8_WAIT_L(0); PG8_BAR; PG8_MMA(1, 0, At, B0); PG8_MMA(1, 1, At, B1); PG8_BAR; PG8_SCHED;
	s_add_i32 s17, s17, s67
	v_lshl_add_u64 v[164:165], v[164:165], 0, s[24:25]
	s_mov_b32 m0, s17
	ds_read_b128 v[182:185], v168 offset:49152
	ds_read_b128 v[186:189], v168 offset:50176
	ds_read_b128 v[190:193], v168 offset:51200
	ds_read_b128 v[208:211], v168 offset:52224
	ds_read_b128 v[212:215], v168 offset:53248
	ds_read_b128 v[216:219], v168 offset:54272
	ds_read_b128 v[220:223], v168 offset:55296
	ds_read_b128 v[228:231], v168 offset:56320
	global_load_lds_dwordx4 v[164:165], off
	v_lshl_add_u64 v[164:165], v[224:225], 0, s[24:25]
	s_add_i32 m0, s17, 0x2000
	s_add_i32 s17, s28, s67
	global_load_lds_dwordx4 v[164:165], off
	v_lshl_add_u64 v[164:165], v[232:233], 0, s[24:25]
	s_mov_b32 m0, s17
	s_nop 0
	global_load_lds_dwordx4 v[164:165], off
	v_lshl_add_u64 v[164:165], v[234:235], 0, s[24:25]
	s_add_i32 m0, s17, 0x2000
	s_nop 0
	global_load_lds_dwordx4 v[164:165], off
	v_lshl_add_u64 v[164:165], v[236:237], 0, s[24:25]
	s_mov_b32 m0, s76
	s_nop 0
	global_load_lds_dwordx4 v[164:165], off
	v_lshl_add_u64 v[164:165], v[238:239], 0, s[24:25]
	s_mov_b32 m0, s77
	s_nop 0
	global_load_lds_dwordx4 v[164:165], off
	s_waitcnt vmcnt(8)
	s_waitcnt lgkmcnt(0)
	s_barrier
	s_setprio 1
	v_mfma_f32_16x16x32_bf16 v[94:97], v[132:135], v[182:185], v[94:97]
	v_mfma_f32_16x16x32_bf16 v[90:93], v[140:143], v[182:185], v[90:93]
	v_mfma_f32_16x16x32_bf16 v[86:89], v[132:135], v[190:193], v[86:89]
	v_mfma_f32_16x16x32_bf16 v[82:85], v[140:143], v[190:193], v[82:85]
	v_mfma_f32_16x16x32_bf16 v[78:81], v[132:135], v[212:215], v[78:81]
	v_mfma_f32_16x16x32_bf16 v[74:77], v[140:143], v[212:215], v[74:77]
	v_mfma_f32_16x16x32_bf16 v[70:73], v[132:135], v[220:223], v[70:73]
	v_mfma_f32_16x16x32_bf16 v[66:69], v[140:143], v[220:223], v[66:69]
	v_mfma_f32_16x16x32_bf16 v[94:97], v[136:139], v[186:189], v[94:97]
	v_mfma_f32_16x16x32_bf16 v[90:93], v[156:159], v[186:189], v[90:93]
	v_mfma_f32_16x16x32_bf16 v[86:89], v[136:139], v[208:211], v[86:89]
	v_mfma_f32_16x16x32_bf16 v[82:85], v[156:159], v[208:211], v[82:85]
	v_mfma_f32_16x16x32_bf16 v[78:81], v[136:139], v[216:219], v[78:81]
	v_mfma_f32_16x16x32_bf16 v[74:77], v[156:159], v[216:219], v[74:77]
	v_mfma_f32_16x16x32_bf16 v[70:73], v[136:139], v[228:231], v[70:73]
	v_mfma_f32_16x16x32_bf16 v[66:69], v[156:159], v[228:231], v[66:69]
	v_mfma_f32_16x16x32_bf16 v[30:33], v[160:163], v[182:185], v[30:33]
	v_mfma_f32_16x16x32_bf16 v[26:29], v[174:177], v[182:185], v[26:29]
	v_mfma_f32_16x16x32_bf16 v[22:25], v[160:163], v[190:193], v[22:25]
	v_mfma_f32_16x16x32_bf16 v[18:21], v[174:177], v[190:193], v[18:21]
	v_mfma_f32_16x16x32_bf16 v[14:17], v[160:163], v[212:215], v[14:17]
	v_mfma_f32_16x16x32_bf16 v[10:13], v[174:177], v[212:215], v[10:13]
	v_mfma_f32_16x16x32_bf16 v[6:9], v[160:163], v[220:223], v[6:9]
	v_mfma_f32_16x16x32_bf16 v[2:5], v[174:177], v[220:223], v[2:5]
	v_mfma_f32_16x16x32_bf16 v[30:33], v[170:173], v[186:189], v[30:33]
	v_mfma_f32_16x16x32_bf16 v[26:29], v[178:181], v[186:189], v[26:29]
	v_mfma_f32_16x16x32_bf16 v[22:25], v[170:173], v[208:211], v[22:25]
	v_mfma_f32_16x16x32_bf16 v[18:21], v[178:181], v[208:211], v[18:21]
	v_mfma_f32_16x16x32_bf16 v[14:17], v[170:173], v[216:219], v[14:17]
	v_mfma_f32_16x16x32_bf16 v[10:13], v[178:181], v[216:219], v[10:13]
	v_mfma_f32_16x16x32_bf16 v[6:9], v[170:173], v[228:231], v[6:9]
	v_mfma_f32_16x16x32_bf16 v[2:5], v[178:181], v[228:231], v[2:5]
	s_setprio 0
	s_barrier
	s_add_u32 s2, s2, 0x100
	s_addc_u32 s3, s3, 0
	s_add_u32 s4, s4, 0x100
	s_addc_u32 s16, s16, 0
	s_cmp_ge_i32 s22, s18
	s_mov_b32 s17, s22
	s_cbranch_scc0 .LBB0_1052

; #define PG8_STAGE(bufoff, gbase, voff) do { _Pragma("unroll") for (int _i = 0; _i < 2; ++_i) \
;         __builtin_amdgcn_global_load_lds((const unsigned*)((const char*)(gbase) + (voff)[_i]), (PG8_LAS unsigned*)(lds + (bufoff) + ldsw + _i * 8192), 16, 0, 0); } while (0)
; #define PG8_LDA(dst, b, h) do { _Pragma("unroll") for (int m = 0; m < 4; ++m) _Pragma("unroll") for (int k = 0; k < 2; ++k) dst[m][k] = *(const PG8_LAS bf16x8*)(lds + PG8_SA(b, h) + aoff + m * 2048 + k * 1024); } while (0)
; #define PG8_LDB(dst, b, h) do { _Pragma("unroll") for (int n = 0; n < 2; ++n) _Pragma("unroll") for (int k = 0; k < 2; ++k) dst[n][k] = *(const PG8_LAS bf16x8*)(lds + PG8_SB(b, h) + boff + n * 2048 + k * 1024); } while (0)
; #define PG8_MMA(ai, bj, At, Bt) do { __builtin_amdgcn_s_setprio(1); _Pragma("unroll") for (int m = 0; m < 4; ++m) _Pragma("unroll") for (int n = 0; n < 2; ++n) _Pragma("unroll") for (int k = 0; k < 2; ++k) \
;         acc[ai][bj][m][n] = __builtin_amdgcn_mfma_f32_16x16x32_bf16(Bt[n][k], At[m][k], acc[ai][bj][m][n], 0, 0, 0); __builtin_amdgcn_s_setprio(0); } while (0)
; #define PG8_WAIT_V(n) asm volatile("s_waitcnt vmcnt(" #n ")" ::: "memory")
; #define PG8_WAIT_L(n) asm volatile("s_waitcnt lgkmcnt(" #n ")" ::: "memory")
; template <class Epi, class Sched, bool ALIGN_EPI = false, bool SP2 = false>
; __device__ __forceinline__ void gemm_phase(PG8_LAS unsigned char* lds, const Gemm g, const Sched& S, const Epi& E) {
;     ...
;             const bool last = (t == nt - 2);
;             const char* a1 = cA + (size_t)(t + 1) * kstep;
;             const char* a2 = last ? nA : cA + (size_t)(t + 2) * kstep; const char* b2 = last ? nB : cB + (size_t)(t + 2) * kstep;
;             const char* a3 = a2 + kstep; const char* b3 = b2 + kstep;
;             if (last && has_next) S.a_ready(nxt);
;             if constexpr (SP2) {
;             PG8_LDB(B0, 0, 0); PG8_LDB(B1, 0, 1); PG8_SCHED; PG8_LDA(At, 0, 0); PG8_STAGE(PG8_SA(1, 1), a1 + hstep, voffA);
;             PG8_WAIT_V(8); PG8_WAIT_L(0); PG8_BAR; PG8_MMA(0, 0, At, B0); PG8_MMA(0, 1, At, B1); PG8_BAR; PG8_SCHED;
;             PG8_LDA(At, 0, 1); PG8_STAGE(PG8_SB(0, 0), b2, voffB); PG8_STAGE(PG8_SB(0, 1), b2 + hstep, voffB); PG8_STAGE(PG8_SA(0, 0), a2, voffA);
;             PG8_WAIT_V(8); PG8_WAIT_L(0); PG8_BAR; PG8_MMA(1, 0, At, B0); PG8_MMA(1, 1, At, B1); PG8_BAR; PG8_SCHED;
.LBB0_1127:
	s_add_i32 s22, s17, 2
	s_add_u32 s28, s2, 0x80
	s_addc_u32 s30, s3, 0
	s_add_i32 s33, 0, 0x10000
	s_cmp_eq_u32 s70, s17
	s_cselect_b32 s35, s57, s30
	s_cselect_b32 s34, s56, s28
	v_add_u32_e32 v98, s33, v154
	s_cselect_b32 s31, s59, s16
	s_cselect_b32 s30, s58, s4
	s_add_i32 s17, 0, 0x14000
	ds_read_b128 v[144:147], v98
	ds_read_b128 v[148:151], v98 offset:1024
	ds_read_b128 v[158:161], v98 offset:2048
	ds_read_b128 v[162:165], v98 offset:3072
	v_add_u32_e32 v98, s17, v154
	ds_read_b128 v[166:169], v98
	ds_read_b128 v[170:173], v98 offset:1024
	ds_read_b128 v[174:177], v98 offset:2048
	ds_read_b128 v[178:181], v98 offset:3072
	v_lshl_add_u64 v[152:153], s[2:3], 0, v[140:141]
	s_add_i32 m0, s63, 0xc000
	ds_read_b128 v[182:185], v156
	ds_read_b128 v[186:189], v156 offset:1024
	ds_read_b128 v[190:193], v156 offset:2048
	ds_read_b128 v[208:211], v156 offset:3072
	ds_read_b128 v[212:215], v156 offset:4096
	ds_read_b128 v[216:219], v156 offset:5120
	ds_read_b128 v[220:223], v156 offset:6144
	ds_read_b128 v[228:231], v156 offset:7168
	global_load_lds_dwordx4 v[152:153], off
	v_lshl_add_u64 v[152:153], s[2:3], 0, v[142:143]
	s_add_i32 m0, s63, 0xe000
	s_nop 0
	global_load_lds_dwordx4 v[152:153], off
	s_waitcnt vmcnt(8)
	s_waitcnt lgkmcnt(0)
	s_barrier
	s_setprio 1
	v_mfma_f32_16x16x32_bf16 v[124:127], v[144:147], v[182:185], v[124:127]
	v_mfma_f32_16x16x32_bf16 v[128:131], v[158:161], v[182:185], v[128:131]
	v_mfma_f32_16x16x32_bf16 v[112:115], v[144:147], v[190:193], v[112:115]
	v_mfma_f32_16x16x32_bf16 v[108:111], v[158:161], v[190:193], v[108:111]
	v_mfma_f32_16x16x32_bf16 v[94:97], v[144:147], v[212:215], v[94:97]
	v_mfma_f32_16x16x32_bf16 v[90:93], v[158:161], v[212:215], v[90:93]
	v_mfma_f32_16x16x32_bf16 v[78:81], v[144:147], v[220:223], v[78:81]
	v_mfma_f32_16x16x32_bf16 v[74:77], v[158:161], v[220:223], v[74:77]
	v_mfma_f32_16x16x32_bf16 v[124:127], v[148:151], v[186:189], v[124:127]
	v_mfma_f32_16x16x32_bf16 v[128:131], v[162:165], v[186:189], v[128:131]
	v_mfma_f32_16x16x32_bf16 v[112:115], v[148:151], v[208:211], v[112:115]
	v_mfma_f32_16x16x32_bf16 v[108:111], v[162:165], v[208:211], v[108:111]
	v_mfma_f32_16x16x32_bf16 v[94:97], v[148:151], v[216:219], v[94:97]
	v_mfma_f32_16x16x32_bf16 v[90:93], v[162:165], v[216:219], v[90:93]
	v_mfma_f32_16x16x32_bf16 v[78:81], v[148:151], v[228:231], v[78:81]
	v_mfma_f32_16x16x32_bf16 v[74:77], v[162:165], v[228:231], v[74:77]
	v_mfma_f32_16x16x32_bf16 v[120:123], v[166:169], v[182:185], v[120:123]
	v_mfma_f32_16x16x32_bf16 v[116:119], v[174:177], v[182:185], v[116:119]
	v_mfma_f32_16x16x32_bf16 v[104:107], v[166:169], v[190:193], v[104:107]
	v_mfma_f32_16x16x32_bf16 v[100:103], v[174:177], v[190:193], v[100:103]
	v_mfma_f32_16x16x32_bf16 v[86:89], v[166:169], v[212:215], v[86:89]
	v_mfma_f32_16x16x32_bf16 v[82:85], v[174:177], v[212:215], v[82:85]
	v_mfma_f32_16x16x32_bf16 v[70:73], v[166:169], v[220:223], v[70:73]
	v_mfma_f32_16x16x32_bf16 v[66:69], v[174:177], v[220:223], v[66:69]
	v_mfma_f32_16x16x32_bf16 v[120:123], v[170:173], v[186:189], v[120:123]
	v_mfma_f32_16x16x32_bf16 v[116:119], v[178:181], v[186:189], v[116:119]
	v_mfma_f32_16x16x32_bf16 v[104:107], v[170:173], v[208:211], v[104:107]
	v_mfma_f32_16x16x32_bf16 v[100:103], v[178:181], v[208:211], v[100:103]
	v_mfma_f32_16x16x32_bf16 v[86:89], v[170:173], v[216:219], v[86:89]
	v_mfma_f32_16x16x32_bf16 v[82:85], v[178:181], v[216:219], v[82:85]
	v_mfma_f32_16x16x32_bf16 v[70:73], v[170:173], v[228:231], v[70:73]
	v_mfma_f32_16x16x32_bf16 v[66:69], v[178:181], v[228:231], v[66:69]
	s_setprio 0
	s_barrier
	s_add_i32 s28, s33, s62
	v_lshl_add_u64 v[152:153], s[30:31], 0, v[134:135]
	s_mov_b32 m0, s28
	ds_read_b128 v[182:185], v156 offset:16384
	ds_read_b128 v[186:189], v156 offset:17408
	ds_read_b128 v[190:193], v156 offset:18432
	ds_read_b128 v[208:211], v156 offset:19456
	ds_read_b128 v[212:215], v156 offset:20480
	ds_read_b128 v[216:219], v156 offset:21504
	ds_read_b128 v[220:223], v156 offset:22528
	ds_read_b128 v[228:231], v156 offset:23552
	global_load_lds_dwordx4 v[152:153], off
	s_add_i32 m0, s28, 0x2000
	v_lshl_add_u64 v[224:225], s[30:31], 0, v[138:139]
	s_add_u32 s30, s30, s14
	s_addc_u32 s31, s31, s15
	s_add_i32 s17, s17, s62
	global_load_lds_dwordx4 v[224:225], off
	v_lshl_add_u64 v[232:233], s[30:31], 0, v[134:135]
	s_mov_b32 m0, s17
	v_lshl_add_u64 v[234:235], s[30:31], 0, v[138:139]
	global_load_lds_dwordx4 v[232:233], off
	s_add_i32 m0, s17, 0x2000
	v_lshl_add_u64 v[236:237], s[34:35], 0, v[132:133]
	global_load_lds_dwordx4 v[234:235], off
	s_mov_b32 m0, s63
	v_lshl_add_u64 v[238:239], s[34:35], 0, v[136:137]
	global_load_lds_dwordx4 v[236:237], off
	s_mov_b32 m0, s64
	s_nop 0
	global_load_lds_dwordx4 v[238:239], off
	s_waitcnt vmcnt(8)
	s_waitcnt lgkmcnt(0)
	s_barrier
; #define PG8_STAGE(bufoff, gbase, voff) do { _Pragma("unroll") for (int _i = 0; _i < 2; ++_i) \
;         __builtin_amdgcn_global_load_lds((const unsigned*)((const char*)(gbase) + (voff)[_i]), (PG8_LAS unsigned*)(lds + (bufoff) + ldsw + _i * 8192), 16, 0, 0); } while (0)
; #define PG8_LDA(dst, b, h) do { _Pragma("unroll") for (int m = 0; m < 4; ++m) _Pragma("unroll") for (int k = 0; k < 2; ++k) dst[m][k] = *(const PG8_LAS bf16x8*)(lds + PG8_SA(b, h) + aoff + m * 2048 + k * 1024); } while (0)
; #define PG8_LDB(dst, b, h) do { _Pragma("unroll") for (int n = 0; n < 2; ++n) _Pragma("unroll") for (int k = 0; k < 2; ++k) dst[n][k] = *(const PG8_LAS bf16x8*)(lds + PG8_SB(b, h) + boff + n * 2048 + k * 1024); } while (0)
; #define PG8_MMA(ai, bj, At, Bt) do { __builtin_amdgcn_s_setprio(1); _Pragma("unroll") for (int m = 0; m < 4; ++m) _Pragma("unroll") for (int n = 0; n < 2; ++n) _Pragma("unroll") for (int k = 0; k < 2; ++k) \
;         acc[ai][bj][m][n] = __builtin_amdgcn_mfma_f32_16x16x32_bf16(Bt[n][k], At[m][k], acc[ai][bj][m][n], 0, 0, 0); __builtin_amdgcn_s_setprio(0); } while (0)
; #define PG8_WAIT_V(n) asm volatile("s_waitcnt vmcnt(" #n ")" ::: "memory")
; #define PG8_WAIT_L(n) asm volatile("s_waitcnt lgkmcnt(" #n ")" ::: "memory")
; #define PG8_BAR __builtin_amdgcn_s_barrier()
; #define PG8_SCHED __builtin_amdgcn_sched_barrier(0)
; template <class Epi, class Sched, bool ALIGN_EPI = false, bool SP2 = false>
; __device__ __forceinline__ void gemm_phase(PG8_LAS unsigned char* lds, const Gemm g, const Sched& S, const Epi& E) {
;     ...
;             PG8_WAIT_V(8); PG8_WAIT_L(0); PG8_BAR; PG8_MMA(1, 0, At, B0); PG8_MMA(1, 1, At, B1); PG8_BAR; PG8_SCHED;
;             PG8_LDB(B0, 1, 0); PG8_LDB(B1, 1, 1); PG8_SCHED; PG8_LDA(At, 1, 0); PG8_STAGE(PG8_SA(0, 1), a2 + hstep, voffA);
;             PG8_WAIT_V(8); PG8_WAIT_L(0); PG8_BAR; PG8_MMA(0, 0, At, B0); PG8_MMA(0, 1, At, B1); PG8_BAR; PG8_SCHED;
	s_setprio 1
	v_mfma_f32_16x16x32_bf16 v[62:65], v[144:147], v[182:185], v[62:65]
	v_mfma_f32_16x16x32_bf16 v[58:61], v[158:161], v[182:185], v[58:61]
	v_mfma_f32_16x16x32_bf16 v[46:49], v[144:147], v[190:193], v[46:49]
	v_mfma_f32_16x16x32_bf16 v[42:45], v[158:161], v[190:193], v[42:45]
	v_mfma_f32_16x16x32_bf16 v[30:33], v[144:147], v[212:215], v[30:33]
	v_mfma_f32_16x16x32_bf16 v[26:29], v[158:161], v[212:215], v[26:29]
	v_mfma_f32_16x16x32_bf16 v[14:17], v[144:147], v[220:223], v[14:17]
	v_mfma_f32_16x16x32_bf16 v[10:13], v[158:161], v[220:223], v[10:13]
	v_mfma_f32_16x16x32_bf16 v[62:65], v[148:151], v[186:189], v[62:65]
	v_mfma_f32_16x16x32_bf16 v[58:61], v[162:165], v[186:189], v[58:61]
	v_mfma_f32_16x16x32_bf16 v[46:49], v[148:151], v[208:211], v[46:49]
	v_mfma_f32_16x16x32_bf16 v[42:45], v[162:165], v[208:211], v[42:45]
	v_mfma_f32_16x16x32_bf16 v[30:33], v[148:151], v[216:219], v[30:33]
	v_mfma_f32_16x16x32_bf16 v[26:29], v[162:165], v[216:219], v[26:29]
	v_mfma_f32_16x16x32_bf16 v[14:17], v[148:151], v[228:231], v[14:17]
	v_mfma_f32_16x16x32_bf16 v[10:13], v[162:165], v[228:231], v[10:13]
	v_mfma_f32_16x16x32_bf16 v[54:57], v[166:169], v[182:185], v[54:57]
	v_mfma_f32_16x16x32_bf16 v[50:53], v[174:177], v[182:185], v[50:53]
	v_mfma_f32_16x16x32_bf16 v[38:41], v[166:169], v[190:193], v[38:41]
	v_mfma_f32_16x16x32_bf16 v[34:37], v[174:177], v[190:193], v[34:37]
	v_mfma_f32_16x16x32_bf16 v[22:25], v[166:169], v[212:215], v[22:25]
	v_mfma_f32_16x16x32_bf16 v[18:21], v[174:177], v[212:215], v[18:21]
	v_mfma_f32_16x16x32_bf16 v[6:9], v[166:169], v[220:223], v[6:9]
	v_mfma_f32_16x16x32_bf16 v[2:5], v[174:177], v[220:223], v[2:5]
	v_mfma_f32_16x16x32_bf16 v[54:57], v[170:173], v[186:189], v[54:57]
	v_mfma_f32_16x16x32_bf16 v[50:53], v[178:181], v[186:189], v[50:53]
	v_mfma_f32_16x16x32_bf16 v[38:41], v[170:173], v[208:211], v[38:41]
	v_mfma_f32_16x16x32_bf16 v[34:37], v[178:181], v[208:211], v[34:37]
	v_mfma_f32_16x16x32_bf16 v[22:25], v[170:173], v[216:219], v[22:25]
	v_mfma_f32_16x16x32_bf16 v[18:21], v[178:181], v[216:219], v[18:21]
	v_mfma_f32_16x16x32_bf16 v[6:9], v[170:173], v[228:231], v[6:9]
	v_mfma_f32_16x16x32_bf16 v[2:5], v[178:181], v[228:231], v[2:5]
	s_setprio 0
	s_barrier
	s_add_i32 s17, 0, 0x18000
	v_add_u32_e32 v98, s17, v154
	s_add_i32 s28, 0, 0x1c000
	ds_read_b128 v[144:147], v98
	ds_read_b128 v[148:151], v98 offset:1024
	ds_read_b128 v[158:161], v98 offset:2048
	ds_read_b128 v[162:165], v98 offset:3072
	v_add_u32_e32 v98, s28, v154
	ds_read_b128 v[166:169], v98
	ds_read_b128 v[170:173], v98 offset:1024
	ds_read_b128 v[174:177], v98 offset:2048
	ds_read_b128 v[178:181], v98 offset:3072
	s_add_u32 s30, s34, s14
	s_addc_u32 s31, s35, s15
	s_mov_b32 m0, s65
	v_lshl_add_u64 v[240:241], s[30:31], 0, v[132:133]
	ds_read_b128 v[182:185], v156 offset:32768
	ds_read_b128 v[186:189], v156 offset:33792
	ds_read_b128 v[190:193], v156 offset:34816
	ds_read_b128 v[208:211], v156 offset:35840
	ds_read_b128 v[212:215], v156 offset:36864
	ds_read_b128 v[216:219], v156 offset:37888
	ds_read_b128 v[220:223], v156 offset:38912
	ds_read_b128 v[228:231], v156 offset:39936
	global_load_lds_dwordx4 v[240:241], off
	v_lshl_add_u64 v[240:241], s[30:31], 0, v[136:137]
	s_mov_b32 m0, s66
	s_nop 0
	global_load_lds_dwordx4 v[240:241], off
	s_waitcnt vmcnt(8)
	s_waitcnt lgkmcnt(0)
	s_barrier
	s_setprio 1
	v_mfma_f32_16x16x32_bf16 v[124:127], v[144:147], v[182:185], v[124:127]
	v_mfma_f32_16x16x32_bf16 v[128:131], v[158:161], v[182:185], v[128:131]
	v_mfma_f32_16x16x32_bf16 v[112:115], v[144:147], v[190:193], v[112:115]
	v_mfma_f32_16x16x32_bf16 v[108:111], v[158:161], v[190:193], v[108:111]
	v_mfma_f32_16x16x32_bf16 v[94:97], v[144:147], v[212:215], v[94:97]
	v_mfma_f32_16x16x32_bf16 v[90:93], v[158:161], v[212:215], v[90:93]
	v_mfma_f32_16x16x32_bf16 v[78:81], v[144:147], v[220:223], v[78:81]
	v_mfma_f32_16x16x32_bf16 v[74:77], v[158:161], v[220:223], v[74:77]
	v_mfma_f32_16x16x32_bf16 v[124:127], v[148:151], v[186:189], v[124:127]
	v_mfma_f32_16x16x32_bf16 v[128:131], v[162:165], v[186:189], v[128:131]
	v_mfma_f32_16x16x32_bf16 v[112:115], v[148:151], v[208:211], v[112:115]
	v_mfma_f32_16x16x32_bf16 v[108:111], v[162:165], v[208:211], v[108:111]
	v_mfma_f32_16x16x32_bf16 v[94:97], v[148:151], v[216:219], v[94:97]
	v_mfma_f32_16x16x32_bf16 v[90:93], v[162:165], v[216:219], v[90:93]
	v_mfma_f32_16x16x32_bf16 v[78:81], v[148:151], v[228:231], v[78:81]
	v_mfma_f32_16x16x32_bf16 v[74:77], v[162:165], v[228:231], v[74:77]
	v_mfma_f32_16x16x32_bf16 v[120:123], v[166:169], v[182:185], v[120:123]
	v_mfma_f32_16x16x32_bf16 v[116:119], v[174:177], v[182:185], v[116:119]
	v_mfma_f32_16x16x32_bf16 v[104:107], v[166:169], v[190:193], v[104:107]
	v_mfma_f32_16x16x32_bf16 v[100:103], v[174:177], v[190:193], v[100:103]
	v_mfma_f32_16x16x32_bf16 v[86:89], v[166:169], v[212:215], v[86:89]
	v_mfma_f32_16x16x32_bf16 v[82:85], v[174:177], v[212:215], v[82:85]
	v_mfma_f32_16x16x32_bf16 v[70:73], v[166:169], v[220:223], v[70:73]
	v_mfma_f32_16x16x32_bf16 v[66:69], v[174:177], v[220:223], v[66:69]
	v_mfma_f32_16x16x32_bf16 v[120:123], v[170:173], v[186:189], v[120:123]
	v_mfma_f32_16x16x32_bf16 v[116:119], v[178:181], v[186:189], v[116:119]
	v_mfma_f32_16x16x32_bf16 v[104:107], v[170:173], v[208:211], v[104:107]
	v_mfma_f32_16x16x32_bf16 v[100:103], v[178:181], v[208:211], v[100:103]
	v_mfma_f32_16x16x32_bf16 v[86:89], v[170:173], v[216:219], v[86:89]
	v_mfma_f32_16x16x32_bf16 v[82:85], v[178:181], v[216:219], v[82:85]
	v_mfma_f32_16x16x32_bf16 v[70:73], v[170:173], v[228:231], v[70:73]
	v_mfma_f32_16x16x32_bf16 v[66:69], v[178:181], v[228:231], v[66:69]
	s_setprio 0
	s_barrier
; #define PG8_STAGE(bufoff, gbase, voff) do { _Pragma("unroll") for (int _i = 0; _i < 2; ++_i) \
;         __builtin_amdgcn_global_load_lds((const unsigned*)((const char*)(gbase) + (voff)[_i]), (PG8_LAS unsigned*)(lds + (bufoff) + ldsw + _i * 8192), 16, 0, 0); } while (0)
; #define PG8_LDA(dst, b, h) do { _Pragma("unroll") for (int m = 0; m < 4; ++m) _Pragma("unroll") for (int k = 0; k < 2; ++k) dst[m][k] = *(const PG8_LAS bf16x8*)(lds + PG8_SA(b, h) + aoff + m * 2048 + k * 1024); } while (0)
; #define PG8_MMA(ai, bj, At, Bt) do { __builtin_amdgcn_s_setprio(1); _Pragma("unroll") for (int m = 0; m < 4; ++m) _Pragma("unroll") for (int n = 0; n < 2; ++n) _Pragma("unroll") for (int k = 0; k < 2; ++k) \
;         acc[ai][bj][m][n] = __builtin_amdgcn_mfma_f32_16x16x32_bf16(Bt[n][k], At[m][k], acc[ai][bj][m][n], 0, 0, 0); __builtin_amdgcn_s_setprio(0); } while (0)
; #define PG8_WAIT_V(n) asm volatile("s_waitcnt vmcnt(" #n ")" ::: "memory")
; #define PG8_WAIT_L(n) asm volatile("s_waitcnt lgkmcnt(" #n ")" ::: "memory")
; #define PG8_BAR __builtin_amdgcn_s_barrier()
; #define PG8_SCHED __builtin_amdgcn_sched_barrier(0)
; template <class Epi, class Sched, bool ALIGN_EPI = false, bool SP2 = false>
; __device__ __forceinline__ void gemm_phase(PG8_LAS unsigned char* lds, const Gemm g, const Sched& S, const Epi& E) {
;     ...
;             PG8_LDA(At, 1, 1); PG8_STAGE(PG8_SB(1, 0), b3, voffB); PG8_STAGE(PG8_SB(1, 1), b3 + hstep, voffB); PG8_STAGE(PG8_SA(1, 0), a3, voffA);
;             PG8_WAIT_V(8); PG8_WAIT_L(0); PG8_BAR; PG8_MMA(1, 0, At, B0); PG8_MMA(1, 1, At, B1); PG8_BAR; PG8_SCHED;
	s_add_i32 s17, s17, s62
	v_lshl_add_u64 v[152:153], v[152:153], 0, s[24:25]
	s_mov_b32 m0, s17
	ds_read_b128 v[182:185], v156 offset:49152
	ds_read_b128 v[186:189], v156 offset:50176
	ds_read_b128 v[190:193], v156 offset:51200
	ds_read_b128 v[208:211], v156 offset:52224
	ds_read_b128 v[212:215], v156 offset:53248
	ds_read_b128 v[216:219], v156 offset:54272
	ds_read_b128 v[220:223], v156 offset:55296
	ds_read_b128 v[228:231], v156 offset:56320
	global_load_lds_dwordx4 v[152:153], off
	v_lshl_add_u64 v[152:153], v[224:225], 0, s[24:25]
	s_add_i32 m0, s17, 0x2000
	s_add_i32 s17, s28, s62
	global_load_lds_dwordx4 v[152:153], off
	v_lshl_add_u64 v[152:153], v[232:233], 0, s[24:25]
	s_mov_b32 m0, s17
	s_nop 0
	global_load_lds_dwordx4 v[152:153], off
	v_lshl_add_u64 v[152:153], v[234:235], 0, s[24:25]
	s_add_i32 m0, s17, 0x2000
	s_nop 0
	global_load_lds_dwordx4 v[152:153], off
	v_lshl_add_u64 v[152:153], v[236:237], 0, s[24:25]
	s_mov_b32 m0, s68
	s_nop 0
	global_load_lds_dwordx4 v[152:153], off
	v_lshl_add_u64 v[152:153], v[238:239], 0, s[24:25]
	s_mov_b32 m0, s69
	s_nop 0
	global_load_lds_dwordx4 v[152:153], off
	s_waitcnt vmcnt(8)
	s_waitcnt lgkmcnt(0)
	s_barrier
	s_setprio 1
	v_mfma_f32_16x16x32_bf16 v[62:65], v[144:147], v[182:185], v[62:65]
	v_mfma_f32_16x16x32_bf16 v[58:61], v[158:161], v[182:185], v[58:61]
	v_mfma_f32_16x16x32_bf16 v[46:49], v[144:147], v[190:193], v[46:49]
	v_mfma_f32_16x16x32_bf16 v[42:45], v[158:161], v[190:193], v[42:45]
	v_mfma_f32_16x16x32_bf16 v[30:33], v[144:147], v[212:215], v[30:33]
	v_mfma_f32_16x16x32_bf16 v[26:29], v[158:161], v[212:215], v[26:29]
	v_mfma_f32_16x16x32_bf16 v[14:17], v[144:147], v[220:223], v[14:17]
	v_mfma_f32_16x16x32_bf16 v[10:13], v[158:161], v[220:223], v[10:13]
	v_mfma_f32_16x16x32_bf16 v[62:65], v[148:151], v[186:189], v[62:65]
	v_mfma_f32_16x16x32_bf16 v[58:61], v[162:165], v[186:189], v[58:61]
	v_mfma_f32_16x16x32_bf16 v[46:49], v[148:151], v[208:211], v[46:49]
	v_mfma_f32_16x16x32_bf16 v[42:45], v[162:165], v[208:211], v[42:45]
	v_mfma_f32_16x16x32_bf16 v[30:33], v[148:151], v[216:219], v[30:33]
	v_mfma_f32_16x16x32_bf16 v[26:29], v[162:165], v[216:219], v[26:29]
	v_mfma_f32_16x16x32_bf16 v[14:17], v[148:151], v[228:231], v[14:17]
	v_mfma_f32_16x16x32_bf16 v[10:13], v[162:165], v[228:231], v[10:13]
	v_mfma_f32_16x16x32_bf16 v[54:57], v[166:169], v[182:185], v[54:57]
	v_mfma_f32_16x16x32_bf16 v[50:53], v[174:177], v[182:185], v[50:53]
	v_mfma_f32_16x16x32_bf16 v[38:41], v[166:169], v[190:193], v[38:41]
	v_mfma_f32_16x16x32_bf16 v[34:37], v[174:177], v[190:193], v[34:37]
	v_mfma_f32_16x16x32_bf16 v[22:25], v[166:169], v[212:215], v[22:25]
	v_mfma_f32_16x16x32_bf16 v[18:21], v[174:177], v[212:215], v[18:21]
	v_mfma_f32_16x16x32_bf16 v[6:9], v[166:169], v[220:223], v[6:9]
	v_mfma_f32_16x16x32_bf16 v[2:5], v[174:177], v[220:223], v[2:5]
	v_mfma_f32_16x16x32_bf16 v[54:57], v[170:173], v[186:189], v[54:57]
	v_mfma_f32_16x16x32_bf16 v[50:53], v[178:181], v[186:189], v[50:53]
	v_mfma_f32_16x16x32_bf16 v[38:41], v[170:173], v[208:211], v[38:41]
	v_mfma_f32_16x16x32_bf16 v[34:37], v[178:181], v[208:211], v[34:37]
	v_mfma_f32_16x16x32_bf16 v[22:25], v[170:173], v[216:219], v[22:25]
	v_mfma_f32_16x16x32_bf16 v[18:21], v[178:181], v[216:219], v[18:21]
	v_mfma_f32_16x16x32_bf16 v[6:9], v[170:173], v[228:231], v[6:9]
	v_mfma_f32_16x16x32_bf16 v[2:5], v[178:181], v[228:231], v[2:5]
	s_setprio 0
	s_barrier
	s_add_u32 s2, s2, 0x100
	s_addc_u32 s3, s3, 0
	s_add_u32 s4, s4, 0x100
	s_addc_u32 s16, s16, 0
	s_cmp_ge_i32 s22, s67
	s_mov_b32 s17, s22
	s_cbranch_scc0 .LBB0_1127

; #define PG8_STAGE(bufoff, gbase, voff) do { _Pragma("unroll") for (int _i = 0; _i < 2; ++_i) \
;         __builtin_amdgcn_global_load_lds((const unsigned*)((const char*)(gbase) + (voff)[_i]), (PG8_LAS unsigned*)(lds + (bufoff) + ldsw + _i * 8192), 16, 0, 0); } while (0)
; #define PG8_LDA(dst, b, h) do { _Pragma("unroll") for (int m = 0; m < 4; ++m) _Pragma("unroll") for (int k = 0; k < 2; ++k) dst[m][k] = *(const PG8_LAS bf16x8*)(lds + PG8_SA(b, h) + aoff + m * 2048 + k * 1024); } while (0)
; #define PG8_LDB(dst, b, h) do { _Pragma("unroll") for (int n = 0; n < 2; ++n) _Pragma("unroll") for (int k = 0; k < 2; ++k) dst[n][k] = *(const PG8_LAS bf16x8*)(lds + PG8_SB(b, h) + boff + n * 2048 + k * 1024); } while (0)
; #define PG8_MMA(ai, bj, At, Bt) do { __builtin_amdgcn_s_setprio(1); _Pragma("unroll") for (int m = 0; m < 4; ++m) _Pragma("unroll") for (int n = 0; n < 2; ++n) _Pragma("unroll") for (int k = 0; k < 2; ++k) \
;         acc[ai][bj][m][n] = __builtin_amdgcn_mfma_f32_16x16x32_bf16(Bt[n][k], At[m][k], acc[ai][bj][m][n], 0, 0, 0); __builtin_amdgcn_s_setprio(0); } while (0)
; #define PG8_WAIT_V(n) asm volatile("s_waitcnt vmcnt(" #n ")" ::: "memory")
; #define PG8_WAIT_L(n) asm volatile("s_waitcnt lgkmcnt(" #n ")" ::: "memory")
; template <class Epi, class Sched, bool ALIGN_EPI = false, bool SP2 = false>
; __device__ __forceinline__ void gemm_phase(PG8_LAS unsigned char* lds, const Gemm g, const Sched& S, const Epi& E) {
;     ...
;             const bool last = (t == nt - 2);
;             const char* a1 = cA + (size_t)(t + 1) * kstep;
;             const char* a2 = last ? nA : cA + (size_t)(t + 2) * kstep; const char* b2 = last ? nB : cB + (size_t)(t + 2) * kstep;
;             const char* a3 = a2 + kstep; const char* b3 = b2 + kstep;
;             if (last && has_next) S.a_ready(nxt);
;             if constexpr (SP2) {
;             PG8_LDB(B0, 0, 0); PG8_LDB(B1, 0, 1); PG8_SCHED; PG8_LDA(At, 0, 0); PG8_STAGE(PG8_SA(1, 1), a1 + hstep, voffA);
;             PG8_WAIT_V(8); PG8_WAIT_L(0); PG8_BAR; PG8_MMA(0, 0, At, B0); PG8_MMA(0, 1, At, B1); PG8_BAR; PG8_SCHED;
;             PG8_LDA(At, 0, 1); PG8_STAGE(PG8_SB(0, 0), b2, voffB); PG8_STAGE(PG8_SB(0, 1), b2 + hstep, voffB); PG8_STAGE(PG8_SA(0, 0), a2, voffA);
;             PG8_WAIT_V(8); PG8_WAIT_L(0); PG8_BAR; PG8_MMA(1, 0, At, B0); PG8_MMA(1, 1, At, B1); PG8_BAR; PG8_SCHED;
.LBB0_1180:
	s_add_i32 s22, s17, 2
	s_add_u32 s28, s34, 0x80
	s_addc_u32 s30, s35, 0
	s_add_i32 s33, 0, 0x10000
	s_cmp_eq_u32 s73, s17
	s_cselect_b32 s37, s3, s30
	s_cselect_b32 s36, s2, s28
	s_cselect_b32 s31, s51, s16
	s_cselect_b32 s30, s50, s4
	s_add_i32 s17, 0, 0x14000
	v_add_u32_e32 v158, s33, v148
	v_add_u32_e32 v174, s17, v148
	ds_read_b128 v[144:147], v158
	ds_read_b128 v[150:153], v158 offset:1024
	ds_read_b128 v[154:157], v158 offset:2048
	ds_read_b128 v[158:161], v158 offset:3072
	ds_read_b128 v[162:165], v174
	ds_read_b128 v[166:169], v174 offset:1024
	ds_read_b128 v[170:173], v174 offset:2048
	ds_read_b128 v[174:177], v174 offset:3072
	v_lshl_add_u64 v[224:225], s[34:35], 0, v[140:141]
	s_add_i32 m0, s66, 0xc000
	ds_read_b128 v[178:181], v149
	ds_read_b128 v[182:185], v149 offset:1024
	ds_read_b128 v[186:189], v149 offset:2048
	ds_read_b128 v[190:193], v149 offset:3072
	ds_read_b128 v[208:211], v149 offset:4096
	ds_read_b128 v[212:215], v149 offset:5120
	ds_read_b128 v[216:219], v149 offset:6144
	ds_read_b128 v[220:223], v149 offset:7168
	global_load_lds_dwordx4 v[224:225], off
	v_lshl_add_u64 v[224:225], s[34:35], 0, v[142:143]
	s_add_i32 m0, s66, 0xe000
	s_nop 0
	global_load_lds_dwordx4 v[224:225], off
	s_waitcnt vmcnt(8)
	s_waitcnt lgkmcnt(0)
	s_barrier
	s_setprio 1
	v_mfma_f32_16x16x32_bf16 v[124:127], v[144:147], v[178:181], v[124:127]
	v_mfma_f32_16x16x32_bf16 v[128:131], v[154:157], v[178:181], v[128:131]
	v_mfma_f32_16x16x32_bf16 v[112:115], v[144:147], v[186:189], v[112:115]
	v_mfma_f32_16x16x32_bf16 v[108:111], v[154:157], v[186:189], v[108:111]
	v_mfma_f32_16x16x32_bf16 v[94:97], v[144:147], v[208:211], v[94:97]
	v_mfma_f32_16x16x32_bf16 v[90:93], v[154:157], v[208:211], v[90:93]
	v_mfma_f32_16x16x32_bf16 v[78:81], v[144:147], v[216:219], v[78:81]
	v_mfma_f32_16x16x32_bf16 v[74:77], v[154:157], v[216:219], v[74:77]
	v_mfma_f32_16x16x32_bf16 v[124:127], v[150:153], v[182:185], v[124:127]
	v_mfma_f32_16x16x32_bf16 v[128:131], v[158:161], v[182:185], v[128:131]
	v_mfma_f32_16x16x32_bf16 v[112:115], v[150:153], v[190:193], v[112:115]
	v_mfma_f32_16x16x32_bf16 v[108:111], v[158:161], v[190:193], v[108:111]
	v_mfma_f32_16x16x32_bf16 v[94:97], v[150:153], v[212:215], v[94:97]
	v_mfma_f32_16x16x32_bf16 v[90:93], v[158:161], v[212:215], v[90:93]
	v_mfma_f32_16x16x32_bf16 v[78:81], v[150:153], v[220:223], v[78:81]
	v_mfma_f32_16x16x32_bf16 v[74:77], v[158:161], v[220:223], v[74:77]
	v_mfma_f32_16x16x32_bf16 v[120:123], v[162:165], v[178:181], v[120:123]
	v_mfma_f32_16x16x32_bf16 v[116:119], v[170:173], v[178:181], v[116:119]
	v_mfma_f32_16x16x32_bf16 v[104:107], v[162:165], v[186:189], v[104:107]
	v_mfma_f32_16x16x32_bf16 v[100:103], v[170:173], v[186:189], v[100:103]
	v_mfma_f32_16x16x32_bf16 v[86:89], v[162:165], v[208:211], v[86:89]
	v_mfma_f32_16x16x32_bf16 v[82:85], v[170:173], v[208:211], v[82:85]
	v_mfma_f32_16x16x32_bf16 v[70:73], v[162:165], v[216:219], v[70:73]
	v_mfma_f32_16x16x32_bf16 v[66:69], v[170:173], v[216:219], v[66:69]
	v_mfma_f32_16x16x32_bf16 v[120:123], v[166:169], v[182:185], v[120:123]
	v_mfma_f32_16x16x32_bf16 v[116:119], v[174:177], v[182:185], v[116:119]
	v_mfma_f32_16x16x32_bf16 v[104:107], v[166:169], v[190:193], v[104:107]
	v_mfma_f32_16x16x32_bf16 v[100:103], v[174:177], v[190:193], v[100:103]
	v_mfma_f32_16x16x32_bf16 v[86:89], v[166:169], v[212:215], v[86:89]
	v_mfma_f32_16x16x32_bf16 v[82:85], v[174:177], v[212:215], v[82:85]
	v_mfma_f32_16x16x32_bf16 v[70:73], v[166:169], v[220:223], v[70:73]
	v_mfma_f32_16x16x32_bf16 v[66:69], v[174:177], v[220:223], v[66:69]
	s_setprio 0
	s_barrier
	s_add_i32 s28, s33, s59
	v_lshl_add_u64 v[224:225], s[30:31], 0, v[98:99]
	s_mov_b32 m0, s28
	ds_read_b128 v[178:181], v149 offset:16384
	ds_read_b128 v[182:185], v149 offset:17408
	ds_read_b128 v[186:189], v149 offset:18432
	ds_read_b128 v[190:193], v149 offset:19456
	ds_read_b128 v[208:211], v149 offset:20480
	ds_read_b128 v[212:215], v149 offset:21504
	ds_read_b128 v[216:219], v149 offset:22528
	ds_read_b128 v[220:223], v149 offset:23552
	global_load_lds_dwordx4 v[224:225], off
	s_add_i32 m0, s28, 0x2000
	v_lshl_add_u64 v[228:229], s[30:31], 0, v[132:133]
	s_add_u32 s30, s30, s10
	s_addc_u32 s31, s31, s11
	s_add_i32 s17, s17, s59
	global_load_lds_dwordx4 v[228:229], off
	v_lshl_add_u64 v[230:231], s[30:31], 0, v[98:99]
	s_mov_b32 m0, s17
	v_lshl_add_u64 v[232:233], s[30:31], 0, v[132:133]
	global_load_lds_dwordx4 v[230:231], off
	s_add_i32 m0, s17, 0x2000
	v_lshl_add_u64 v[234:235], s[36:37], 0, v[136:137]
	global_load_lds_dwordx4 v[232:233], off
	s_mov_b32 m0, s66
	v_lshl_add_u64 v[236:237], s[36:37], 0, v[134:135]
	global_load_lds_dwordx4 v[234:235], off
	s_mov_b32 m0, s67
	s_nop 0
	global_load_lds_dwordx4 v[236:237], off
	s_waitcnt vmcnt(8)
	s_waitcnt lgkmcnt(0)
	s_barrier
; #define PG8_STAGE(bufoff, gbase, voff) do { _Pragma("unroll") for (int _i = 0; _i < 2; ++_i) \
;         __builtin_amdgcn_global_load_lds((const unsigned*)((const char*)(gbase) + (voff)[_i]), (PG8_LAS unsigned*)(lds + (bufoff) + ldsw + _i * 8192), 16, 0, 0); } while (0)
; #define PG8_LDA(dst, b, h) do { _Pragma("unroll") for (int m = 0; m < 4; ++m) _Pragma("unroll") for (int k = 0; k < 2; ++k) dst[m][k] = *(const PG8_LAS bf16x8*)(lds + PG8_SA(b, h) + aoff + m * 2048 + k * 1024); } while (0)
; #define PG8_LDB(dst, b, h) do { _Pragma("unroll") for (int n = 0; n < 2; ++n) _Pragma("unroll") for (int k = 0; k < 2; ++k) dst[n][k] = *(const PG8_LAS bf16x8*)(lds + PG8_SB(b, h) + boff + n * 2048 + k * 1024); } while (0)
; #define PG8_MMA(ai, bj, At, Bt) do { __builtin_amdgcn_s_setprio(1); _Pragma("unroll") for (int m = 0; m < 4; ++m) _Pragma("unroll") for (int n = 0; n < 2; ++n) _Pragma("unroll") for (int k = 0; k < 2; ++k) \
;         acc[ai][bj][m][n] = __builtin_amdgcn_mfma_f32_16x16x32_bf16(Bt[n][k], At[m][k], acc[ai][bj][m][n], 0, 0, 0); __builtin_amdgcn_s_setprio(0); } while (0)
; #define PG8_WAIT_V(n) asm volatile("s_waitcnt vmcnt(" #n ")" ::: "memory")
; #define PG8_WAIT_L(n) asm volatile("s_waitcnt lgkmcnt(" #n ")" ::: "memory")
; #define PG8_BAR __builtin_amdgcn_s_barrier()
; #define PG8_SCHED __builtin_amdgcn_sched_barrier(0)
; template <class Epi, class Sched, bool ALIGN_EPI = false, bool SP2 = false>
; __device__ __forceinline__ void gemm_phase(PG8_LAS unsigned char* lds, const Gemm g, const Sched& S, const Epi& E) {
;     ...
;             PG8_WAIT_V(8); PG8_WAIT_L(0); PG8_BAR; PG8_MMA(1, 0, At, B0); PG8_MMA(1, 1, At, B1); PG8_BAR; PG8_SCHED;
;             PG8_LDB(B0, 1, 0); PG8_LDB(B1, 1, 1); PG8_SCHED; PG8_LDA(At, 1, 0); PG8_STAGE(PG8_SA(0, 1), a2 + hstep, voffA);
;             PG8_WAIT_V(8); PG8_WAIT_L(0); PG8_BAR; PG8_MMA(0, 0, At, B0); PG8_MMA(0, 1, At, B1); PG8_BAR; PG8_SCHED;
	s_setprio 1
	v_mfma_f32_16x16x32_bf16 v[62:65], v[144:147], v[178:181], v[62:65]
	v_mfma_f32_16x16x32_bf16 v[58:61], v[154:157], v[178:181], v[58:61]
	v_mfma_f32_16x16x32_bf16 v[46:49], v[144:147], v[186:189], v[46:49]
	v_mfma_f32_16x16x32_bf16 v[42:45], v[154:157], v[186:189], v[42:45]
	v_mfma_f32_16x16x32_bf16 v[30:33], v[144:147], v[208:211], v[30:33]
	v_mfma_f32_16x16x32_bf16 v[26:29], v[154:157], v[208:211], v[26:29]
	v_mfma_f32_16x16x32_bf16 v[14:17], v[144:147], v[216:219], v[14:17]
	v_mfma_f32_16x16x32_bf16 v[10:13], v[154:157], v[216:219], v[10:13]
	v_mfma_f32_16x16x32_bf16 v[62:65], v[150:153], v[182:185], v[62:65]
	v_mfma_f32_16x16x32_bf16 v[58:61], v[158:161], v[182:185], v[58:61]
	v_mfma_f32_16x16x32_bf16 v[46:49], v[150:153], v[190:193], v[46:49]
	v_mfma_f32_16x16x32_bf16 v[42:45], v[158:161], v[190:193], v[42:45]
	v_mfma_f32_16x16x32_bf16 v[30:33], v[150:153], v[212:215], v[30:33]
	v_mfma_f32_16x16x32_bf16 v[26:29], v[158:161], v[212:215], v[26:29]
	v_mfma_f32_16x16x32_bf16 v[14:17], v[150:153], v[220:223], v[14:17]
	v_mfma_f32_16x16x32_bf16 v[10:13], v[158:161], v[220:223], v[10:13]
	v_mfma_f32_16x16x32_bf16 v[54:57], v[162:165], v[178:181], v[54:57]
	v_mfma_f32_16x16x32_bf16 v[50:53], v[170:173], v[178:181], v[50:53]
	v_mfma_f32_16x16x32_bf16 v[38:41], v[162:165], v[186:189], v[38:41]
	v_mfma_f32_16x16x32_bf16 v[34:37], v[170:173], v[186:189], v[34:37]
	v_mfma_f32_16x16x32_bf16 v[22:25], v[162:165], v[208:211], v[22:25]
	v_mfma_f32_16x16x32_bf16 v[18:21], v[170:173], v[208:211], v[18:21]
	v_mfma_f32_16x16x32_bf16 v[6:9], v[162:165], v[216:219], v[6:9]
	v_mfma_f32_16x16x32_bf16 v[2:5], v[170:173], v[216:219], v[2:5]
	v_mfma_f32_16x16x32_bf16 v[54:57], v[166:169], v[182:185], v[54:57]
	v_mfma_f32_16x16x32_bf16 v[50:53], v[174:177], v[182:185], v[50:53]
	v_mfma_f32_16x16x32_bf16 v[38:41], v[166:169], v[190:193], v[38:41]
	v_mfma_f32_16x16x32_bf16 v[34:37], v[174:177], v[190:193], v[34:37]
	v_mfma_f32_16x16x32_bf16 v[22:25], v[166:169], v[212:215], v[22:25]
	v_mfma_f32_16x16x32_bf16 v[18:21], v[174:177], v[212:215], v[18:21]
	v_mfma_f32_16x16x32_bf16 v[6:9], v[166:169], v[220:223], v[6:9]
	v_mfma_f32_16x16x32_bf16 v[2:5], v[174:177], v[220:223], v[2:5]
	s_setprio 0
	s_barrier
	s_add_i32 s17, 0, 0x18000
	s_add_i32 s28, 0, 0x1c000
	v_add_u32_e32 v158, s17, v148
	v_add_u32_e32 v174, s28, v148
	ds_read_b128 v[144:147], v158
	ds_read_b128 v[150:153], v158 offset:1024
	ds_read_b128 v[154:157], v158 offset:2048
	ds_read_b128 v[158:161], v158 offset:3072
	ds_read_b128 v[162:165], v174
	ds_read_b128 v[166:169], v174 offset:1024
	ds_read_b128 v[170:173], v174 offset:2048
	ds_read_b128 v[174:177], v174 offset:3072
	s_add_u32 s30, s36, s10
	s_addc_u32 s31, s37, s11
	s_mov_b32 m0, s68
	v_lshl_add_u64 v[238:239], s[30:31], 0, v[136:137]
	ds_read_b128 v[178:181], v149 offset:32768
	ds_read_b128 v[182:185], v149 offset:33792
	ds_read_b128 v[186:189], v149 offset:34816
	ds_read_b128 v[190:193], v149 offset:35840
	ds_read_b128 v[208:211], v149 offset:36864
	ds_read_b128 v[212:215], v149 offset:37888
	ds_read_b128 v[216:219], v149 offset:38912
	ds_read_b128 v[220:223], v149 offset:39936
	global_load_lds_dwordx4 v[238:239], off
	v_lshl_add_u64 v[238:239], s[30:31], 0, v[134:135]
	s_mov_b32 m0, s69
	s_nop 0
	global_load_lds_dwordx4 v[238:239], off
	s_waitcnt vmcnt(8)
	s_waitcnt lgkmcnt(0)
	s_barrier
	s_setprio 1
	v_mfma_f32_16x16x32_bf16 v[124:127], v[144:147], v[178:181], v[124:127]
	v_mfma_f32_16x16x32_bf16 v[128:131], v[154:157], v[178:181], v[128:131]
	v_mfma_f32_16x16x32_bf16 v[112:115], v[144:147], v[186:189], v[112:115]
	v_mfma_f32_16x16x32_bf16 v[108:111], v[154:157], v[186:189], v[108:111]
	v_mfma_f32_16x16x32_bf16 v[94:97], v[144:147], v[208:211], v[94:97]
	v_mfma_f32_16x16x32_bf16 v[90:93], v[154:157], v[208:211], v[90:93]
	v_mfma_f32_16x16x32_bf16 v[78:81], v[144:147], v[216:219], v[78:81]
	v_mfma_f32_16x16x32_bf16 v[74:77], v[154:157], v[216:219], v[74:77]
	v_mfma_f32_16x16x32_bf16 v[124:127], v[150:153], v[182:185], v[124:127]
	v_mfma_f32_16x16x32_bf16 v[128:131], v[158:161], v[182:185], v[128:131]
	v_mfma_f32_16x16x32_bf16 v[112:115], v[150:153], v[190:193], v[112:115]
	v_mfma_f32_16x16x32_bf16 v[108:111], v[158:161], v[190:193], v[108:111]
	v_mfma_f32_16x16x32_bf16 v[94:97], v[150:153], v[212:215], v[94:97]
	v_mfma_f32_16x16x32_bf16 v[90:93], v[158:161], v[212:215], v[90:93]
	v_mfma_f32_16x16x32_bf16 v[78:81], v[150:153], v[220:223], v[78:81]
	v_mfma_f32_16x16x32_bf16 v[74:77], v[158:161], v[220:223], v[74:77]
	v_mfma_f32_16x16x32_bf16 v[120:123], v[162:165], v[178:181], v[120:123]
	v_mfma_f32_16x16x32_bf16 v[116:119], v[170:173], v[178:181], v[116:119]
	v_mfma_f32_16x16x32_bf16 v[104:107], v[162:165], v[186:189], v[104:107]
	v_mfma_f32_16x16x32_bf16 v[100:103], v[170:173], v[186:189], v[100:103]
	v_mfma_f32_16x16x32_bf16 v[86:89], v[162:165], v[208:211], v[86:89]
	v_mfma_f32_16x16x32_bf16 v[82:85], v[170:173], v[208:211], v[82:85]
	v_mfma_f32_16x16x32_bf16 v[70:73], v[162:165], v[216:219], v[70:73]
	v_mfma_f32_16x16x32_bf16 v[66:69], v[170:173], v[216:219], v[66:69]
	v_mfma_f32_16x16x32_bf16 v[120:123], v[166:169], v[182:185], v[120:123]
	v_mfma_f32_16x16x32_bf16 v[116:119], v[174:177], v[182:185], v[116:119]
	v_mfma_f32_16x16x32_bf16 v[104:107], v[166:169], v[190:193], v[104:107]
	v_mfma_f32_16x16x32_bf16 v[100:103], v[174:177], v[190:193], v[100:103]
	v_mfma_f32_16x16x32_bf16 v[86:89], v[166:169], v[212:215], v[86:89]
	v_mfma_f32_16x16x32_bf16 v[82:85], v[174:177], v[212:215], v[82:85]
	v_mfma_f32_16x16x32_bf16 v[70:73], v[166:169], v[220:223], v[70:73]
	v_mfma_f32_16x16x32_bf16 v[66:69], v[174:177], v[220:223], v[66:69]
	s_setprio 0
	s_barrier
; #define PG8_STAGE(bufoff, gbase, voff) do { _Pragma("unroll") for (int _i = 0; _i < 2; ++_i) \
;         __builtin_amdgcn_global_load_lds((const unsigned*)((const char*)(gbase) + (voff)[_i]), (PG8_LAS unsigned*)(lds + (bufoff) + ldsw + _i * 8192), 16, 0, 0); } while (0)
; #define PG8_LDA(dst, b, h) do { _Pragma("unroll") for (int m = 0; m < 4; ++m) _Pragma("unroll") for (int k = 0; k < 2; ++k) dst[m][k] = *(const PG8_LAS bf16x8*)(lds + PG8_SA(b, h) + aoff + m * 2048 + k * 1024); } while (0)
; #define PG8_MMA(ai, bj, At, Bt) do { __builtin_amdgcn_s_setprio(1); _Pragma("unroll") for (int m = 0; m < 4; ++m) _Pragma("unroll") for (int n = 0; n < 2; ++n) _Pragma("unroll") for (int k = 0; k < 2; ++k) \
;         acc[ai][bj][m][n] = __builtin_amdgcn_mfma_f32_16x16x32_bf16(Bt[n][k], At[m][k], acc[ai][bj][m][n], 0, 0, 0); __builtin_amdgcn_s_setprio(0); } while (0)
; #define PG8_WAIT_V(n) asm volatile("s_waitcnt vmcnt(" #n ")" ::: "memory")
; #define PG8_WAIT_L(n) asm volatile("s_waitcnt lgkmcnt(" #n ")" ::: "memory")
; #define PG8_BAR __builtin_amdgcn_s_barrier()
; #define PG8_SCHED __builtin_amdgcn_sched_barrier(0)
; template <class Epi, class Sched, bool ALIGN_EPI = false, bool SP2 = false>
; __device__ __forceinline__ void gemm_phase(PG8_LAS unsigned char* lds, const Gemm g, const Sched& S, const Epi& E) {
;     ...
;             PG8_LDA(At, 1, 1); PG8_STAGE(PG8_SB(1, 0), b3, voffB); PG8_STAGE(PG8_SB(1, 1), b3 + hstep, voffB); PG8_STAGE(PG8_SA(1, 0), a3, voffA);
;             PG8_WAIT_V(8); PG8_WAIT_L(0); PG8_BAR; PG8_MMA(1, 0, At, B0); PG8_MMA(1, 1, At, B1); PG8_BAR; PG8_SCHED;
	s_add_i32 s17, s17, s59
	v_lshl_add_u64 v[224:225], v[224:225], 0, s[24:25]
	s_mov_b32 m0, s17
	ds_read_b128 v[178:181], v149 offset:49152
	ds_read_b128 v[182:185], v149 offset:50176
	ds_read_b128 v[186:189], v149 offset:51200
	ds_read_b128 v[190:193], v149 offset:52224
	ds_read_b128 v[208:211], v149 offset:53248
	ds_read_b128 v[212:215], v149 offset:54272
	ds_read_b128 v[216:219], v149 offset:55296
	ds_read_b128 v[220:223], v149 offset:56320
	global_load_lds_dwordx4 v[224:225], off
	v_lshl_add_u64 v[224:225], v[228:229], 0, s[24:25]
	s_add_i32 m0, s17, 0x2000
	s_add_i32 s17, s28, s59
	global_load_lds_dwordx4 v[224:225], off
	v_lshl_add_u64 v[224:225], v[230:231], 0, s[24:25]
	s_mov_b32 m0, s17
	s_nop 0
	global_load_lds_dwordx4 v[224:225], off
	v_lshl_add_u64 v[224:225], v[232:233], 0, s[24:25]
	s_add_i32 m0, s17, 0x2000
	s_nop 0
	global_load_lds_dwordx4 v[224:225], off
	v_lshl_add_u64 v[224:225], v[234:235], 0, s[24:25]
	s_mov_b32 m0, s71
	s_nop 0
	global_load_lds_dwordx4 v[224:225], off
	v_lshl_add_u64 v[224:225], v[236:237], 0, s[24:25]
	s_mov_b32 m0, s72
	s_nop 0
	global_load_lds_dwordx4 v[224:225], off
	s_waitcnt vmcnt(8)
	s_waitcnt lgkmcnt(0)
	s_barrier
	s_setprio 1
	v_mfma_f32_16x16x32_bf16 v[62:65], v[144:147], v[178:181], v[62:65]
	v_mfma_f32_16x16x32_bf16 v[58:61], v[154:157], v[178:181], v[58:61]
	v_mfma_f32_16x16x32_bf16 v[46:49], v[144:147], v[186:189], v[46:49]
	v_mfma_f32_16x16x32_bf16 v[42:45], v[154:157], v[186:189], v[42:45]
	v_mfma_f32_16x16x32_bf16 v[30:33], v[144:147], v[208:211], v[30:33]
	v_mfma_f32_16x16x32_bf16 v[26:29], v[154:157], v[208:211], v[26:29]
	v_mfma_f32_16x16x32_bf16 v[14:17], v[144:147], v[216:219], v[14:17]
	v_mfma_f32_16x16x32_bf16 v[10:13], v[154:157], v[216:219], v[10:13]
	v_mfma_f32_16x16x32_bf16 v[62:65], v[150:153], v[182:185], v[62:65]
	v_mfma_f32_16x16x32_bf16 v[58:61], v[158:161], v[182:185], v[58:61]
	v_mfma_f32_16x16x32_bf16 v[46:49], v[150:153], v[190:193], v[46:49]
	v_mfma_f32_16x16x32_bf16 v[42:45], v[158:161], v[190:193], v[42:45]
	v_mfma_f32_16x16x32_bf16 v[30:33], v[150:153], v[212:215], v[30:33]
	v_mfma_f32_16x16x32_bf16 v[26:29], v[158:161], v[212:215], v[26:29]
	v_mfma_f32_16x16x32_bf16 v[14:17], v[150:153], v[220:223], v[14:17]
	v_mfma_f32_16x16x32_bf16 v[10:13], v[158:161], v[220:223], v[10:13]
	v_mfma_f32_16x16x32_bf16 v[54:57], v[162:165], v[178:181], v[54:57]
	v_mfma_f32_16x16x32_bf16 v[50:53], v[170:173], v[178:181], v[50:53]
	v_mfma_f32_16x16x32_bf16 v[38:41], v[162:165], v[186:189], v[38:41]
	v_mfma_f32_16x16x32_bf16 v[34:37], v[170:173], v[186:189], v[34:37]
	v_mfma_f32_16x16x32_bf16 v[22:25], v[162:165], v[208:211], v[22:25]
	v_mfma_f32_16x16x32_bf16 v[18:21], v[170:173], v[208:211], v[18:21]
	v_mfma_f32_16x16x32_bf16 v[6:9], v[162:165], v[216:219], v[6:9]
	v_mfma_f32_16x16x32_bf16 v[2:5], v[170:173], v[216:219], v[2:5]
	v_mfma_f32_16x16x32_bf16 v[54:57], v[166:169], v[182:185], v[54:57]
	v_mfma_f32_16x16x32_bf16 v[50:53], v[174:177], v[182:185], v[50:53]
	v_mfma_f32_16x16x32_bf16 v[38:41], v[166:169], v[190:193], v[38:41]
	v_mfma_f32_16x16x32_bf16 v[34:37], v[174:177], v[190:193], v[34:37]
	v_mfma_f32_16x16x32_bf16 v[22:25], v[166:169], v[212:215], v[22:25]
	v_mfma_f32_16x16x32_bf16 v[18:21], v[174:177], v[212:215], v[18:21]
	v_mfma_f32_16x16x32_bf16 v[6:9], v[166:169], v[220:223], v[6:9]
	v_mfma_f32_16x16x32_bf16 v[2:5], v[174:177], v[220:223], v[2:5]
	s_setprio 0
	s_barrier
	s_add_u32 s34, s34, 0x100
	s_addc_u32 s35, s35, 0
	s_add_u32 s4, s4, 0x100
	s_addc_u32 s16, s16, 0
	s_cmp_ge_i32 s22, s70
	s_mov_b32 s17, s22
	s_cbranch_scc0 .LBB0_1180

; #define PG8_STAGE(bufoff, gbase, voff) do { _Pragma("unroll") for (int _i = 0; _i < 2; ++_i) \
;         __builtin_amdgcn_global_load_lds((const unsigned*)((const char*)(gbase) + (voff)[_i]), (PG8_LAS unsigned*)(lds + (bufoff) + ldsw + _i * 8192), 16, 0, 0); } while (0)
; #define PG8_LDA(dst, b, h) do { _Pragma("unroll") for (int m = 0; m < 4; ++m) _Pragma("unroll") for (int k = 0; k < 2; ++k) dst[m][k] = *(const PG8_LAS bf16x8*)(lds + PG8_SA(b, h) + aoff + m * 2048 + k * 1024); } while (0)
; #define PG8_LDB(dst, b, h) do { _Pragma("unroll") for (int n = 0; n < 2; ++n) _Pragma("unroll") for (int k = 0; k < 2; ++k) dst[n][k] = *(const PG8_LAS bf16x8*)(lds + PG8_SB(b, h) + boff + n * 2048 + k * 1024); } while (0)
; #define PG8_MMA(ai, bj, At, Bt) do { __builtin_amdgcn_s_setprio(1); _Pragma("unroll") for (int m = 0; m < 4; ++m) _Pragma("unroll") for (int n = 0; n < 2; ++n) _Pragma("unroll") for (int k = 0; k < 2; ++k) \
;         acc[ai][bj][m][n] = __builtin_amdgcn_mfma_f32_16x16x32_bf16(Bt[n][k], At[m][k], acc[ai][bj][m][n], 0, 0, 0); __builtin_amdgcn_s_setprio(0); } while (0)
; #define PG8_WAIT_V(n) asm volatile("s_waitcnt vmcnt(" #n ")" ::: "memory")
; #define PG8_WAIT_L(n) asm volatile("s_waitcnt lgkmcnt(" #n ")" ::: "memory")
; template <class Epi, class Sched, bool ALIGN_EPI = false, bool SP2 = false>
; __device__ __forceinline__ void gemm_phase(PG8_LAS unsigned char* lds, const Gemm g, const Sched& S, const Epi& E) {
;     ...
;             const bool last = (t == nt - 2);
;             const char* a1 = cA + (size_t)(t + 1) * kstep;
;             const char* a2 = last ? nA : cA + (size_t)(t + 2) * kstep; const char* b2 = last ? nB : cB + (size_t)(t + 2) * kstep;
;             const char* a3 = a2 + kstep; const char* b3 = b2 + kstep;
;             if (last && has_next) S.a_ready(nxt);
;             if constexpr (SP2) {
;             PG8_LDB(B0, 0, 0); PG8_LDB(B1, 0, 1); PG8_SCHED; PG8_LDA(At, 0, 0); PG8_STAGE(PG8_SA(1, 1), a1 + hstep, voffA);
;             PG8_WAIT_V(8); PG8_WAIT_L(0); PG8_BAR; PG8_MMA(0, 0, At, B0); PG8_MMA(0, 1, At, B1); PG8_BAR; PG8_SCHED;
;             PG8_LDA(At, 0, 1); PG8_STAGE(PG8_SB(0, 0), b2, voffB); PG8_STAGE(PG8_SB(0, 1), b2 + hstep, voffB); PG8_STAGE(PG8_SA(0, 0), a2, voffA);
;             PG8_WAIT_V(8); PG8_WAIT_L(0); PG8_BAR; PG8_MMA(1, 0, At, B0); PG8_MMA(1, 1, At, B1); PG8_BAR; PG8_SCHED;
.LBB0_1209:
	s_add_i32 s22, s17, 2
	s_add_u32 s28, s2, 0x80
	s_addc_u32 s30, s3, 0
	s_add_i32 s33, 0, 0x10000
	s_cmp_eq_u32 s74, s17
	s_cselect_b32 s35, s51, s30
	s_cselect_b32 s34, s50, s28
	v_add_u32_e32 v98, s33, v166
	s_cselect_b32 s31, s53, s16
	s_cselect_b32 s30, s52, s4
	s_add_i32 s17, 0, 0x14000
	ds_read_b128 v[132:135], v98
	ds_read_b128 v[136:139], v98 offset:1024
	ds_read_b128 v[140:143], v98 offset:2048
	ds_read_b128 v[156:159], v98 offset:3072
	v_add_u32_e32 v98, s17, v166
	ds_read_b128 v[160:163], v98
	ds_read_b128 v[170:173], v98 offset:1024
	ds_read_b128 v[174:177], v98 offset:2048
	ds_read_b128 v[178:181], v98 offset:3072
	v_lshl_add_u64 v[164:165], s[2:3], 0, v[152:153]
	s_add_i32 m0, s67, 0xc000
	ds_read_b128 v[182:185], v168
	ds_read_b128 v[186:189], v168 offset:1024
	ds_read_b128 v[190:193], v168 offset:2048
	ds_read_b128 v[208:211], v168 offset:3072
	ds_read_b128 v[212:215], v168 offset:4096
	ds_read_b128 v[216:219], v168 offset:5120
	ds_read_b128 v[220:223], v168 offset:6144
	ds_read_b128 v[228:231], v168 offset:7168
	global_load_lds_dwordx4 v[164:165], off
	v_lshl_add_u64 v[164:165], s[2:3], 0, v[154:155]
	s_add_i32 m0, s67, 0xe000
	s_nop 0
	global_load_lds_dwordx4 v[164:165], off
	s_waitcnt vmcnt(8)
	s_waitcnt lgkmcnt(0)
	s_barrier
	s_setprio 1
	v_mfma_f32_16x16x32_bf16 v[128:131], v[132:135], v[182:185], v[128:131]
	v_mfma_f32_16x16x32_bf16 v[124:127], v[140:143], v[182:185], v[124:127]
	v_mfma_f32_16x16x32_bf16 v[120:123], v[132:135], v[190:193], v[120:123]
	v_mfma_f32_16x16x32_bf16 v[116:119], v[140:143], v[190:193], v[116:119]
	v_mfma_f32_16x16x32_bf16 v[112:115], v[132:135], v[212:215], v[112:115]
	v_mfma_f32_16x16x32_bf16 v[108:111], v[140:143], v[212:215], v[108:111]
	v_mfma_f32_16x16x32_bf16 v[104:107], v[132:135], v[220:223], v[104:107]
	v_mfma_f32_16x16x32_bf16 v[100:103], v[140:143], v[220:223], v[100:103]
	v_mfma_f32_16x16x32_bf16 v[128:131], v[136:139], v[186:189], v[128:131]
	v_mfma_f32_16x16x32_bf16 v[124:127], v[156:159], v[186:189], v[124:127]
	v_mfma_f32_16x16x32_bf16 v[120:123], v[136:139], v[208:211], v[120:123]
	v_mfma_f32_16x16x32_bf16 v[116:119], v[156:159], v[208:211], v[116:119]
	v_mfma_f32_16x16x32_bf16 v[112:115], v[136:139], v[216:219], v[112:115]
	v_mfma_f32_16x16x32_bf16 v[108:111], v[156:159], v[216:219], v[108:111]
	v_mfma_f32_16x16x32_bf16 v[104:107], v[136:139], v[228:231], v[104:107]
	v_mfma_f32_16x16x32_bf16 v[100:103], v[156:159], v[228:231], v[100:103]
	v_mfma_f32_16x16x32_bf16 v[62:65], v[160:163], v[182:185], v[62:65]
	v_mfma_f32_16x16x32_bf16 v[58:61], v[174:177], v[182:185], v[58:61]
	v_mfma_f32_16x16x32_bf16 v[54:57], v[160:163], v[190:193], v[54:57]
	v_mfma_f32_16x16x32_bf16 v[50:53], v[174:177], v[190:193], v[50:53]
	v_mfma_f32_16x16x32_bf16 v[46:49], v[160:163], v[212:215], v[46:49]
	v_mfma_f32_16x16x32_bf16 v[42:45], v[174:177], v[212:215], v[42:45]
	v_mfma_f32_16x16x32_bf16 v[38:41], v[160:163], v[220:223], v[38:41]
	v_mfma_f32_16x16x32_bf16 v[34:37], v[174:177], v[220:223], v[34:37]
	v_mfma_f32_16x16x32_bf16 v[62:65], v[170:173], v[186:189], v[62:65]
	v_mfma_f32_16x16x32_bf16 v[58:61], v[178:181], v[186:189], v[58:61]
	v_mfma_f32_16x16x32_bf16 v[54:57], v[170:173], v[208:211], v[54:57]
	v_mfma_f32_16x16x32_bf16 v[50:53], v[178:181], v[208:211], v[50:53]
	v_mfma_f32_16x16x32_bf16 v[46:49], v[170:173], v[216:219], v[46:49]
	v_mfma_f32_16x16x32_bf16 v[42:45], v[178:181], v[216:219], v[42:45]
	v_mfma_f32_16x16x32_bf16 v[38:41], v[170:173], v[228:231], v[38:41]
	v_mfma_f32_16x16x32_bf16 v[34:37], v[178:181], v[228:231], v[34:37]
	s_setprio 0
	s_barrier
	s_add_i32 s28, s33, s62
	v_lshl_add_u64 v[164:165], s[30:31], 0, v[146:147]
	s_mov_b32 m0, s28
	ds_read_b128 v[182:185], v168 offset:16384
	ds_read_b128 v[186:189], v168 offset:17408
	ds_read_b128 v[190:193], v168 offset:18432
	ds_read_b128 v[208:211], v168 offset:19456
	ds_read_b128 v[212:215], v168 offset:20480
	ds_read_b128 v[216:219], v168 offset:21504
	ds_read_b128 v[220:223], v168 offset:22528
	ds_read_b128 v[228:231], v168 offset:23552
	global_load_lds_dwordx4 v[164:165], off
	s_add_i32 m0, s28, 0x2000
	v_lshl_add_u64 v[224:225], s[30:31], 0, v[150:151]
	s_add_u32 s30, s30, s10
	s_addc_u32 s31, s31, s11
	s_add_i32 s17, s17, s62
	global_load_lds_dwordx4 v[224:225], off
	v_lshl_add_u64 v[232:233], s[30:31], 0, v[146:147]
	s_mov_b32 m0, s17
	v_lshl_add_u64 v[234:235], s[30:31], 0, v[150:151]
	global_load_lds_dwordx4 v[232:233], off
	s_add_i32 m0, s17, 0x2000
	v_lshl_add_u64 v[236:237], s[34:35], 0, v[144:145]
	global_load_lds_dwordx4 v[234:235], off
	s_mov_b32 m0, s67
	v_lshl_add_u64 v[238:239], s[34:35], 0, v[148:149]
	global_load_lds_dwordx4 v[236:237], off
	s_mov_b32 m0, s68
	s_nop 0
	global_load_lds_dwordx4 v[238:239], off
	s_waitcnt vmcnt(8)
	s_waitcnt lgkmcnt(0)
	s_barrier
; #define PG8_STAGE(bufoff, gbase, voff) do { _Pragma("unroll") for (int _i = 0; _i < 2; ++_i) \
;         __builtin_amdgcn_global_load_lds((const unsigned*)((const char*)(gbase) + (voff)[_i]), (PG8_LAS unsigned*)(lds + (bufoff) + ldsw + _i * 8192), 16, 0, 0); } while (0)
; #define PG8_LDA(dst, b, h) do { _Pragma("unroll") for (int m = 0; m < 4; ++m) _Pragma("unroll") for (int k = 0; k < 2; ++k) dst[m][k] = *(const PG8_LAS bf16x8*)(lds + PG8_SA(b, h) + aoff + m * 2048 + k * 1024); } while (0)
; #define PG8_LDB(dst, b, h) do { _Pragma("unroll") for (int n = 0; n < 2; ++n) _Pragma("unroll") for (int k = 0; k < 2; ++k) dst[n][k] = *(const PG8_LAS bf16x8*)(lds + PG8_SB(b, h) + boff + n * 2048 + k * 1024); } while (0)
; #define PG8_MMA(ai, bj, At, Bt) do { __builtin_amdgcn_s_setprio(1); _Pragma("unroll") for (int m = 0; m < 4; ++m) _Pragma("unroll") for (int n = 0; n < 2; ++n) _Pragma("unroll") for (int k = 0; k < 2; ++k) \
;         acc[ai][bj][m][n] = __builtin_amdgcn_mfma_f32_16x16x32_bf16(Bt[n][k], At[m][k], acc[ai][bj][m][n], 0, 0, 0); __builtin_amdgcn_s_setprio(0); } while (0)
; #define PG8_WAIT_V(n) asm volatile("s_waitcnt vmcnt(" #n ")" ::: "memory")
; #define PG8_WAIT_L(n) asm volatile("s_waitcnt lgkmcnt(" #n ")" ::: "memory")
; #define PG8_BAR __builtin_amdgcn_s_barrier()
; #define PG8_SCHED __builtin_amdgcn_sched_barrier(0)
; template <class Epi, class Sched, bool ALIGN_EPI = false, bool SP2 = false>
; __device__ __forceinline__ void gemm_phase(PG8_LAS unsigned char* lds, const Gemm g, const Sched& S, const Epi& E) {
;     ...
;             PG8_WAIT_V(8); PG8_WAIT_L(0); PG8_BAR; PG8_MMA(1, 0, At, B0); PG8_MMA(1, 1, At, B1); PG8_BAR; PG8_SCHED;
;             PG8_LDB(B0, 1, 0); PG8_LDB(B1, 1, 1); PG8_SCHED; PG8_LDA(At, 1, 0); PG8_STAGE(PG8_SA(0, 1), a2 + hstep, voffA);
;             PG8_WAIT_V(8); PG8_WAIT_L(0); PG8_BAR; PG8_MMA(0, 0, At, B0); PG8_MMA(0, 1, At, B1); PG8_BAR; PG8_SCHED;
	s_setprio 1
	v_mfma_f32_16x16x32_bf16 v[94:97], v[132:135], v[182:185], v[94:97]
	v_mfma_f32_16x16x32_bf16 v[90:93], v[140:143], v[182:185], v[90:93]
	v_mfma_f32_16x16x32_bf16 v[86:89], v[132:135], v[190:193], v[86:89]
	v_mfma_f32_16x16x32_bf16 v[82:85], v[140:143], v[190:193], v[82:85]
	v_mfma_f32_16x16x32_bf16 v[78:81], v[132:135], v[212:215], v[78:81]
	v_mfma_f32_16x16x32_bf16 v[74:77], v[140:143], v[212:215], v[74:77]
	v_mfma_f32_16x16x32_bf16 v[70:73], v[132:135], v[220:223], v[70:73]
	v_mfma_f32_16x16x32_bf16 v[66:69], v[140:143], v[220:223], v[66:69]
	v_mfma_f32_16x16x32_bf16 v[94:97], v[136:139], v[186:189], v[94:97]
	v_mfma_f32_16x16x32_bf16 v[90:93], v[156:159], v[186:189], v[90:93]
	v_mfma_f32_16x16x32_bf16 v[86:89], v[136:139], v[208:211], v[86:89]
	v_mfma_f32_16x16x32_bf16 v[82:85], v[156:159], v[208:211], v[82:85]
	v_mfma_f32_16x16x32_bf16 v[78:81], v[136:139], v[216:219], v[78:81]
	v_mfma_f32_16x16x32_bf16 v[74:77], v[156:159], v[216:219], v[74:77]
	v_mfma_f32_16x16x32_bf16 v[70:73], v[136:139], v[228:231], v[70:73]
	v_mfma_f32_16x16x32_bf16 v[66:69], v[156:159], v[228:231], v[66:69]
	v_mfma_f32_16x16x32_bf16 v[30:33], v[160:163], v[182:185], v[30:33]
	v_mfma_f32_16x16x32_bf16 v[26:29], v[174:177], v[182:185], v[26:29]
	v_mfma_f32_16x16x32_bf16 v[22:25], v[160:163], v[190:193], v[22:25]
	v_mfma_f32_16x16x32_bf16 v[18:21], v[174:177], v[190:193], v[18:21]
	v_mfma_f32_16x16x32_bf16 v[14:17], v[160:163], v[212:215], v[14:17]
	v_mfma_f32_16x16x32_bf16 v[10:13], v[174:177], v[212:215], v[10:13]
	v_mfma_f32_16x16x32_bf16 v[6:9], v[160:163], v[220:223], v[6:9]
	v_mfma_f32_16x16x32_bf16 v[2:5], v[174:177], v[220:223], v[2:5]
	v_mfma_f32_16x16x32_bf16 v[30:33], v[170:173], v[186:189], v[30:33]
	v_mfma_f32_16x16x32_bf16 v[26:29], v[178:181], v[186:189], v[26:29]
	v_mfma_f32_16x16x32_bf16 v[22:25], v[170:173], v[208:211], v[22:25]
	v_mfma_f32_16x16x32_bf16 v[18:21], v[178:181], v[208:211], v[18:21]
	v_mfma_f32_16x16x32_bf16 v[14:17], v[170:173], v[216:219], v[14:17]
	v_mfma_f32_16x16x32_bf16 v[10:13], v[178:181], v[216:219], v[10:13]
	v_mfma_f32_16x16x32_bf16 v[6:9], v[170:173], v[228:231], v[6:9]
	v_mfma_f32_16x16x32_bf16 v[2:5], v[178:181], v[228:231], v[2:5]
	s_setprio 0
	s_barrier
	s_add_i32 s17, 0, 0x18000
	v_add_u32_e32 v98, s17, v166
	s_add_i32 s28, 0, 0x1c000
	ds_read_b128 v[132:135], v98
	ds_read_b128 v[136:139], v98 offset:1024
	ds_read_b128 v[140:143], v98 offset:2048
	ds_read_b128 v[156:159], v98 offset:3072
	v_add_u32_e32 v98, s28, v166
	ds_read_b128 v[160:163], v98
	ds_read_b128 v[170:173], v98 offset:1024
	ds_read_b128 v[174:177], v98 offset:2048
	ds_read_b128 v[178:181], v98 offset:3072
	s_add_u32 s30, s34, s10
	s_addc_u32 s31, s35, s11
	s_mov_b32 m0, s69
	v_lshl_add_u64 v[240:241], s[30:31], 0, v[144:145]
	ds_read_b128 v[182:185], v168 offset:32768
	ds_read_b128 v[186:189], v168 offset:33792
	ds_read_b128 v[190:193], v168 offset:34816
	ds_read_b128 v[208:211], v168 offset:35840
	ds_read_b128 v[212:215], v168 offset:36864
	ds_read_b128 v[216:219], v168 offset:37888
	ds_read_b128 v[220:223], v168 offset:38912
	ds_read_b128 v[228:231], v168 offset:39936
	global_load_lds_dwordx4 v[240:241], off
	v_lshl_add_u64 v[240:241], s[30:31], 0, v[148:149]
	s_mov_b32 m0, s70
	s_nop 0
	global_load_lds_dwordx4 v[240:241], off
	s_waitcnt vmcnt(8)
	s_waitcnt lgkmcnt(0)
	s_barrier
	s_setprio 1
	v_mfma_f32_16x16x32_bf16 v[128:131], v[132:135], v[182:185], v[128:131]
	v_mfma_f32_16x16x32_bf16 v[124:127], v[140:143], v[182:185], v[124:127]
	v_mfma_f32_16x16x32_bf16 v[120:123], v[132:135], v[190:193], v[120:123]
	v_mfma_f32_16x16x32_bf16 v[116:119], v[140:143], v[190:193], v[116:119]
	v_mfma_f32_16x16x32_bf16 v[112:115], v[132:135], v[212:215], v[112:115]
	v_mfma_f32_16x16x32_bf16 v[108:111], v[140:143], v[212:215], v[108:111]
	v_mfma_f32_16x16x32_bf16 v[104:107], v[132:135], v[220:223], v[104:107]
	v_mfma_f32_16x16x32_bf16 v[100:103], v[140:143], v[220:223], v[100:103]
	v_mfma_f32_16x16x32_bf16 v[128:131], v[136:139], v[186:189], v[128:131]
	v_mfma_f32_16x16x32_bf16 v[124:127], v[156:159], v[186:189], v[124:127]
	v_mfma_f32_16x16x32_bf16 v[120:123], v[136:139], v[208:211], v[120:123]
	v_mfma_f32_16x16x32_bf16 v[116:119], v[156:159], v[208:211], v[116:119]
	v_mfma_f32_16x16x32_bf16 v[112:115], v[136:139], v[216:219], v[112:115]
	v_mfma_f32_16x16x32_bf16 v[108:111], v[156:159], v[216:219], v[108:111]
	v_mfma_f32_16x16x32_bf16 v[104:107], v[136:139], v[228:231], v[104:107]
	v_mfma_f32_16x16x32_bf16 v[100:103], v[156:159], v[228:231], v[100:103]
	v_mfma_f32_16x16x32_bf16 v[62:65], v[160:163], v[182:185], v[62:65]
	v_mfma_f32_16x16x32_bf16 v[58:61], v[174:177], v[182:185], v[58:61]
	v_mfma_f32_16x16x32_bf16 v[54:57], v[160:163], v[190:193], v[54:57]
	v_mfma_f32_16x16x32_bf16 v[50:53], v[174:177], v[190:193], v[50:53]
	v_mfma_f32_16x16x32_bf16 v[46:49], v[160:163], v[212:215], v[46:49]
	v_mfma_f32_16x16x32_bf16 v[42:45], v[174:177], v[212:215], v[42:45]
	v_mfma_f32_16x16x32_bf16 v[38:41], v[160:163], v[220:223], v[38:41]
	v_mfma_f32_16x16x32_bf16 v[34:37], v[174:177], v[220:223], v[34:37]
	v_mfma_f32_16x16x32_bf16 v[62:65], v[170:173], v[186:189], v[62:65]
	v_mfma_f32_16x16x32_bf16 v[58:61], v[178:181], v[186:189], v[58:61]
	v_mfma_f32_16x16x32_bf16 v[54:57], v[170:173], v[208:211], v[54:57]
	v_mfma_f32_16x16x32_bf16 v[50:53], v[178:181], v[208:211], v[50:53]
	v_mfma_f32_16x16x32_bf16 v[46:49], v[170:173], v[216:219], v[46:49]
	v_mfma_f32_16x16x32_bf16 v[42:45], v[178:181], v[216:219], v[42:45]
	v_mfma_f32_16x16x32_bf16 v[38:41], v[170:173], v[228:231], v[38:41]
	v_mfma_f32_16x16x32_bf16 v[34:37], v[178:181], v[228:231], v[34:37]
	s_setprio 0
	s_barrier
; #define PG8_STAGE(bufoff, gbase, voff) do { _Pragma("unroll") for (int _i = 0; _i < 2; ++_i) \
;         __builtin_amdgcn_global_load_lds((const unsigned*)((const char*)(gbase) + (voff)[_i]), (PG8_LAS unsigned*)(lds + (bufoff) + ldsw + _i * 8192), 16, 0, 0); } while (0)
; #define PG8_LDA(dst, b, h) do { _Pragma("unroll") for (int m = 0; m < 4; ++m) _Pragma("unroll") for (int k = 0; k < 2; ++k) dst[m][k] = *(const PG8_LAS bf16x8*)(lds + PG8_SA(b, h) + aoff + m * 2048 + k * 1024); } while (0)
; #define PG8_MMA(ai, bj, At, Bt) do { __builtin_amdgcn_s_setprio(1); _Pragma("unroll") for (int m = 0; m < 4; ++m) _Pragma("unroll") for (int n = 0; n < 2; ++n) _Pragma("unroll") for (int k = 0; k < 2; ++k) \
;         acc[ai][bj][m][n] = __builtin_amdgcn_mfma_f32_16x16x32_bf16(Bt[n][k], At[m][k], acc[ai][bj][m][n], 0, 0, 0); __builtin_amdgcn_s_setprio(0); } while (0)
; #define PG8_WAIT_V(n) asm volatile("s_waitcnt vmcnt(" #n ")" ::: "memory")
; #define PG8_WAIT_L(n) asm volatile("s_waitcnt lgkmcnt(" #n ")" ::: "memory")
; #define PG8_BAR __builtin_amdgcn_s_barrier()
; #define PG8_SCHED __builtin_amdgcn_sched_barrier(0)
; template <class Epi, class Sched, bool ALIGN_EPI = false, bool SP2 = false>
; __device__ __forceinline__ void gemm_phase(PG8_LAS unsigned char* lds, const Gemm g, const Sched& S, const Epi& E) {
;     ...
;             PG8_LDA(At, 1, 1); PG8_STAGE(PG8_SB(1, 0), b3, voffB); PG8_STAGE(PG8_SB(1, 1), b3 + hstep, voffB); PG8_STAGE(PG8_SA(1, 0), a3, voffA);
;             PG8_WAIT_V(8); PG8_WAIT_L(0); PG8_BAR; PG8_MMA(1, 0, At, B0); PG8_MMA(1, 1, At, B1); PG8_BAR; PG8_SCHED;
	s_add_i32 s17, s17, s62
	v_lshl_add_u64 v[164:165], v[164:165], 0, s[24:25]
	s_mov_b32 m0, s17
	ds_read_b128 v[182:185], v168 offset:49152
	ds_read_b128 v[186:189], v168 offset:50176
	ds_read_b128 v[190:193], v168 offset:51200
	ds_read_b128 v[208:211], v168 offset:52224
	ds_read_b128 v[212:215], v168 offset:53248
	ds_read_b128 v[216:219], v168 offset:54272
	ds_read_b128 v[220:223], v168 offset:55296
	ds_read_b128 v[228:231], v168 offset:56320
	global_load_lds_dwordx4 v[164:165], off
	v_lshl_add_u64 v[164:165], v[224:225], 0, s[24:25]
	s_add_i32 m0, s17, 0x2000
	s_add_i32 s17, s28, s62
	global_load_lds_dwordx4 v[164:165], off
	v_lshl_add_u64 v[164:165], v[232:233], 0, s[24:25]
	s_mov_b32 m0, s17
	s_nop 0
	global_load_lds_dwordx4 v[164:165], off
	v_lshl_add_u64 v[164:165], v[234:235], 0, s[24:25]
	s_add_i32 m0, s17, 0x2000
	s_nop 0
	global_load_lds_dwordx4 v[164:165], off
	v_lshl_add_u64 v[164:165], v[236:237], 0, s[24:25]
	s_mov_b32 m0, s72
	s_nop 0
	global_load_lds_dwordx4 v[164:165], off
	v_lshl_add_u64 v[164:165], v[238:239], 0, s[24:25]
	s_mov_b32 m0, s73
	s_nop 0
	global_load_lds_dwordx4 v[164:165], off
	s_waitcnt vmcnt(8)
	s_waitcnt lgkmcnt(0)
	s_barrier
	s_setprio 1
	v_mfma_f32_16x16x32_bf16 v[94:97], v[132:135], v[182:185], v[94:97]
	v_mfma_f32_16x16x32_bf16 v[90:93], v[140:143], v[182:185], v[90:93]
	v_mfma_f32_16x16x32_bf16 v[86:89], v[132:135], v[190:193], v[86:89]
	v_mfma_f32_16x16x32_bf16 v[82:85], v[140:143], v[190:193], v[82:85]
	v_mfma_f32_16x16x32_bf16 v[78:81], v[132:135], v[212:215], v[78:81]
	v_mfma_f32_16x16x32_bf16 v[74:77], v[140:143], v[212:215], v[74:77]
	v_mfma_f32_16x16x32_bf16 v[70:73], v[132:135], v[220:223], v[70:73]
	v_mfma_f32_16x16x32_bf16 v[66:69], v[140:143], v[220:223], v[66:69]
	v_mfma_f32_16x16x32_bf16 v[94:97], v[136:139], v[186:189], v[94:97]
	v_mfma_f32_16x16x32_bf16 v[90:93], v[156:159], v[186:189], v[90:93]
	v_mfma_f32_16x16x32_bf16 v[86:89], v[136:139], v[208:211], v[86:89]
	v_mfma_f32_16x16x32_bf16 v[82:85], v[156:159], v[208:211], v[82:85]
	v_mfma_f32_16x16x32_bf16 v[78:81], v[136:139], v[216:219], v[78:81]
	v_mfma_f32_16x16x32_bf16 v[74:77], v[156:159], v[216:219], v[74:77]
	v_mfma_f32_16x16x32_bf16 v[70:73], v[136:139], v[228:231], v[70:73]
	v_mfma_f32_16x16x32_bf16 v[66:69], v[156:159], v[228:231], v[66:69]
	v_mfma_f32_16x16x32_bf16 v[30:33], v[160:163], v[182:185], v[30:33]
	v_mfma_f32_16x16x32_bf16 v[26:29], v[174:177], v[182:185], v[26:29]
	v_mfma_f32_16x16x32_bf16 v[22:25], v[160:163], v[190:193], v[22:25]
	v_mfma_f32_16x16x32_bf16 v[18:21], v[174:177], v[190:193], v[18:21]
	v_mfma_f32_16x16x32_bf16 v[14:17], v[160:163], v[212:215], v[14:17]
	v_mfma_f32_16x16x32_bf16 v[10:13], v[174:177], v[212:215], v[10:13]
	v_mfma_f32_16x16x32_bf16 v[6:9], v[160:163], v[220:223], v[6:9]
	v_mfma_f32_16x16x32_bf16 v[2:5], v[174:177], v[220:223], v[2:5]
	v_mfma_f32_16x16x32_bf16 v[30:33], v[170:173], v[186:189], v[30:33]
	v_mfma_f32_16x16x32_bf16 v[26:29], v[178:181], v[186:189], v[26:29]
	v_mfma_f32_16x16x32_bf16 v[22:25], v[170:173], v[208:211], v[22:25]
	v_mfma_f32_16x16x32_bf16 v[18:21], v[178:181], v[208:211], v[18:21]
	v_mfma_f32_16x16x32_bf16 v[14:17], v[170:173], v[216:219], v[14:17]
	v_mfma_f32_16x16x32_bf16 v[10:13], v[178:181], v[216:219], v[10:13]
	v_mfma_f32_16x16x32_bf16 v[6:9], v[170:173], v[228:231], v[6:9]
	v_mfma_f32_16x16x32_bf16 v[2:5], v[178:181], v[228:231], v[2:5]
	s_setprio 0
	s_barrier
	s_add_u32 s2, s2, 0x100
	s_addc_u32 s3, s3, 0
	s_add_u32 s4, s4, 0x100
	s_addc_u32 s16, s16, 0
	s_cmp_ge_i32 s22, s71
	s_mov_b32 s17, s22
	s_cbranch_scc0 .LBB0_1209

; #define PG8_STAGE(bufoff, gbase, voff) do { _Pragma("unroll") for (int _i = 0; _i < 2; ++_i) \
;         __builtin_amdgcn_global_load_lds((const unsigned*)((const char*)(gbase) + (voff)[_i]), (PG8_LAS unsigned*)(lds + (bufoff) + ldsw + _i * 8192), 16, 0, 0); } while (0)
; #define PG8_LDA(dst, b, h) do { _Pragma("unroll") for (int m = 0; m < 4; ++m) _Pragma("unroll") for (int k = 0; k < 2; ++k) dst[m][k] = *(const PG8_LAS bf16x8*)(lds + PG8_SA(b, h) + aoff + m * 2048 + k * 1024); } while (0)
; #define PG8_LDB(dst, b, h) do { _Pragma("unroll") for (int n = 0; n < 2; ++n) _Pragma("unroll") for (int k = 0; k < 2; ++k) dst[n][k] = *(const PG8_LAS bf16x8*)(lds + PG8_SB(b, h) + boff + n * 2048 + k * 1024); } while (0)
; #define PG8_MMA(ai, bj, At, Bt) do { __builtin_amdgcn_s_setprio(1); _Pragma("unroll") for (int m = 0; m < 4; ++m) _Pragma("unroll") for (int n = 0; n < 2; ++n) _Pragma("unroll") for (int k = 0; k < 2; ++k) \
;         acc[ai][bj][m][n] = __builtin_amdgcn_mfma_f32_16x16x32_bf16(Bt[n][k], At[m][k], acc[ai][bj][m][n], 0, 0, 0); __builtin_amdgcn_s_setprio(0); } while (0)
; #define PG8_WAIT_V(n) asm volatile("s_waitcnt vmcnt(" #n ")" ::: "memory")
; #define PG8_WAIT_L(n) asm volatile("s_waitcnt lgkmcnt(" #n ")" ::: "memory")
; #define PG8_BAR __builtin_amdgcn_s_barrier()
; template <class Epi, class Sched, bool ALIGN_EPI = false, bool SP2 = false>
; __device__ __forceinline__ void gemm_phase(PG8_LAS unsigned char* lds, const Gemm g, const Sched& S, const Epi& E) {
;     ...
;             const char* a1 = cA + (size_t)(t + 1) * kstep;
;             const char* a2 = last ? nA : cA + (size_t)(t + 2) * kstep; const char* b2 = last ? nB : cB + (size_t)(t + 2) * kstep;
;             const char* a3 = a2 + kstep; const char* b3 = b2 + kstep;
;             if (last && has_next) S.a_ready(nxt);
;             if constexpr (SP2) {
;             PG8_LDB(B0, 0, 0); PG8_LDB(B1, 0, 1); PG8_SCHED; PG8_LDA(At, 0, 0); PG8_STAGE(PG8_SA(1, 1), a1 + hstep, voffA);
;             PG8_WAIT_V(8); PG8_WAIT_L(0); PG8_BAR; PG8_MMA(0, 0, At, B0); PG8_MMA(0, 1, At, B1); PG8_BAR; PG8_SCHED;
;             PG8_LDA(At, 0, 1); PG8_STAGE(PG8_SB(0, 0), b2, voffB); PG8_STAGE(PG8_SB(0, 1), b2 + hstep, voffB); PG8_STAGE(PG8_SA(0, 0), a2, voffA);
;             PG8_WAIT_V(8); PG8_WAIT_L(0); PG8_BAR; PG8_MMA(1, 0, At, B0); PG8_MMA(1, 1, At, B1); PG8_BAR; PG8_SCHED;
.LBB0_1392:
	s_add_i32 s22, s17, 2
	s_add_u32 s28, s62, s2
	s_addc_u32 s30, s63, s3
	s_add_u32 s28, s28, 0x100
	s_addc_u32 s30, s30, 0
	s_add_u32 s33, s4, s2
	s_addc_u32 s31, s16, s3
	s_add_i32 s36, 0, 0x10000
	s_cmp_eq_u32 s76, s17
	s_cselect_b32 s35, s59, s30
	s_cselect_b32 s34, s58, s28
	v_add_u32_e32 v98, s36, v151
	s_cselect_b32 s31, s61, s31
	s_cselect_b32 s30, s60, s33
	s_add_i32 s17, 0, 0x14000
	ds_read_b128 v[156:159], v98
	ds_read_b128 v[160:163], v98 offset:1024
	ds_read_b128 v[164:167], v98 offset:2048
	ds_read_b128 v[168:171], v98 offset:3072
	v_add_u32_e32 v98, s17, v151
	ds_read_b128 v[172:175], v98
	ds_read_b128 v[176:179], v98 offset:1024
	ds_read_b128 v[180:183], v98 offset:2048
	ds_read_b128 v[184:187], v98 offset:3072
	v_lshl_add_u64 v[100:101], v[146:147], 0, s[2:3]
	s_add_i32 m0, s68, 0xc000
	ds_read_b128 v[188:191], v155
	ds_read_b128 v[208:211], v155 offset:1024
	ds_read_b128 v[212:215], v155 offset:2048
	ds_read_b128 v[216:219], v155 offset:3072
	ds_read_b128 v[220:223], v155 offset:4096
	ds_read_b128 v[228:231], v155 offset:5120
	ds_read_b128 v[232:235], v155 offset:6144
	ds_read_b128 v[236:239], v155 offset:7168
	global_load_lds_dwordx4 v[100:101], off
	v_lshl_add_u64 v[100:101], v[148:149], 0, s[2:3]
	s_add_i32 m0, s68, 0xe000
	s_nop 0
	global_load_lds_dwordx4 v[100:101], off
	s_waitcnt vmcnt(8)
	s_waitcnt lgkmcnt(0)
	s_barrier
	s_setprio 1
	v_mfma_f32_16x16x32_bf16 v[126:129], v[156:159], v[188:191], v[126:129]
	v_mfma_f32_16x16x32_bf16 v[130:133], v[164:167], v[188:191], v[130:133]
	v_mfma_f32_16x16x32_bf16 v[114:117], v[156:159], v[212:215], v[114:117]
	v_mfma_f32_16x16x32_bf16 v[110:113], v[164:167], v[212:215], v[110:113]
	v_mfma_f32_16x16x32_bf16 v[94:97], v[156:159], v[220:223], v[94:97]
	v_mfma_f32_16x16x32_bf16 v[90:93], v[164:167], v[220:223], v[90:93]
	v_mfma_f32_16x16x32_bf16 v[78:81], v[156:159], v[232:235], v[78:81]
	v_mfma_f32_16x16x32_bf16 v[74:77], v[164:167], v[232:235], v[74:77]
	v_mfma_f32_16x16x32_bf16 v[126:129], v[160:163], v[208:211], v[126:129]
	v_mfma_f32_16x16x32_bf16 v[130:133], v[168:171], v[208:211], v[130:133]
	v_mfma_f32_16x16x32_bf16 v[114:117], v[160:163], v[216:219], v[114:117]
	v_mfma_f32_16x16x32_bf16 v[110:113], v[168:171], v[216:219], v[110:113]
	v_mfma_f32_16x16x32_bf16 v[94:97], v[160:163], v[228:231], v[94:97]
	v_mfma_f32_16x16x32_bf16 v[90:93], v[168:171], v[228:231], v[90:93]
	v_mfma_f32_16x16x32_bf16 v[78:81], v[160:163], v[236:239], v[78:81]
	v_mfma_f32_16x16x32_bf16 v[74:77], v[168:171], v[236:239], v[74:77]
	v_mfma_f32_16x16x32_bf16 v[122:125], v[172:175], v[188:191], v[122:125]
	v_mfma_f32_16x16x32_bf16 v[118:121], v[180:183], v[188:191], v[118:121]
	v_mfma_f32_16x16x32_bf16 v[106:109], v[172:175], v[212:215], v[106:109]
	v_mfma_f32_16x16x32_bf16 v[100:103], v[180:183], v[212:215], v[102:105]
	v_mfma_f32_16x16x32_bf16 v[86:89], v[172:175], v[220:223], v[86:89]
	v_mfma_f32_16x16x32_bf16 v[82:85], v[180:183], v[220:223], v[82:85]
	v_mfma_f32_16x16x32_bf16 v[70:73], v[172:175], v[232:235], v[70:73]
	v_mfma_f32_16x16x32_bf16 v[66:69], v[180:183], v[232:235], v[66:69]
	v_mfma_f32_16x16x32_bf16 v[122:125], v[176:179], v[208:211], v[122:125]
	v_mfma_f32_16x16x32_bf16 v[118:121], v[184:187], v[208:211], v[118:121]
	v_mfma_f32_16x16x32_bf16 v[106:109], v[176:179], v[216:219], v[106:109]
	v_mfma_f32_16x16x32_bf16 v[100:103], v[184:187], v[216:219], v[100:103]
	v_mfma_f32_16x16x32_bf16 v[86:89], v[176:179], v[228:231], v[86:89]
	v_mfma_f32_16x16x32_bf16 v[82:85], v[184:187], v[228:231], v[82:85]
	v_mfma_f32_16x16x32_bf16 v[70:73], v[176:179], v[236:239], v[70:73]
	v_mfma_f32_16x16x32_bf16 v[66:69], v[184:187], v[236:239], v[66:69]
	s_setprio 0
	s_barrier
	s_add_i32 s28, s36, s67
	v_lshl_add_u64 v[192:193], s[30:31], 0, v[136:137]
	s_mov_b32 m0, s28
	ds_read_b128 v[188:191], v155 offset:16384
	ds_read_b128 v[208:211], v155 offset:17408
	ds_read_b128 v[212:215], v155 offset:18432
	ds_read_b128 v[216:219], v155 offset:19456
	ds_read_b128 v[220:223], v155 offset:20480
	ds_read_b128 v[228:231], v155 offset:21504
	ds_read_b128 v[232:235], v155 offset:22528
	ds_read_b128 v[236:239], v155 offset:23552
	global_load_lds_dwordx4 v[192:193], off
	s_add_i32 m0, s28, 0x2000
	v_lshl_add_u64 v[224:225], s[30:31], 0, v[140:141]
	s_add_u32 s30, s30, s14
	s_addc_u32 s31, s31, s15
	s_add_i32 s17, s17, s67
	global_load_lds_dwordx4 v[224:225], off
	v_lshl_add_u64 v[240:241], s[30:31], 0, v[136:137]
	s_mov_b32 m0, s17
	v_lshl_add_u64 v[242:243], s[30:31], 0, v[140:141]
	global_load_lds_dwordx4 v[240:241], off
	s_add_i32 m0, s17, 0x2000
	v_lshl_add_u64 v[244:245], s[34:35], 0, v[134:135]
	global_load_lds_dwordx4 v[242:243], off
	s_mov_b32 m0, s68
	v_lshl_add_u64 v[246:247], s[34:35], 0, v[138:139]
	global_load_lds_dwordx4 v[244:245], off
	s_mov_b32 m0, s69
	s_nop 0
	global_load_lds_dwordx4 v[246:247], off
	s_waitcnt vmcnt(8)
	s_waitcnt lgkmcnt(0)
	s_barrier
; #define PG8_STAGE(bufoff, gbase, voff) do { _Pragma("unroll") for (int _i = 0; _i < 2; ++_i) \
;         __builtin_amdgcn_global_load_lds((const unsigned*)((const char*)(gbase) + (voff)[_i]), (PG8_LAS unsigned*)(lds + (bufoff) + ldsw + _i * 8192), 16, 0, 0); } while (0)
; #define PG8_LDA(dst, b, h) do { _Pragma("unroll") for (int m = 0; m < 4; ++m) _Pragma("unroll") for (int k = 0; k < 2; ++k) dst[m][k] = *(const PG8_LAS bf16x8*)(lds + PG8_SA(b, h) + aoff + m * 2048 + k * 1024); } while (0)
; #define PG8_LDB(dst, b, h) do { _Pragma("unroll") for (int n = 0; n < 2; ++n) _Pragma("unroll") for (int k = 0; k < 2; ++k) dst[n][k] = *(const PG8_LAS bf16x8*)(lds + PG8_SB(b, h) + boff + n * 2048 + k * 1024); } while (0)
; #define PG8_MMA(ai, bj, At, Bt) do { __builtin_amdgcn_s_setprio(1); _Pragma("unroll") for (int m = 0; m < 4; ++m) _Pragma("unroll") for (int n = 0; n < 2; ++n) _Pragma("unroll") for (int k = 0; k < 2; ++k) \
;         acc[ai][bj][m][n] = __builtin_amdgcn_mfma_f32_16x16x32_bf16(Bt[n][k], At[m][k], acc[ai][bj][m][n], 0, 0, 0); __builtin_amdgcn_s_setprio(0); } while (0)
; #define PG8_WAIT_V(n) asm volatile("s_waitcnt vmcnt(" #n ")" ::: "memory")
; #define PG8_WAIT_L(n) asm volatile("s_waitcnt lgkmcnt(" #n ")" ::: "memory")
; #define PG8_BAR __builtin_amdgcn_s_barrier()
; #define PG8_SCHED __builtin_amdgcn_sched_barrier(0)
; template <class Epi, class Sched, bool ALIGN_EPI = false, bool SP2 = false>
; __device__ __forceinline__ void gemm_phase(PG8_LAS unsigned char* lds, const Gemm g, const Sched& S, const Epi& E) {
;     ...
;             PG8_WAIT_V(8); PG8_WAIT_L(0); PG8_BAR; PG8_MMA(1, 0, At, B0); PG8_MMA(1, 1, At, B1); PG8_BAR; PG8_SCHED;
;             PG8_LDB(B0, 1, 0); PG8_LDB(B1, 1, 1); PG8_SCHED; PG8_LDA(At, 1, 0); PG8_STAGE(PG8_SA(0, 1), a2 + hstep, voffA);
;             PG8_WAIT_V(8); PG8_WAIT_L(0); PG8_BAR; PG8_MMA(0, 0, At, B0); PG8_MMA(0, 1, At, B1); PG8_BAR; PG8_SCHED;
	s_setprio 1
	v_mfma_f32_16x16x32_bf16 v[62:65], v[156:159], v[188:191], v[62:65]
	v_mfma_f32_16x16x32_bf16 v[58:61], v[164:167], v[188:191], v[58:61]
	v_mfma_f32_16x16x32_bf16 v[46:49], v[156:159], v[212:215], v[46:49]
	v_mfma_f32_16x16x32_bf16 v[42:45], v[164:167], v[212:215], v[42:45]
	v_mfma_f32_16x16x32_bf16 v[30:33], v[156:159], v[220:223], v[30:33]
	v_mfma_f32_16x16x32_bf16 v[26:29], v[164:167], v[220:223], v[26:29]
	v_mfma_f32_16x16x32_bf16 v[14:17], v[156:159], v[232:235], v[14:17]
	v_mfma_f32_16x16x32_bf16 v[10:13], v[164:167], v[232:235], v[10:13]
	v_mfma_f32_16x16x32_bf16 v[62:65], v[160:163], v[208:211], v[62:65]
	v_mfma_f32_16x16x32_bf16 v[58:61], v[168:171], v[208:211], v[58:61]
	v_mfma_f32_16x16x32_bf16 v[46:49], v[160:163], v[216:219], v[46:49]
	v_mfma_f32_16x16x32_bf16 v[42:45], v[168:171], v[216:219], v[42:45]
	v_mfma_f32_16x16x32_bf16 v[30:33], v[160:163], v[228:231], v[30:33]
	v_mfma_f32_16x16x32_bf16 v[26:29], v[168:171], v[228:231], v[26:29]
	v_mfma_f32_16x16x32_bf16 v[14:17], v[160:163], v[236:239], v[14:17]
	v_mfma_f32_16x16x32_bf16 v[10:13], v[168:171], v[236:239], v[10:13]
	v_mfma_f32_16x16x32_bf16 v[54:57], v[172:175], v[188:191], v[54:57]
	v_mfma_f32_16x16x32_bf16 v[50:53], v[180:183], v[188:191], v[50:53]
	v_mfma_f32_16x16x32_bf16 v[38:41], v[172:175], v[212:215], v[38:41]
	v_mfma_f32_16x16x32_bf16 v[34:37], v[180:183], v[212:215], v[34:37]
	v_mfma_f32_16x16x32_bf16 v[22:25], v[172:175], v[220:223], v[22:25]
	v_mfma_f32_16x16x32_bf16 v[18:21], v[180:183], v[220:223], v[18:21]
	v_mfma_f32_16x16x32_bf16 v[6:9], v[172:175], v[232:235], v[6:9]
	v_mfma_f32_16x16x32_bf16 v[2:5], v[180:183], v[232:235], v[2:5]
	v_mfma_f32_16x16x32_bf16 v[54:57], v[176:179], v[208:211], v[54:57]
	v_mfma_f32_16x16x32_bf16 v[50:53], v[184:187], v[208:211], v[50:53]
	v_mfma_f32_16x16x32_bf16 v[38:41], v[176:179], v[216:219], v[38:41]
	v_mfma_f32_16x16x32_bf16 v[34:37], v[184:187], v[216:219], v[34:37]
	v_mfma_f32_16x16x32_bf16 v[22:25], v[176:179], v[228:231], v[22:25]
	v_mfma_f32_16x16x32_bf16 v[18:21], v[184:187], v[228:231], v[18:21]
	v_mfma_f32_16x16x32_bf16 v[6:9], v[176:179], v[236:239], v[6:9]
	v_mfma_f32_16x16x32_bf16 v[2:5], v[184:187], v[236:239], v[2:5]
	s_setprio 0
	s_barrier
	s_add_i32 s17, 0, 0x18000
	v_add_u32_e32 v98, s17, v151
	s_add_i32 s28, 0, 0x1c000
	ds_read_b128 v[156:159], v98
	ds_read_b128 v[160:163], v98 offset:1024
	ds_read_b128 v[164:167], v98 offset:2048
	ds_read_b128 v[168:171], v98 offset:3072
	v_add_u32_e32 v98, s28, v151
	ds_read_b128 v[172:175], v98
	ds_read_b128 v[176:179], v98 offset:1024
	ds_read_b128 v[180:183], v98 offset:2048
	ds_read_b128 v[184:187], v98 offset:3072
	s_add_u32 s30, s34, s14
	s_addc_u32 s31, s35, s15
	s_mov_b32 m0, s70
	v_lshl_add_u64 v[104:105], s[30:31], 0, v[134:135]
	ds_read_b128 v[188:191], v155 offset:32768
	ds_read_b128 v[208:211], v155 offset:33792
	ds_read_b128 v[212:215], v155 offset:34816
	ds_read_b128 v[216:219], v155 offset:35840
	ds_read_b128 v[220:223], v155 offset:36864
	ds_read_b128 v[228:231], v155 offset:37888
	ds_read_b128 v[232:235], v155 offset:38912
	ds_read_b128 v[236:239], v155 offset:39936
	global_load_lds_dwordx4 v[104:105], off
	v_lshl_add_u64 v[104:105], s[30:31], 0, v[138:139]
	s_mov_b32 m0, s71
	s_nop 0
	global_load_lds_dwordx4 v[104:105], off
	s_waitcnt vmcnt(8)
	s_waitcnt lgkmcnt(0)
	s_barrier
	s_setprio 1
	v_mfma_f32_16x16x32_bf16 v[126:129], v[156:159], v[188:191], v[126:129]
	v_mfma_f32_16x16x32_bf16 v[130:133], v[164:167], v[188:191], v[130:133]
	v_mfma_f32_16x16x32_bf16 v[114:117], v[156:159], v[212:215], v[114:117]
	v_mfma_f32_16x16x32_bf16 v[110:113], v[164:167], v[212:215], v[110:113]
	v_mfma_f32_16x16x32_bf16 v[94:97], v[156:159], v[220:223], v[94:97]
	v_mfma_f32_16x16x32_bf16 v[90:93], v[164:167], v[220:223], v[90:93]
	v_mfma_f32_16x16x32_bf16 v[78:81], v[156:159], v[232:235], v[78:81]
	v_mfma_f32_16x16x32_bf16 v[74:77], v[164:167], v[232:235], v[74:77]
	v_mfma_f32_16x16x32_bf16 v[126:129], v[160:163], v[208:211], v[126:129]
	v_mfma_f32_16x16x32_bf16 v[130:133], v[168:171], v[208:211], v[130:133]
	v_mfma_f32_16x16x32_bf16 v[114:117], v[160:163], v[216:219], v[114:117]
	v_mfma_f32_16x16x32_bf16 v[110:113], v[168:171], v[216:219], v[110:113]
	v_mfma_f32_16x16x32_bf16 v[94:97], v[160:163], v[228:231], v[94:97]
	v_mfma_f32_16x16x32_bf16 v[90:93], v[168:171], v[228:231], v[90:93]
	v_mfma_f32_16x16x32_bf16 v[78:81], v[160:163], v[236:239], v[78:81]
	v_mfma_f32_16x16x32_bf16 v[74:77], v[168:171], v[236:239], v[74:77]
	v_mfma_f32_16x16x32_bf16 v[122:125], v[172:175], v[188:191], v[122:125]
	v_mfma_f32_16x16x32_bf16 v[118:121], v[180:183], v[188:191], v[118:121]
	v_mfma_f32_16x16x32_bf16 v[104:107], v[172:175], v[212:215], v[106:109]
	v_mfma_f32_16x16x32_bf16 v[100:103], v[180:183], v[212:215], v[100:103]
	v_mfma_f32_16x16x32_bf16 v[86:89], v[172:175], v[220:223], v[86:89]
	v_mfma_f32_16x16x32_bf16 v[82:85], v[180:183], v[220:223], v[82:85]
	v_mfma_f32_16x16x32_bf16 v[70:73], v[172:175], v[232:235], v[70:73]
	v_mfma_f32_16x16x32_bf16 v[66:69], v[180:183], v[232:235], v[66:69]
	v_mfma_f32_16x16x32_bf16 v[122:125], v[176:179], v[208:211], v[122:125]
	v_mfma_f32_16x16x32_bf16 v[118:121], v[184:187], v[208:211], v[118:121]
	v_mfma_f32_16x16x32_bf16 v[106:109], v[176:179], v[216:219], v[104:107]
	v_mfma_f32_16x16x32_bf16 v[102:105], v[184:187], v[216:219], v[100:103]
	v_mfma_f32_16x16x32_bf16 v[86:89], v[176:179], v[228:231], v[86:89]
	v_mfma_f32_16x16x32_bf16 v[82:85], v[184:187], v[228:231], v[82:85]
	v_mfma_f32_16x16x32_bf16 v[70:73], v[176:179], v[236:239], v[70:73]
	v_mfma_f32_16x16x32_bf16 v[66:69], v[184:187], v[236:239], v[66:69]
	s_setprio 0
	s_barrier
; #define PG8_STAGE(bufoff, gbase, voff) do { _Pragma("unroll") for (int _i = 0; _i < 2; ++_i) \
;         __builtin_amdgcn_global_load_lds((const unsigned*)((const char*)(gbase) + (voff)[_i]), (PG8_LAS unsigned*)(lds + (bufoff) + ldsw + _i * 8192), 16, 0, 0); } while (0)
; #define PG8_LDA(dst, b, h) do { _Pragma("unroll") for (int m = 0; m < 4; ++m) _Pragma("unroll") for (int k = 0; k < 2; ++k) dst[m][k] = *(const PG8_LAS bf16x8*)(lds + PG8_SA(b, h) + aoff + m * 2048 + k * 1024); } while (0)
; #define PG8_MMA(ai, bj, At, Bt) do { __builtin_amdgcn_s_setprio(1); _Pragma("unroll") for (int m = 0; m < 4; ++m) _Pragma("unroll") for (int n = 0; n < 2; ++n) _Pragma("unroll") for (int k = 0; k < 2; ++k) \
;         acc[ai][bj][m][n] = __builtin_amdgcn_mfma_f32_16x16x32_bf16(Bt[n][k], At[m][k], acc[ai][bj][m][n], 0, 0, 0); __builtin_amdgcn_s_setprio(0); } while (0)
; #define PG8_WAIT_V(n) asm volatile("s_waitcnt vmcnt(" #n ")" ::: "memory")
; #define PG8_WAIT_L(n) asm volatile("s_waitcnt lgkmcnt(" #n ")" ::: "memory")
; #define PG8_BAR __builtin_amdgcn_s_barrier()
; #define PG8_SCHED __builtin_amdgcn_sched_barrier(0)
; template <class Epi, class Sched, bool ALIGN_EPI = false, bool SP2 = false>
; __device__ __forceinline__ void gemm_phase(PG8_LAS unsigned char* lds, const Gemm g, const Sched& S, const Epi& E) {
;     ...
;         for (int t = 0; t < nt; t += 2) {
;     ...
;             PG8_LDA(At, 1, 1); PG8_STAGE(PG8_SB(1, 0), b3, voffB); PG8_STAGE(PG8_SB(1, 1), b3 + hstep, voffB); PG8_STAGE(PG8_SA(1, 0), a3, voffA);
;             PG8_WAIT_V(8); PG8_WAIT_L(0); PG8_BAR; PG8_MMA(1, 0, At, B0); PG8_MMA(1, 1, At, B1); PG8_BAR; PG8_SCHED;
	s_add_i32 s17, s17, s67
	v_lshl_add_u64 v[100:101], v[192:193], 0, s[24:25]
	s_mov_b32 m0, s17
	ds_read_b128 v[188:191], v155 offset:49152
	ds_read_b128 v[208:211], v155 offset:50176
	ds_read_b128 v[212:215], v155 offset:51200
	ds_read_b128 v[216:219], v155 offset:52224
	ds_read_b128 v[220:223], v155 offset:53248
	ds_read_b128 v[228:231], v155 offset:54272
	ds_read_b128 v[232:235], v155 offset:55296
	ds_read_b128 v[236:239], v155 offset:56320
	global_load_lds_dwordx4 v[100:101], off
	v_lshl_add_u64 v[100:101], v[224:225], 0, s[24:25]
	s_add_i32 m0, s17, 0x2000
	s_add_i32 s17, s28, s67
	global_load_lds_dwordx4 v[100:101], off
	v_lshl_add_u64 v[100:101], v[240:241], 0, s[24:25]
	s_mov_b32 m0, s17
	s_nop 0
	global_load_lds_dwordx4 v[100:101], off
	v_lshl_add_u64 v[100:101], v[242:243], 0, s[24:25]
	s_add_i32 m0, s17, 0x2000
	s_nop 0
	global_load_lds_dwordx4 v[100:101], off
	v_lshl_add_u64 v[100:101], v[244:245], 0, s[24:25]
	s_mov_b32 m0, s73
	s_nop 0
	global_load_lds_dwordx4 v[100:101], off
	v_lshl_add_u64 v[100:101], v[246:247], 0, s[24:25]
	s_mov_b32 m0, s74
	s_nop 0
	global_load_lds_dwordx4 v[100:101], off
	s_waitcnt vmcnt(8)
	s_waitcnt lgkmcnt(0)
	s_barrier
	s_setprio 1
	v_mfma_f32_16x16x32_bf16 v[62:65], v[156:159], v[188:191], v[62:65]
	v_mfma_f32_16x16x32_bf16 v[58:61], v[164:167], v[188:191], v[58:61]
	v_mfma_f32_16x16x32_bf16 v[46:49], v[156:159], v[212:215], v[46:49]
	v_mfma_f32_16x16x32_bf16 v[42:45], v[164:167], v[212:215], v[42:45]
	v_mfma_f32_16x16x32_bf16 v[30:33], v[156:159], v[220:223], v[30:33]
	v_mfma_f32_16x16x32_bf16 v[26:29], v[164:167], v[220:223], v[26:29]
	v_mfma_f32_16x16x32_bf16 v[14:17], v[156:159], v[232:235], v[14:17]
	v_mfma_f32_16x16x32_bf16 v[10:13], v[164:167], v[232:235], v[10:13]
	v_mfma_f32_16x16x32_bf16 v[62:65], v[160:163], v[208:211], v[62:65]
	v_mfma_f32_16x16x32_bf16 v[58:61], v[168:171], v[208:211], v[58:61]
	v_mfma_f32_16x16x32_bf16 v[46:49], v[160:163], v[216:219], v[46:49]
	v_mfma_f32_16x16x32_bf16 v[42:45], v[168:171], v[216:219], v[42:45]
	v_mfma_f32_16x16x32_bf16 v[30:33], v[160:163], v[228:231], v[30:33]
	v_mfma_f32_16x16x32_bf16 v[26:29], v[168:171], v[228:231], v[26:29]
	v_mfma_f32_16x16x32_bf16 v[14:17], v[160:163], v[236:239], v[14:17]
	v_mfma_f32_16x16x32_bf16 v[10:13], v[168:171], v[236:239], v[10:13]
	v_mfma_f32_16x16x32_bf16 v[54:57], v[172:175], v[188:191], v[54:57]
	v_mfma_f32_16x16x32_bf16 v[50:53], v[180:183], v[188:191], v[50:53]
	v_mfma_f32_16x16x32_bf16 v[38:41], v[172:175], v[212:215], v[38:41]
	v_mfma_f32_16x16x32_bf16 v[34:37], v[180:183], v[212:215], v[34:37]
	v_mfma_f32_16x16x32_bf16 v[22:25], v[172:175], v[220:223], v[22:25]
	v_mfma_f32_16x16x32_bf16 v[18:21], v[180:183], v[220:223], v[18:21]
	v_mfma_f32_16x16x32_bf16 v[6:9], v[172:175], v[232:235], v[6:9]
	v_mfma_f32_16x16x32_bf16 v[2:5], v[180:183], v[232:235], v[2:5]
	v_mfma_f32_16x16x32_bf16 v[54:57], v[176:179], v[208:211], v[54:57]
	v_mfma_f32_16x16x32_bf16 v[50:53], v[184:187], v[208:211], v[50:53]
	v_mfma_f32_16x16x32_bf16 v[38:41], v[176:179], v[216:219], v[38:41]
	v_mfma_f32_16x16x32_bf16 v[34:37], v[184:187], v[216:219], v[34:37]
	v_mfma_f32_16x16x32_bf16 v[22:25], v[176:179], v[228:231], v[22:25]
	v_mfma_f32_16x16x32_bf16 v[18:21], v[184:187], v[228:231], v[18:21]
	v_mfma_f32_16x16x32_bf16 v[6:9], v[176:179], v[236:239], v[6:9]
	v_mfma_f32_16x16x32_bf16 v[2:5], v[184:187], v[236:239], v[2:5]
	s_setprio 0
	s_barrier
	s_add_u32 s2, s2, 0x100
	s_addc_u32 s3, s3, 0
	s_cmp_ge_i32 s22, s72
	s_cbranch_scc0 .LBB0_1390

; #define PG8_STAGE(bufoff, gbase, voff) do { _Pragma("unroll") for (int _i = 0; _i < 2; ++_i) \
;         __builtin_amdgcn_global_load_lds((const unsigned*)((const char*)(gbase) + (voff)[_i]), (PG8_LAS unsigned*)(lds + (bufoff) + ldsw + _i * 8192), 16, 0, 0); } while (0)
; #define PG8_LDA(dst, b, h) do { _Pragma("unroll") for (int m = 0; m < 4; ++m) _Pragma("unroll") for (int k = 0; k < 2; ++k) dst[m][k] = *(const PG8_LAS bf16x8*)(lds + PG8_SA(b, h) + aoff + m * 2048 + k * 1024); } while (0)
; #define PG8_LDB(dst, b, h) do { _Pragma("unroll") for (int n = 0; n < 2; ++n) _Pragma("unroll") for (int k = 0; k < 2; ++k) dst[n][k] = *(const PG8_LAS bf16x8*)(lds + PG8_SB(b, h) + boff + n * 2048 + k * 1024); } while (0)
; #define PG8_MMA(ai, bj, At, Bt) do { __builtin_amdgcn_s_setprio(1); _Pragma("unroll") for (int m = 0; m < 4; ++m) _Pragma("unroll") for (int n = 0; n < 2; ++n) _Pragma("unroll") for (int k = 0; k < 2; ++k) \
;         acc[ai][bj][m][n] = __builtin_amdgcn_mfma_f32_16x16x32_bf16(Bt[n][k], At[m][k], acc[ai][bj][m][n], 0, 0, 0); __builtin_amdgcn_s_setprio(0); } while (0)
; #define PG8_WAIT_V(n) asm volatile("s_waitcnt vmcnt(" #n ")" ::: "memory")
; #define PG8_WAIT_L(n) asm volatile("s_waitcnt lgkmcnt(" #n ")" ::: "memory")
; template <class Epi, class Sched, bool ALIGN_EPI = false, bool SP2 = false>
; __device__ __forceinline__ void gemm_phase(PG8_LAS unsigned char* lds, const Gemm g, const Sched& S, const Epi& E) {
;     ...
;         for (int t = 0; t < nt; t += 2) {
;             if constexpr (Epi::MID) { if (t == (nt >> 1)) E.mid(acc, wr, fr, lds); }
;             const bool last = (t == nt - 2);
;             const char* a1 = cA + (size_t)(t + 1) * kstep;
;             const char* a2 = last ? nA : cA + (size_t)(t + 2) * kstep; const char* b2 = last ? nB : cB + (size_t)(t + 2) * kstep;
;             const char* a3 = a2 + kstep; const char* b3 = b2 + kstep;
;             if (last && has_next) S.a_ready(nxt);
;             if constexpr (SP2) {
;             PG8_LDB(B0, 0, 0); PG8_LDB(B1, 0, 1); PG8_SCHED; PG8_LDA(At, 0, 0); PG8_STAGE(PG8_SA(1, 1), a1 + hstep, voffA);
;             PG8_WAIT_V(8); PG8_WAIT_L(0); PG8_BAR; PG8_MMA(0, 0, At, B0); PG8_MMA(0, 1, At, B1); PG8_BAR; PG8_SCHED;
;             PG8_LDA(At, 0, 1); PG8_STAGE(PG8_SB(0, 0), b2, voffB); PG8_STAGE(PG8_SB(0, 1), b2 + hstep, voffB); PG8_STAGE(PG8_SA(0, 0), a2, voffA);
.LBB0_1483:
	s_add_i32 s22, s17, 2
	s_add_u32 s28, s2, 0x80
	s_addc_u32 s30, s3, 0
	s_add_i32 s33, 0, 0x10000
	s_cmp_eq_u32 s70, s17
	s_cselect_b32 s35, s51, s30
	s_cselect_b32 s34, s50, s28
	v_add_u32_e32 v146, s33, v148
	s_cselect_b32 s31, s53, s16
	s_cselect_b32 s30, s52, s4
	s_add_i32 s17, 0, 0x14000
	ds_read_b128 v[142:145], v146
	ds_read_b128 v[154:157], v146 offset:1024
	ds_read_b128 v[158:161], v146 offset:2048
	ds_read_b128 v[162:165], v146 offset:3072
	v_add_u32_e32 v146, s17, v148
	ds_read_b128 v[166:169], v146
	ds_read_b128 v[170:173], v146 offset:1024
	ds_read_b128 v[174:177], v146 offset:2048
	ds_read_b128 v[178:181], v146 offset:3072
	v_lshl_add_u64 v[146:147], s[2:3], 0, v[138:139]
	s_add_i32 m0, s64, 0xc000
	ds_read_b128 v[182:185], v153
	ds_read_b128 v[186:189], v153 offset:1024
	ds_read_b128 v[190:193], v153 offset:2048
	ds_read_b128 v[208:211], v153 offset:3072
	ds_read_b128 v[212:215], v153 offset:4096
	ds_read_b128 v[216:219], v153 offset:5120
	ds_read_b128 v[220:223], v153 offset:6144
	ds_read_b128 v[228:231], v153 offset:7168
	global_load_lds_dwordx4 v[146:147], off
	v_lshl_add_u64 v[146:147], s[2:3], 0, v[140:141]
	s_add_i32 m0, s64, 0xe000
	s_nop 0
	global_load_lds_dwordx4 v[146:147], off
	s_waitcnt vmcnt(8)
	s_waitcnt lgkmcnt(0)
	s_barrier
	s_setprio 1
	v_mfma_f32_16x16x32_bf16 v[124:127], v[142:145], v[182:185], v[124:127]
	v_mfma_f32_16x16x32_bf16 v[120:123], v[158:161], v[182:185], v[120:123]
	v_mfma_f32_16x16x32_bf16 v[112:115], v[142:145], v[190:193], v[112:115]
	v_mfma_f32_16x16x32_bf16 v[104:107], v[158:161], v[190:193], v[104:107]
	v_mfma_f32_16x16x32_bf16 v[94:97], v[142:145], v[212:215], v[94:97]
	v_mfma_f32_16x16x32_bf16 v[86:89], v[158:161], v[212:215], v[86:89]
	v_mfma_f32_16x16x32_bf16 v[78:81], v[142:145], v[220:223], v[78:81]
	v_mfma_f32_16x16x32_bf16 v[70:73], v[158:161], v[220:223], v[70:73]
	v_mfma_f32_16x16x32_bf16 v[124:127], v[154:157], v[186:189], v[124:127]
	v_mfma_f32_16x16x32_bf16 v[120:123], v[162:165], v[186:189], v[120:123]
	v_mfma_f32_16x16x32_bf16 v[112:115], v[154:157], v[208:211], v[112:115]
	v_mfma_f32_16x16x32_bf16 v[104:107], v[162:165], v[208:211], v[104:107]
	v_mfma_f32_16x16x32_bf16 v[94:97], v[154:157], v[216:219], v[94:97]
	v_mfma_f32_16x16x32_bf16 v[86:89], v[162:165], v[216:219], v[86:89]
	v_mfma_f32_16x16x32_bf16 v[78:81], v[154:157], v[228:231], v[78:81]
	v_mfma_f32_16x16x32_bf16 v[70:73], v[162:165], v[228:231], v[70:73]
	v_mfma_f32_16x16x32_bf16 v[128:131], v[166:169], v[182:185], v[128:131]
	v_mfma_f32_16x16x32_bf16 v[116:119], v[174:177], v[182:185], v[116:119]
	v_mfma_f32_16x16x32_bf16 v[108:111], v[166:169], v[190:193], v[108:111]
	v_mfma_f32_16x16x32_bf16 v[100:103], v[174:177], v[190:193], v[100:103]
	v_mfma_f32_16x16x32_bf16 v[90:93], v[166:169], v[212:215], v[90:93]
	v_mfma_f32_16x16x32_bf16 v[82:85], v[174:177], v[212:215], v[82:85]
	v_mfma_f32_16x16x32_bf16 v[74:77], v[166:169], v[220:223], v[74:77]
	v_mfma_f32_16x16x32_bf16 v[66:69], v[174:177], v[220:223], v[66:69]
	v_mfma_f32_16x16x32_bf16 v[128:131], v[170:173], v[186:189], v[128:131]
	v_mfma_f32_16x16x32_bf16 v[116:119], v[178:181], v[186:189], v[116:119]
	v_mfma_f32_16x16x32_bf16 v[108:111], v[170:173], v[208:211], v[108:111]
	v_mfma_f32_16x16x32_bf16 v[100:103], v[178:181], v[208:211], v[100:103]
	v_mfma_f32_16x16x32_bf16 v[90:93], v[170:173], v[216:219], v[90:93]
	v_mfma_f32_16x16x32_bf16 v[82:85], v[178:181], v[216:219], v[82:85]
	v_mfma_f32_16x16x32_bf16 v[74:77], v[170:173], v[228:231], v[74:77]
	v_mfma_f32_16x16x32_bf16 v[66:69], v[178:181], v[228:231], v[66:69]
	s_setprio 0
	s_barrier
	s_add_i32 s28, s33, s57
	v_lshl_add_u64 v[146:147], s[30:31], 0, v[98:99]
	s_mov_b32 m0, s28
	ds_read_b128 v[182:185], v153 offset:16384
	ds_read_b128 v[186:189], v153 offset:17408
	ds_read_b128 v[190:193], v153 offset:18432
	ds_read_b128 v[208:211], v153 offset:19456
	ds_read_b128 v[212:215], v153 offset:20480
	ds_read_b128 v[216:219], v153 offset:21504
	ds_read_b128 v[220:223], v153 offset:22528
	ds_read_b128 v[228:231], v153 offset:23552
	global_load_lds_dwordx4 v[146:147], off
	s_add_i32 m0, s28, 0x2000
	v_lshl_add_u64 v[224:225], s[30:31], 0, v[132:133]
	s_add_u32 s30, s30, s8
	s_addc_u32 s31, s31, s9
	s_add_i32 s17, s17, s57
	global_load_lds_dwordx4 v[224:225], off
	v_lshl_add_u64 v[232:233], s[30:31], 0, v[98:99]
	s_mov_b32 m0, s17
	v_lshl_add_u64 v[234:235], s[30:31], 0, v[132:133]
	global_load_lds_dwordx4 v[232:233], off
	s_add_i32 m0, s17, 0x2000
	v_lshl_add_u64 v[236:237], s[34:35], 0, v[136:137]
	global_load_lds_dwordx4 v[234:235], off
	s_mov_b32 m0, s64
	v_lshl_add_u64 v[238:239], s[34:35], 0, v[134:135]
	global_load_lds_dwordx4 v[236:237], off
	s_mov_b32 m0, s65
	s_nop 0
	global_load_lds_dwordx4 v[238:239], off
	s_waitcnt vmcnt(8)
	s_waitcnt lgkmcnt(0)
	s_barrier
; #define PG8_STAGE(bufoff, gbase, voff) do { _Pragma("unroll") for (int _i = 0; _i < 2; ++_i) \
;         __builtin_amdgcn_global_load_lds((const unsigned*)((const char*)(gbase) + (voff)[_i]), (PG8_LAS unsigned*)(lds + (bufoff) + ldsw + _i * 8192), 16, 0, 0); } while (0)
; #define PG8_LDA(dst, b, h) do { _Pragma("unroll") for (int m = 0; m < 4; ++m) _Pragma("unroll") for (int k = 0; k < 2; ++k) dst[m][k] = *(const PG8_LAS bf16x8*)(lds + PG8_SA(b, h) + aoff + m * 2048 + k * 1024); } while (0)
; #define PG8_LDB(dst, b, h) do { _Pragma("unroll") for (int n = 0; n < 2; ++n) _Pragma("unroll") for (int k = 0; k < 2; ++k) dst[n][k] = *(const PG8_LAS bf16x8*)(lds + PG8_SB(b, h) + boff + n * 2048 + k * 1024); } while (0)
; #define PG8_MMA(ai, bj, At, Bt) do { __builtin_amdgcn_s_setprio(1); _Pragma("unroll") for (int m = 0; m < 4; ++m) _Pragma("unroll") for (int n = 0; n < 2; ++n) _Pragma("unroll") for (int k = 0; k < 2; ++k) \
;         acc[ai][bj][m][n] = __builtin_amdgcn_mfma_f32_16x16x32_bf16(Bt[n][k], At[m][k], acc[ai][bj][m][n], 0, 0, 0); __builtin_amdgcn_s_setprio(0); } while (0)
; #define PG8_WAIT_V(n) asm volatile("s_waitcnt vmcnt(" #n ")" ::: "memory")
; #define PG8_WAIT_L(n) asm volatile("s_waitcnt lgkmcnt(" #n ")" ::: "memory")
; #define PG8_BAR __builtin_amdgcn_s_barrier()
; #define PG8_SCHED __builtin_amdgcn_sched_barrier(0)
; template <class Epi, class Sched, bool ALIGN_EPI = false, bool SP2 = false>
; __device__ __forceinline__ void gemm_phase(PG8_LAS unsigned char* lds, const Gemm g, const Sched& S, const Epi& E) {
;     ...
;             PG8_WAIT_V(8); PG8_WAIT_L(0); PG8_BAR; PG8_MMA(1, 0, At, B0); PG8_MMA(1, 1, At, B1); PG8_BAR; PG8_SCHED;
;             PG8_LDB(B0, 1, 0); PG8_LDB(B1, 1, 1); PG8_SCHED; PG8_LDA(At, 1, 0); PG8_STAGE(PG8_SA(0, 1), a2 + hstep, voffA);
;             PG8_WAIT_V(8); PG8_WAIT_L(0); PG8_BAR; PG8_MMA(0, 0, At, B0); PG8_MMA(0, 1, At, B1); PG8_BAR; PG8_SCHED;
	s_setprio 1
	v_mfma_f32_16x16x32_bf16 v[62:65], v[142:145], v[182:185], v[62:65]
	v_mfma_f32_16x16x32_bf16 v[54:57], v[158:161], v[182:185], v[54:57]
	v_mfma_f32_16x16x32_bf16 v[46:49], v[142:145], v[190:193], v[46:49]
	v_mfma_f32_16x16x32_bf16 v[38:41], v[158:161], v[190:193], v[38:41]
	v_mfma_f32_16x16x32_bf16 v[30:33], v[142:145], v[212:215], v[30:33]
	v_mfma_f32_16x16x32_bf16 v[22:25], v[158:161], v[212:215], v[22:25]
	v_mfma_f32_16x16x32_bf16 v[14:17], v[142:145], v[220:223], v[14:17]
	v_mfma_f32_16x16x32_bf16 v[6:9], v[158:161], v[220:223], v[6:9]
	v_mfma_f32_16x16x32_bf16 v[62:65], v[154:157], v[186:189], v[62:65]
	v_mfma_f32_16x16x32_bf16 v[54:57], v[162:165], v[186:189], v[54:57]
	v_mfma_f32_16x16x32_bf16 v[46:49], v[154:157], v[208:211], v[46:49]
	v_mfma_f32_16x16x32_bf16 v[38:41], v[162:165], v[208:211], v[38:41]
	v_mfma_f32_16x16x32_bf16 v[30:33], v[154:157], v[216:219], v[30:33]
	v_mfma_f32_16x16x32_bf16 v[22:25], v[162:165], v[216:219], v[22:25]
	v_mfma_f32_16x16x32_bf16 v[14:17], v[154:157], v[228:231], v[14:17]
	v_mfma_f32_16x16x32_bf16 v[6:9], v[162:165], v[228:231], v[6:9]
	v_mfma_f32_16x16x32_bf16 v[58:61], v[166:169], v[182:185], v[58:61]
	v_mfma_f32_16x16x32_bf16 v[50:53], v[174:177], v[182:185], v[50:53]
	v_mfma_f32_16x16x32_bf16 v[42:45], v[166:169], v[190:193], v[42:45]
	v_mfma_f32_16x16x32_bf16 v[34:37], v[174:177], v[190:193], v[34:37]
	v_mfma_f32_16x16x32_bf16 v[26:29], v[166:169], v[212:215], v[26:29]
	v_mfma_f32_16x16x32_bf16 v[18:21], v[174:177], v[212:215], v[18:21]
	v_mfma_f32_16x16x32_bf16 v[10:13], v[166:169], v[220:223], v[10:13]
	v_mfma_f32_16x16x32_bf16 v[2:5], v[174:177], v[220:223], v[2:5]
	v_mfma_f32_16x16x32_bf16 v[58:61], v[170:173], v[186:189], v[58:61]
	v_mfma_f32_16x16x32_bf16 v[50:53], v[178:181], v[186:189], v[50:53]
	v_mfma_f32_16x16x32_bf16 v[42:45], v[170:173], v[208:211], v[42:45]
	v_mfma_f32_16x16x32_bf16 v[34:37], v[178:181], v[208:211], v[34:37]
	v_mfma_f32_16x16x32_bf16 v[26:29], v[170:173], v[216:219], v[26:29]
	v_mfma_f32_16x16x32_bf16 v[18:21], v[178:181], v[216:219], v[18:21]
	v_mfma_f32_16x16x32_bf16 v[10:13], v[170:173], v[228:231], v[10:13]
	v_mfma_f32_16x16x32_bf16 v[2:5], v[178:181], v[228:231], v[2:5]
	s_setprio 0
	s_barrier
	s_add_i32 s17, 0, 0x18000
	s_add_i32 s28, 0, 0x1c000
	v_add_u32_e32 v162, s17, v148
	v_add_u32_e32 v178, s28, v148
	ds_read_b128 v[142:145], v162
	ds_read_b128 v[154:157], v162 offset:1024
	ds_read_b128 v[158:161], v162 offset:2048
	ds_read_b128 v[162:165], v162 offset:3072
	ds_read_b128 v[166:169], v178
	ds_read_b128 v[170:173], v178 offset:1024
	ds_read_b128 v[174:177], v178 offset:2048
	ds_read_b128 v[178:181], v178 offset:3072
	s_add_u32 s30, s34, s8
	s_addc_u32 s31, s35, s9
	s_mov_b32 m0, s66
	v_lshl_add_u64 v[240:241], s[30:31], 0, v[136:137]
	ds_read_b128 v[182:185], v153 offset:32768
	ds_read_b128 v[186:189], v153 offset:33792
	ds_read_b128 v[190:193], v153 offset:34816
	ds_read_b128 v[208:211], v153 offset:35840
	ds_read_b128 v[212:215], v153 offset:36864
	ds_read_b128 v[216:219], v153 offset:37888
	ds_read_b128 v[220:223], v153 offset:38912
	ds_read_b128 v[228:231], v153 offset:39936
	global_load_lds_dwordx4 v[240:241], off
	v_lshl_add_u64 v[240:241], s[30:31], 0, v[134:135]
	s_mov_b32 m0, s67
	s_nop 0
	global_load_lds_dwordx4 v[240:241], off
	s_waitcnt vmcnt(8)
	s_waitcnt lgkmcnt(0)
	s_barrier
	s_setprio 1
	v_mfma_f32_16x16x32_bf16 v[124:127], v[142:145], v[182:185], v[124:127]
	v_mfma_f32_16x16x32_bf16 v[120:123], v[158:161], v[182:185], v[120:123]
	v_mfma_f32_16x16x32_bf16 v[112:115], v[142:145], v[190:193], v[112:115]
	v_mfma_f32_16x16x32_bf16 v[104:107], v[158:161], v[190:193], v[104:107]
	v_mfma_f32_16x16x32_bf16 v[94:97], v[142:145], v[212:215], v[94:97]
	v_mfma_f32_16x16x32_bf16 v[86:89], v[158:161], v[212:215], v[86:89]
	v_mfma_f32_16x16x32_bf16 v[78:81], v[142:145], v[220:223], v[78:81]
	v_mfma_f32_16x16x32_bf16 v[70:73], v[158:161], v[220:223], v[70:73]
	v_mfma_f32_16x16x32_bf16 v[124:127], v[154:157], v[186:189], v[124:127]
	v_mfma_f32_16x16x32_bf16 v[120:123], v[162:165], v[186:189], v[120:123]
	v_mfma_f32_16x16x32_bf16 v[112:115], v[154:157], v[208:211], v[112:115]
	v_mfma_f32_16x16x32_bf16 v[104:107], v[162:165], v[208:211], v[104:107]
	v_mfma_f32_16x16x32_bf16 v[94:97], v[154:157], v[216:219], v[94:97]
	v_mfma_f32_16x16x32_bf16 v[86:89], v[162:165], v[216:219], v[86:89]
	v_mfma_f32_16x16x32_bf16 v[78:81], v[154:157], v[228:231], v[78:81]
	v_mfma_f32_16x16x32_bf16 v[70:73], v[162:165], v[228:231], v[70:73]
	v_mfma_f32_16x16x32_bf16 v[128:131], v[166:169], v[182:185], v[128:131]
	v_mfma_f32_16x16x32_bf16 v[116:119], v[174:177], v[182:185], v[116:119]
	v_mfma_f32_16x16x32_bf16 v[108:111], v[166:169], v[190:193], v[108:111]
	v_mfma_f32_16x16x32_bf16 v[100:103], v[174:177], v[190:193], v[100:103]
	v_mfma_f32_16x16x32_bf16 v[90:93], v[166:169], v[212:215], v[90:93]
	v_mfma_f32_16x16x32_bf16 v[82:85], v[174:177], v[212:215], v[82:85]
	v_mfma_f32_16x16x32_bf16 v[74:77], v[166:169], v[220:223], v[74:77]
	v_mfma_f32_16x16x32_bf16 v[66:69], v[174:177], v[220:223], v[66:69]
	v_mfma_f32_16x16x32_bf16 v[128:131], v[170:173], v[186:189], v[128:131]
	v_mfma_f32_16x16x32_bf16 v[116:119], v[178:181], v[186:189], v[116:119]
	v_mfma_f32_16x16x32_bf16 v[108:111], v[170:173], v[208:211], v[108:111]
	v_mfma_f32_16x16x32_bf16 v[100:103], v[178:181], v[208:211], v[100:103]
	v_mfma_f32_16x16x32_bf16 v[90:93], v[170:173], v[216:219], v[90:93]
	v_mfma_f32_16x16x32_bf16 v[82:85], v[178:181], v[216:219], v[82:85]
	v_mfma_f32_16x16x32_bf16 v[74:77], v[170:173], v[228:231], v[74:77]
	v_mfma_f32_16x16x32_bf16 v[66:69], v[178:181], v[228:231], v[66:69]
	s_setprio 0
	s_barrier
; #define PG8_STAGE(bufoff, gbase, voff) do { _Pragma("unroll") for (int _i = 0; _i < 2; ++_i) \
;         __builtin_amdgcn_global_load_lds((const unsigned*)((const char*)(gbase) + (voff)[_i]), (PG8_LAS unsigned*)(lds + (bufoff) + ldsw + _i * 8192), 16, 0, 0); } while (0)
; #define PG8_LDA(dst, b, h) do { _Pragma("unroll") for (int m = 0; m < 4; ++m) _Pragma("unroll") for (int k = 0; k < 2; ++k) dst[m][k] = *(const PG8_LAS bf16x8*)(lds + PG8_SA(b, h) + aoff + m * 2048 + k * 1024); } while (0)
; #define PG8_MMA(ai, bj, At, Bt) do { __builtin_amdgcn_s_setprio(1); _Pragma("unroll") for (int m = 0; m < 4; ++m) _Pragma("unroll") for (int n = 0; n < 2; ++n) _Pragma("unroll") for (int k = 0; k < 2; ++k) \
;         acc[ai][bj][m][n] = __builtin_amdgcn_mfma_f32_16x16x32_bf16(Bt[n][k], At[m][k], acc[ai][bj][m][n], 0, 0, 0); __builtin_amdgcn_s_setprio(0); } while (0)
; #define PG8_WAIT_V(n) asm volatile("s_waitcnt vmcnt(" #n ")" ::: "memory")
; #define PG8_WAIT_L(n) asm volatile("s_waitcnt lgkmcnt(" #n ")" ::: "memory")
; #define PG8_BAR __builtin_amdgcn_s_barrier()
; #define PG8_SCHED __builtin_amdgcn_sched_barrier(0)
; template <class Epi, class Sched, bool ALIGN_EPI = false, bool SP2 = false>
; __device__ __forceinline__ void gemm_phase(PG8_LAS unsigned char* lds, const Gemm g, const Sched& S, const Epi& E) {
;     ...
;         for (int t = 0; t < nt; t += 2) {
;     ...
;             PG8_LDA(At, 1, 1); PG8_STAGE(PG8_SB(1, 0), b3, voffB); PG8_STAGE(PG8_SB(1, 1), b3 + hstep, voffB); PG8_STAGE(PG8_SA(1, 0), a3, voffA);
;             PG8_WAIT_V(8); PG8_WAIT_L(0); PG8_BAR; PG8_MMA(1, 0, At, B0); PG8_MMA(1, 1, At, B1); PG8_BAR; PG8_SCHED;
	s_add_i32 s17, s17, s57
	v_lshl_add_u64 v[146:147], v[146:147], 0, s[24:25]
	s_mov_b32 m0, s17
	ds_read_b128 v[182:185], v153 offset:49152
	ds_read_b128 v[186:189], v153 offset:50176
	ds_read_b128 v[190:193], v153 offset:51200
	ds_read_b128 v[208:211], v153 offset:52224
	ds_read_b128 v[212:215], v153 offset:53248
	ds_read_b128 v[216:219], v153 offset:54272
	ds_read_b128 v[220:223], v153 offset:55296
	ds_read_b128 v[228:231], v153 offset:56320
	global_load_lds_dwordx4 v[146:147], off
	v_lshl_add_u64 v[146:147], v[224:225], 0, s[24:25]
	s_add_i32 m0, s17, 0x2000
	s_add_i32 s17, s28, s57
	global_load_lds_dwordx4 v[146:147], off
	v_lshl_add_u64 v[146:147], v[232:233], 0, s[24:25]
	s_mov_b32 m0, s17
	s_nop 0
	global_load_lds_dwordx4 v[146:147], off
	v_lshl_add_u64 v[146:147], v[234:235], 0, s[24:25]
	s_add_i32 m0, s17, 0x2000
	s_nop 0
	global_load_lds_dwordx4 v[146:147], off
	v_lshl_add_u64 v[146:147], v[236:237], 0, s[24:25]
	s_mov_b32 m0, s68
	s_nop 0
	global_load_lds_dwordx4 v[146:147], off
	v_lshl_add_u64 v[146:147], v[238:239], 0, s[24:25]
	s_mov_b32 m0, s69
	s_nop 0
	global_load_lds_dwordx4 v[146:147], off
	s_waitcnt vmcnt(8)
	s_waitcnt lgkmcnt(0)
	s_barrier
	s_setprio 1
	v_mfma_f32_16x16x32_bf16 v[62:65], v[142:145], v[182:185], v[62:65]
	v_mfma_f32_16x16x32_bf16 v[54:57], v[158:161], v[182:185], v[54:57]
	v_mfma_f32_16x16x32_bf16 v[46:49], v[142:145], v[190:193], v[46:49]
	v_mfma_f32_16x16x32_bf16 v[38:41], v[158:161], v[190:193], v[38:41]
	v_mfma_f32_16x16x32_bf16 v[30:33], v[142:145], v[212:215], v[30:33]
	v_mfma_f32_16x16x32_bf16 v[22:25], v[158:161], v[212:215], v[22:25]
	v_mfma_f32_16x16x32_bf16 v[14:17], v[142:145], v[220:223], v[14:17]
	v_mfma_f32_16x16x32_bf16 v[6:9], v[158:161], v[220:223], v[6:9]
	v_mfma_f32_16x16x32_bf16 v[62:65], v[154:157], v[186:189], v[62:65]
	v_mfma_f32_16x16x32_bf16 v[54:57], v[162:165], v[186:189], v[54:57]
	v_mfma_f32_16x16x32_bf16 v[46:49], v[154:157], v[208:211], v[46:49]
	v_mfma_f32_16x16x32_bf16 v[38:41], v[162:165], v[208:211], v[38:41]
	v_mfma_f32_16x16x32_bf16 v[30:33], v[154:157], v[216:219], v[30:33]
	v_mfma_f32_16x16x32_bf16 v[22:25], v[162:165], v[216:219], v[22:25]
	v_mfma_f32_16x16x32_bf16 v[14:17], v[154:157], v[228:231], v[14:17]
	v_mfma_f32_16x16x32_bf16 v[6:9], v[162:165], v[228:231], v[6:9]
	v_mfma_f32_16x16x32_bf16 v[58:61], v[166:169], v[182:185], v[58:61]
	v_mfma_f32_16x16x32_bf16 v[50:53], v[174:177], v[182:185], v[50:53]
	v_mfma_f32_16x16x32_bf16 v[42:45], v[166:169], v[190:193], v[42:45]
	v_mfma_f32_16x16x32_bf16 v[34:37], v[174:177], v[190:193], v[34:37]
	v_mfma_f32_16x16x32_bf16 v[26:29], v[166:169], v[212:215], v[26:29]
	v_mfma_f32_16x16x32_bf16 v[18:21], v[174:177], v[212:215], v[18:21]
	v_mfma_f32_16x16x32_bf16 v[10:13], v[166:169], v[220:223], v[10:13]
	v_mfma_f32_16x16x32_bf16 v[2:5], v[174:177], v[220:223], v[2:5]
	v_mfma_f32_16x16x32_bf16 v[58:61], v[170:173], v[186:189], v[58:61]
	v_mfma_f32_16x16x32_bf16 v[50:53], v[178:181], v[186:189], v[50:53]
	v_mfma_f32_16x16x32_bf16 v[42:45], v[170:173], v[208:211], v[42:45]
	v_mfma_f32_16x16x32_bf16 v[34:37], v[178:181], v[208:211], v[34:37]
	v_mfma_f32_16x16x32_bf16 v[26:29], v[170:173], v[216:219], v[26:29]
	v_mfma_f32_16x16x32_bf16 v[18:21], v[178:181], v[216:219], v[18:21]
	v_mfma_f32_16x16x32_bf16 v[10:13], v[170:173], v[228:231], v[10:13]
	v_mfma_f32_16x16x32_bf16 v[2:5], v[178:181], v[228:231], v[2:5]
	s_setprio 0
	s_barrier
	s_add_u32 s2, s2, 0x100
	s_addc_u32 s3, s3, 0
	s_add_u32 s4, s4, 0x100
	s_addc_u32 s16, s16, 0
	s_cmp_ge_i32 s22, s18
	s_mov_b32 s17, s22
	s_cbranch_scc0 .LBB0_1483

; #define PG8_STAGE(bufoff, gbase, voff) do { _Pragma("unroll") for (int _i = 0; _i < 2; ++_i) \
;         __builtin_amdgcn_global_load_lds((const unsigned*)((const char*)(gbase) + (voff)[_i]), (PG8_LAS unsigned*)(lds + (bufoff) + ldsw + _i * 8192), 16, 0, 0); } while (0)
; #define PG8_LDA(dst, b, h) do { _Pragma("unroll") for (int m = 0; m < 4; ++m) _Pragma("unroll") for (int k = 0; k < 2; ++k) dst[m][k] = *(const PG8_LAS bf16x8*)(lds + PG8_SA(b, h) + aoff + m * 2048 + k * 1024); } while (0)
; #define PG8_LDB(dst, b, h) do { _Pragma("unroll") for (int n = 0; n < 2; ++n) _Pragma("unroll") for (int k = 0; k < 2; ++k) dst[n][k] = *(const PG8_LAS bf16x8*)(lds + PG8_SB(b, h) + boff + n * 2048 + k * 1024); } while (0)
; #define PG8_MMA(ai, bj, At, Bt) do { __builtin_amdgcn_s_setprio(1); _Pragma("unroll") for (int m = 0; m < 4; ++m) _Pragma("unroll") for (int n = 0; n < 2; ++n) _Pragma("unroll") for (int k = 0; k < 2; ++k) \
;         acc[ai][bj][m][n] = __builtin_amdgcn_mfma_f32_16x16x32_bf16(Bt[n][k], At[m][k], acc[ai][bj][m][n], 0, 0, 0); __builtin_amdgcn_s_setprio(0); } while (0)
; #define PG8_WAIT_V(n) asm volatile("s_waitcnt vmcnt(" #n ")" ::: "memory")
; #define PG8_WAIT_L(n) asm volatile("s_waitcnt lgkmcnt(" #n ")" ::: "memory")
; template <class Epi, class Sched, bool ALIGN_EPI = false, bool SP2 = false>
; __device__ __forceinline__ void gemm_phase(PG8_LAS unsigned char* lds, const Gemm g, const Sched& S, const Epi& E) {
;     ...
;         for (int t = 0; t < nt; t += 2) {
;             if constexpr (Epi::MID) { if (t == (nt >> 1)) E.mid(acc, wr, fr, lds); }
;             const bool last = (t == nt - 2);
;             const char* a1 = cA + (size_t)(t + 1) * kstep;
;             const char* a2 = last ? nA : cA + (size_t)(t + 2) * kstep; const char* b2 = last ? nB : cB + (size_t)(t + 2) * kstep;
;             const char* a3 = a2 + kstep; const char* b3 = b2 + kstep;
;             if (last && has_next) S.a_ready(nxt);
;             if constexpr (SP2) {
;             PG8_LDB(B0, 0, 0); PG8_LDB(B1, 0, 1); PG8_SCHED; PG8_LDA(At, 0, 0); PG8_STAGE(PG8_SA(1, 1), a1 + hstep, voffA);
;             PG8_WAIT_V(8); PG8_WAIT_L(0); PG8_BAR; PG8_MMA(0, 0, At, B0); PG8_MMA(0, 1, At, B1); PG8_BAR; PG8_SCHED;
;             PG8_LDA(At, 0, 1); PG8_STAGE(PG8_SB(0, 0), b2, voffB); PG8_STAGE(PG8_SB(0, 1), b2 + hstep, voffB); PG8_STAGE(PG8_SA(0, 0), a2, voffA);
.LBB0_1762:
	s_add_i32 s22, s17, 2
	s_add_u32 s28, s34, 0x80
	s_addc_u32 s30, s35, 0
	s_add_i32 s33, 0, 0x10000
	s_cmp_eq_u32 s65, s17
	s_cselect_b32 s37, s3, s30
	s_cselect_b32 s36, s2, s28
	v_add_u32_e32 v146, s33, v148
	s_cselect_b32 s31, s53, s16
	s_cselect_b32 s30, s52, s4
	s_add_i32 s17, 0, 0x14000
	ds_read_b128 v[142:145], v146
	ds_read_b128 v[152:155], v146 offset:1024
	ds_read_b128 v[156:159], v146 offset:2048
	ds_read_b128 v[160:163], v146 offset:3072
	v_add_u32_e32 v146, s17, v148
	ds_read_b128 v[164:167], v146
	ds_read_b128 v[168:171], v146 offset:1024
	ds_read_b128 v[172:175], v146 offset:2048
	ds_read_b128 v[176:179], v146 offset:3072
	v_lshl_add_u64 v[146:147], s[34:35], 0, v[138:139]
	s_add_i32 m0, s58, 0xc000
	ds_read_b128 v[180:183], v150
	ds_read_b128 v[184:187], v150 offset:1024
	ds_read_b128 v[188:191], v150 offset:2048
	ds_read_b128 v[208:211], v150 offset:3072
	ds_read_b128 v[212:215], v150 offset:4096
	ds_read_b128 v[216:219], v150 offset:5120
	ds_read_b128 v[220:223], v150 offset:6144
	ds_read_b128 v[228:231], v150 offset:7168
	global_load_lds_dwordx4 v[146:147], off
	v_lshl_add_u64 v[146:147], s[34:35], 0, v[140:141]
	s_add_i32 m0, s58, 0xe000
	s_nop 0
	global_load_lds_dwordx4 v[146:147], off
	s_waitcnt vmcnt(8)
	s_waitcnt lgkmcnt(0)
	s_barrier
	s_setprio 1
	v_mfma_f32_16x16x32_bf16 v[128:131], v[142:145], v[180:183], v[128:131]
	v_mfma_f32_16x16x32_bf16 v[124:127], v[156:159], v[180:183], v[124:127]
	v_mfma_f32_16x16x32_bf16 v[112:115], v[142:145], v[188:191], v[112:115]
	v_mfma_f32_16x16x32_bf16 v[108:111], v[156:159], v[188:191], v[108:111]
	v_mfma_f32_16x16x32_bf16 v[94:97], v[142:145], v[212:215], v[94:97]
	v_mfma_f32_16x16x32_bf16 v[90:93], v[156:159], v[212:215], v[90:93]
	v_mfma_f32_16x16x32_bf16 v[78:81], v[142:145], v[220:223], v[78:81]
	v_mfma_f32_16x16x32_bf16 v[74:77], v[156:159], v[220:223], v[74:77]
	v_mfma_f32_16x16x32_bf16 v[128:131], v[152:155], v[184:187], v[128:131]
	v_mfma_f32_16x16x32_bf16 v[124:127], v[160:163], v[184:187], v[124:127]
	v_mfma_f32_16x16x32_bf16 v[112:115], v[152:155], v[208:211], v[112:115]
	v_mfma_f32_16x16x32_bf16 v[108:111], v[160:163], v[208:211], v[108:111]
	v_mfma_f32_16x16x32_bf16 v[94:97], v[152:155], v[216:219], v[94:97]
	v_mfma_f32_16x16x32_bf16 v[90:93], v[160:163], v[216:219], v[90:93]
	v_mfma_f32_16x16x32_bf16 v[78:81], v[152:155], v[228:231], v[78:81]
	v_mfma_f32_16x16x32_bf16 v[74:77], v[160:163], v[228:231], v[74:77]
	v_mfma_f32_16x16x32_bf16 v[120:123], v[164:167], v[180:183], v[120:123]
	v_mfma_f32_16x16x32_bf16 v[116:119], v[172:175], v[180:183], v[116:119]
	v_mfma_f32_16x16x32_bf16 v[104:107], v[164:167], v[188:191], v[104:107]
	v_mfma_f32_16x16x32_bf16 v[100:103], v[172:175], v[188:191], v[100:103]
	v_mfma_f32_16x16x32_bf16 v[86:89], v[164:167], v[212:215], v[86:89]
	v_mfma_f32_16x16x32_bf16 v[82:85], v[172:175], v[212:215], v[82:85]
	v_mfma_f32_16x16x32_bf16 v[70:73], v[164:167], v[220:223], v[70:73]
	v_mfma_f32_16x16x32_bf16 v[66:69], v[172:175], v[220:223], v[66:69]
	v_mfma_f32_16x16x32_bf16 v[120:123], v[168:171], v[184:187], v[120:123]
	v_mfma_f32_16x16x32_bf16 v[116:119], v[176:179], v[184:187], v[116:119]
	v_mfma_f32_16x16x32_bf16 v[104:107], v[168:171], v[208:211], v[104:107]
	v_mfma_f32_16x16x32_bf16 v[100:103], v[176:179], v[208:211], v[100:103]
	v_mfma_f32_16x16x32_bf16 v[86:89], v[168:171], v[216:219], v[86:89]
	v_mfma_f32_16x16x32_bf16 v[82:85], v[176:179], v[216:219], v[82:85]
	v_mfma_f32_16x16x32_bf16 v[70:73], v[168:171], v[228:231], v[70:73]
	v_mfma_f32_16x16x32_bf16 v[66:69], v[176:179], v[228:231], v[66:69]
	s_setprio 0
	s_barrier
	s_add_i32 s28, s33, s57
	v_lshl_add_u64 v[146:147], s[30:31], 0, v[98:99]
	s_mov_b32 m0, s28
	ds_read_b128 v[180:183], v150 offset:16384
	ds_read_b128 v[184:187], v150 offset:17408
	ds_read_b128 v[188:191], v150 offset:18432
	ds_read_b128 v[208:211], v150 offset:19456
	ds_read_b128 v[212:215], v150 offset:20480
	ds_read_b128 v[216:219], v150 offset:21504
	ds_read_b128 v[220:223], v150 offset:22528
	ds_read_b128 v[228:231], v150 offset:23552
	global_load_lds_dwordx4 v[146:147], off
	s_add_i32 m0, s28, 0x2000
	v_lshl_add_u64 v[192:193], s[30:31], 0, v[136:137]
	s_add_u32 s30, s30, s8
	s_addc_u32 s31, s31, s9
	s_add_i32 s17, s17, s57
	global_load_lds_dwordx4 v[192:193], off
	v_lshl_add_u64 v[224:225], s[30:31], 0, v[98:99]
	s_mov_b32 m0, s17
	v_lshl_add_u64 v[232:233], s[30:31], 0, v[136:137]
	global_load_lds_dwordx4 v[224:225], off
	s_add_i32 m0, s17, 0x2000
	v_lshl_add_u64 v[234:235], s[36:37], 0, v[132:133]
	global_load_lds_dwordx4 v[232:233], off
	s_mov_b32 m0, s58
	v_lshl_add_u64 v[236:237], s[36:37], 0, v[134:135]
	global_load_lds_dwordx4 v[234:235], off
	s_mov_b32 m0, s59
	s_nop 0
	global_load_lds_dwordx4 v[236:237], off
	s_waitcnt vmcnt(8)
	s_waitcnt lgkmcnt(0)
	s_barrier
; #define PG8_STAGE(bufoff, gbase, voff) do { _Pragma("unroll") for (int _i = 0; _i < 2; ++_i) \
;         __builtin_amdgcn_global_load_lds((const unsigned*)((const char*)(gbase) + (voff)[_i]), (PG8_LAS unsigned*)(lds + (bufoff) + ldsw + _i * 8192), 16, 0, 0); } while (0)
; #define PG8_LDA(dst, b, h) do { _Pragma("unroll") for (int m = 0; m < 4; ++m) _Pragma("unroll") for (int k = 0; k < 2; ++k) dst[m][k] = *(const PG8_LAS bf16x8*)(lds + PG8_SA(b, h) + aoff + m * 2048 + k * 1024); } while (0)
; #define PG8_LDB(dst, b, h) do { _Pragma("unroll") for (int n = 0; n < 2; ++n) _Pragma("unroll") for (int k = 0; k < 2; ++k) dst[n][k] = *(const PG8_LAS bf16x8*)(lds + PG8_SB(b, h) + boff + n * 2048 + k * 1024); } while (0)
; #define PG8_MMA(ai, bj, At, Bt) do { __builtin_amdgcn_s_setprio(1); _Pragma("unroll") for (int m = 0; m < 4; ++m) _Pragma("unroll") for (int n = 0; n < 2; ++n) _Pragma("unroll") for (int k = 0; k < 2; ++k) \
;         acc[ai][bj][m][n] = __builtin_amdgcn_mfma_f32_16x16x32_bf16(Bt[n][k], At[m][k], acc[ai][bj][m][n], 0, 0, 0); __builtin_amdgcn_s_setprio(0); } while (0)
; #define PG8_WAIT_V(n) asm volatile("s_waitcnt vmcnt(" #n ")" ::: "memory")
; #define PG8_WAIT_L(n) asm volatile("s_waitcnt lgkmcnt(" #n ")" ::: "memory")
; #define PG8_BAR __builtin_amdgcn_s_barrier()
; #define PG8_SCHED __builtin_amdgcn_sched_barrier(0)
; template <class Epi, class Sched, bool ALIGN_EPI = false, bool SP2 = false>
; __device__ __forceinline__ void gemm_phase(PG8_LAS unsigned char* lds, const Gemm g, const Sched& S, const Epi& E) {
;     ...
;             PG8_WAIT_V(8); PG8_WAIT_L(0); PG8_BAR; PG8_MMA(1, 0, At, B0); PG8_MMA(1, 1, At, B1); PG8_BAR; PG8_SCHED;
;             PG8_LDB(B0, 1, 0); PG8_LDB(B1, 1, 1); PG8_SCHED; PG8_LDA(At, 1, 0); PG8_STAGE(PG8_SA(0, 1), a2 + hstep, voffA);
;             PG8_WAIT_V(8); PG8_WAIT_L(0); PG8_BAR; PG8_MMA(0, 0, At, B0); PG8_MMA(0, 1, At, B1); PG8_BAR; PG8_SCHED;
	s_setprio 1
	v_mfma_f32_16x16x32_bf16 v[62:65], v[142:145], v[180:183], v[62:65]
	v_mfma_f32_16x16x32_bf16 v[58:61], v[156:159], v[180:183], v[58:61]
	v_mfma_f32_16x16x32_bf16 v[46:49], v[142:145], v[188:191], v[46:49]
	v_mfma_f32_16x16x32_bf16 v[42:45], v[156:159], v[188:191], v[42:45]
	v_mfma_f32_16x16x32_bf16 v[30:33], v[142:145], v[212:215], v[30:33]
	v_mfma_f32_16x16x32_bf16 v[26:29], v[156:159], v[212:215], v[26:29]
	v_mfma_f32_16x16x32_bf16 v[14:17], v[142:145], v[220:223], v[14:17]
	v_mfma_f32_16x16x32_bf16 v[10:13], v[156:159], v[220:223], v[10:13]
	v_mfma_f32_16x16x32_bf16 v[62:65], v[152:155], v[184:187], v[62:65]
	v_mfma_f32_16x16x32_bf16 v[58:61], v[160:163], v[184:187], v[58:61]
	v_mfma_f32_16x16x32_bf16 v[46:49], v[152:155], v[208:211], v[46:49]
	v_mfma_f32_16x16x32_bf16 v[42:45], v[160:163], v[208:211], v[42:45]
	v_mfma_f32_16x16x32_bf16 v[30:33], v[152:155], v[216:219], v[30:33]
	v_mfma_f32_16x16x32_bf16 v[26:29], v[160:163], v[216:219], v[26:29]
	v_mfma_f32_16x16x32_bf16 v[14:17], v[152:155], v[228:231], v[14:17]
	v_mfma_f32_16x16x32_bf16 v[10:13], v[160:163], v[228:231], v[10:13]
	v_mfma_f32_16x16x32_bf16 v[54:57], v[164:167], v[180:183], v[54:57]
	v_mfma_f32_16x16x32_bf16 v[50:53], v[172:175], v[180:183], v[50:53]
	v_mfma_f32_16x16x32_bf16 v[38:41], v[164:167], v[188:191], v[38:41]
	v_mfma_f32_16x16x32_bf16 v[34:37], v[172:175], v[188:191], v[34:37]
	v_mfma_f32_16x16x32_bf16 v[22:25], v[164:167], v[212:215], v[22:25]
	v_mfma_f32_16x16x32_bf16 v[18:21], v[172:175], v[212:215], v[18:21]
	v_mfma_f32_16x16x32_bf16 v[6:9], v[164:167], v[220:223], v[6:9]
	v_mfma_f32_16x16x32_bf16 v[2:5], v[172:175], v[220:223], v[2:5]
	v_mfma_f32_16x16x32_bf16 v[54:57], v[168:171], v[184:187], v[54:57]
	v_mfma_f32_16x16x32_bf16 v[50:53], v[176:179], v[184:187], v[50:53]
	v_mfma_f32_16x16x32_bf16 v[38:41], v[168:171], v[208:211], v[38:41]
	v_mfma_f32_16x16x32_bf16 v[34:37], v[176:179], v[208:211], v[34:37]
	v_mfma_f32_16x16x32_bf16 v[22:25], v[168:171], v[216:219], v[22:25]
	v_mfma_f32_16x16x32_bf16 v[18:21], v[176:179], v[216:219], v[18:21]
	v_mfma_f32_16x16x32_bf16 v[6:9], v[168:171], v[228:231], v[6:9]
	v_mfma_f32_16x16x32_bf16 v[2:5], v[176:179], v[228:231], v[2:5]
	s_setprio 0
	s_barrier
	s_add_i32 s17, 0, 0x18000
	v_add_u32_e32 v151, s17, v148
	s_add_i32 s28, 0, 0x1c000
	ds_read_b128 v[142:145], v151
	ds_read_b128 v[152:155], v151 offset:1024
	ds_read_b128 v[156:159], v151 offset:2048
	ds_read_b128 v[160:163], v151 offset:3072
	v_add_u32_e32 v151, s28, v148
	ds_read_b128 v[164:167], v151
	ds_read_b128 v[168:171], v151 offset:1024
	ds_read_b128 v[172:175], v151 offset:2048
	ds_read_b128 v[176:179], v151 offset:3072
	s_add_u32 s30, s36, s8
	s_addc_u32 s31, s37, s9
	s_mov_b32 m0, s60
	v_lshl_add_u64 v[238:239], s[30:31], 0, v[132:133]
	ds_read_b128 v[180:183], v150 offset:32768
	ds_read_b128 v[184:187], v150 offset:33792
	ds_read_b128 v[188:191], v150 offset:34816
	ds_read_b128 v[208:211], v150 offset:35840
	ds_read_b128 v[212:215], v150 offset:36864
	ds_read_b128 v[216:219], v150 offset:37888
	ds_read_b128 v[220:223], v150 offset:38912
	ds_read_b128 v[228:231], v150 offset:39936
	global_load_lds_dwordx4 v[238:239], off
	v_lshl_add_u64 v[238:239], s[30:31], 0, v[134:135]
	s_mov_b32 m0, s61
	s_nop 0
	global_load_lds_dwordx4 v[238:239], off
	s_waitcnt vmcnt(8)
	s_waitcnt lgkmcnt(0)
	s_barrier
	s_setprio 1
	v_mfma_f32_16x16x32_bf16 v[128:131], v[142:145], v[180:183], v[128:131]
	v_mfma_f32_16x16x32_bf16 v[124:127], v[156:159], v[180:183], v[124:127]
	v_mfma_f32_16x16x32_bf16 v[112:115], v[142:145], v[188:191], v[112:115]
	v_mfma_f32_16x16x32_bf16 v[108:111], v[156:159], v[188:191], v[108:111]
	v_mfma_f32_16x16x32_bf16 v[94:97], v[142:145], v[212:215], v[94:97]
	v_mfma_f32_16x16x32_bf16 v[90:93], v[156:159], v[212:215], v[90:93]
	v_mfma_f32_16x16x32_bf16 v[78:81], v[142:145], v[220:223], v[78:81]
	v_mfma_f32_16x16x32_bf16 v[74:77], v[156:159], v[220:223], v[74:77]
	v_mfma_f32_16x16x32_bf16 v[128:131], v[152:155], v[184:187], v[128:131]
	v_mfma_f32_16x16x32_bf16 v[124:127], v[160:163], v[184:187], v[124:127]
	v_mfma_f32_16x16x32_bf16 v[112:115], v[152:155], v[208:211], v[112:115]
	v_mfma_f32_16x16x32_bf16 v[108:111], v[160:163], v[208:211], v[108:111]
	v_mfma_f32_16x16x32_bf16 v[94:97], v[152:155], v[216:219], v[94:97]
	v_mfma_f32_16x16x32_bf16 v[90:93], v[160:163], v[216:219], v[90:93]
	v_mfma_f32_16x16x32_bf16 v[78:81], v[152:155], v[228:231], v[78:81]
	v_mfma_f32_16x16x32_bf16 v[74:77], v[160:163], v[228:231], v[74:77]
	v_mfma_f32_16x16x32_bf16 v[120:123], v[164:167], v[180:183], v[120:123]
	v_mfma_f32_16x16x32_bf16 v[116:119], v[172:175], v[180:183], v[116:119]
	v_mfma_f32_16x16x32_bf16 v[104:107], v[164:167], v[188:191], v[104:107]
	v_mfma_f32_16x16x32_bf16 v[100:103], v[172:175], v[188:191], v[100:103]
	v_mfma_f32_16x16x32_bf16 v[86:89], v[164:167], v[212:215], v[86:89]
	v_mfma_f32_16x16x32_bf16 v[82:85], v[172:175], v[212:215], v[82:85]
	v_mfma_f32_16x16x32_bf16 v[70:73], v[164:167], v[220:223], v[70:73]
	v_mfma_f32_16x16x32_bf16 v[66:69], v[172:175], v[220:223], v[66:69]
	v_mfma_f32_16x16x32_bf16 v[120:123], v[168:171], v[184:187], v[120:123]
	v_mfma_f32_16x16x32_bf16 v[116:119], v[176:179], v[184:187], v[116:119]
	v_mfma_f32_16x16x32_bf16 v[104:107], v[168:171], v[208:211], v[104:107]
	v_mfma_f32_16x16x32_bf16 v[100:103], v[176:179], v[208:211], v[100:103]
	v_mfma_f32_16x16x32_bf16 v[86:89], v[168:171], v[216:219], v[86:89]
	v_mfma_f32_16x16x32_bf16 v[82:85], v[176:179], v[216:219], v[82:85]
	v_mfma_f32_16x16x32_bf16 v[70:73], v[168:171], v[228:231], v[70:73]
	v_mfma_f32_16x16x32_bf16 v[66:69], v[176:179], v[228:231], v[66:69]
	s_setprio 0
	s_barrier
; #define PG8_STAGE(bufoff, gbase, voff) do { _Pragma("unroll") for (int _i = 0; _i < 2; ++_i) \
;         __builtin_amdgcn_global_load_lds((const unsigned*)((const char*)(gbase) + (voff)[_i]), (PG8_LAS unsigned*)(lds + (bufoff) + ldsw + _i * 8192), 16, 0, 0); } while (0)
; #define PG8_LDA(dst, b, h) do { _Pragma("unroll") for (int m = 0; m < 4; ++m) _Pragma("unroll") for (int k = 0; k < 2; ++k) dst[m][k] = *(const PG8_LAS bf16x8*)(lds + PG8_SA(b, h) + aoff + m * 2048 + k * 1024); } while (0)
; #define PG8_MMA(ai, bj, At, Bt) do { __builtin_amdgcn_s_setprio(1); _Pragma("unroll") for (int m = 0; m < 4; ++m) _Pragma("unroll") for (int n = 0; n < 2; ++n) _Pragma("unroll") for (int k = 0; k < 2; ++k) \
;         acc[ai][bj][m][n] = __builtin_amdgcn_mfma_f32_16x16x32_bf16(Bt[n][k], At[m][k], acc[ai][bj][m][n], 0, 0, 0); __builtin_amdgcn_s_setprio(0); } while (0)
; #define PG8_WAIT_V(n) asm volatile("s_waitcnt vmcnt(" #n ")" ::: "memory")
; #define PG8_WAIT_L(n) asm volatile("s_waitcnt lgkmcnt(" #n ")" ::: "memory")
; #define PG8_BAR __builtin_amdgcn_s_barrier()
; #define PG8_SCHED __builtin_amdgcn_sched_barrier(0)
; template <class Epi, class Sched, bool ALIGN_EPI = false, bool SP2 = false>
; __device__ __forceinline__ void gemm_phase(PG8_LAS unsigned char* lds, const Gemm g, const Sched& S, const Epi& E) {
;     ...
;         for (int t = 0; t < nt; t += 2) {
;     ...
;             PG8_LDA(At, 1, 1); PG8_STAGE(PG8_SB(1, 0), b3, voffB); PG8_STAGE(PG8_SB(1, 1), b3 + hstep, voffB); PG8_STAGE(PG8_SA(1, 0), a3, voffA);
;             PG8_WAIT_V(8); PG8_WAIT_L(0); PG8_BAR; PG8_MMA(1, 0, At, B0); PG8_MMA(1, 1, At, B1); PG8_BAR; PG8_SCHED;
	s_add_i32 s17, s17, s57
	v_lshl_add_u64 v[146:147], v[146:147], 0, s[24:25]
	s_mov_b32 m0, s17
	ds_read_b128 v[180:183], v150 offset:49152
	ds_read_b128 v[184:187], v150 offset:50176
	ds_read_b128 v[188:191], v150 offset:51200
	ds_read_b128 v[208:211], v150 offset:52224
	ds_read_b128 v[212:215], v150 offset:53248
	ds_read_b128 v[216:219], v150 offset:54272
	ds_read_b128 v[220:223], v150 offset:55296
	ds_read_b128 v[228:231], v150 offset:56320
	global_load_lds_dwordx4 v[146:147], off
	v_lshl_add_u64 v[146:147], v[192:193], 0, s[24:25]
	s_add_i32 m0, s17, 0x2000
	s_add_i32 s17, s28, s57
	global_load_lds_dwordx4 v[146:147], off
	v_lshl_add_u64 v[146:147], v[224:225], 0, s[24:25]
	s_mov_b32 m0, s17
	s_nop 0
	global_load_lds_dwordx4 v[146:147], off
	v_lshl_add_u64 v[146:147], v[232:233], 0, s[24:25]
	s_add_i32 m0, s17, 0x2000
	s_nop 0
	global_load_lds_dwordx4 v[146:147], off
	v_lshl_add_u64 v[146:147], v[234:235], 0, s[24:25]
	s_mov_b32 m0, s63
	s_nop 0
	global_load_lds_dwordx4 v[146:147], off
	v_lshl_add_u64 v[146:147], v[236:237], 0, s[24:25]
	s_mov_b32 m0, s64
	s_nop 0
	global_load_lds_dwordx4 v[146:147], off
	s_waitcnt vmcnt(8)
	s_waitcnt lgkmcnt(0)
	s_barrier
	s_setprio 1
	v_mfma_f32_16x16x32_bf16 v[62:65], v[142:145], v[180:183], v[62:65]
	v_mfma_f32_16x16x32_bf16 v[58:61], v[156:159], v[180:183], v[58:61]
	v_mfma_f32_16x16x32_bf16 v[46:49], v[142:145], v[188:191], v[46:49]
	v_mfma_f32_16x16x32_bf16 v[42:45], v[156:159], v[188:191], v[42:45]
	v_mfma_f32_16x16x32_bf16 v[30:33], v[142:145], v[212:215], v[30:33]
	v_mfma_f32_16x16x32_bf16 v[26:29], v[156:159], v[212:215], v[26:29]
	v_mfma_f32_16x16x32_bf16 v[14:17], v[142:145], v[220:223], v[14:17]
	v_mfma_f32_16x16x32_bf16 v[10:13], v[156:159], v[220:223], v[10:13]
	v_mfma_f32_16x16x32_bf16 v[62:65], v[152:155], v[184:187], v[62:65]
	v_mfma_f32_16x16x32_bf16 v[58:61], v[160:163], v[184:187], v[58:61]
	v_mfma_f32_16x16x32_bf16 v[46:49], v[152:155], v[208:211], v[46:49]
	v_mfma_f32_16x16x32_bf16 v[42:45], v[160:163], v[208:211], v[42:45]
	v_mfma_f32_16x16x32_bf16 v[30:33], v[152:155], v[216:219], v[30:33]
	v_mfma_f32_16x16x32_bf16 v[26:29], v[160:163], v[216:219], v[26:29]
	v_mfma_f32_16x16x32_bf16 v[14:17], v[152:155], v[228:231], v[14:17]
	v_mfma_f32_16x16x32_bf16 v[10:13], v[160:163], v[228:231], v[10:13]
	v_mfma_f32_16x16x32_bf16 v[54:57], v[164:167], v[180:183], v[54:57]
	v_mfma_f32_16x16x32_bf16 v[50:53], v[172:175], v[180:183], v[50:53]
	v_mfma_f32_16x16x32_bf16 v[38:41], v[164:167], v[188:191], v[38:41]
	v_mfma_f32_16x16x32_bf16 v[34:37], v[172:175], v[188:191], v[34:37]
	v_mfma_f32_16x16x32_bf16 v[22:25], v[164:167], v[212:215], v[22:25]
	v_mfma_f32_16x16x32_bf16 v[18:21], v[172:175], v[212:215], v[18:21]
	v_mfma_f32_16x16x32_bf16 v[6:9], v[164:167], v[220:223], v[6:9]
	v_mfma_f32_16x16x32_bf16 v[2:5], v[172:175], v[220:223], v[2:5]
	v_mfma_f32_16x16x32_bf16 v[54:57], v[168:171], v[184:187], v[54:57]
	v_mfma_f32_16x16x32_bf16 v[50:53], v[176:179], v[184:187], v[50:53]
	v_mfma_f32_16x16x32_bf16 v[38:41], v[168:171], v[208:211], v[38:41]
	v_mfma_f32_16x16x32_bf16 v[34:37], v[176:179], v[208:211], v[34:37]
	v_mfma_f32_16x16x32_bf16 v[22:25], v[168:171], v[216:219], v[22:25]
	v_mfma_f32_16x16x32_bf16 v[18:21], v[176:179], v[216:219], v[18:21]
	v_mfma_f32_16x16x32_bf16 v[6:9], v[168:171], v[228:231], v[6:9]
	v_mfma_f32_16x16x32_bf16 v[2:5], v[176:179], v[228:231], v[2:5]
	s_setprio 0
	s_barrier
	s_add_u32 s34, s34, 0x100
	s_addc_u32 s35, s35, 0
	s_add_u32 s4, s4, 0x100
	s_addc_u32 s16, s16, 0
	s_cmp_ge_i32 s22, s62
	s_mov_b32 s17, s22
	s_cbranch_scc0 .LBB0_1762

; #define PG8_STAGE(bufoff, gbase, voff) do { _Pragma("unroll") for (int _i = 0; _i < 2; ++_i) \
;         __builtin_amdgcn_global_load_lds((const unsigned*)((const char*)(gbase) + (voff)[_i]), (PG8_LAS unsigned*)(lds + (bufoff) + ldsw + _i * 8192), 16, 0, 0); } while (0)
; #define PG8_LDA(dst, b, h) do { _Pragma("unroll") for (int m = 0; m < 4; ++m) _Pragma("unroll") for (int k = 0; k < 2; ++k) dst[m][k] = *(const PG8_LAS bf16x8*)(lds + PG8_SA(b, h) + aoff + m * 2048 + k * 1024); } while (0)
; #define PG8_LDB(dst, b, h) do { _Pragma("unroll") for (int n = 0; n < 2; ++n) _Pragma("unroll") for (int k = 0; k < 2; ++k) dst[n][k] = *(const PG8_LAS bf16x8*)(lds + PG8_SB(b, h) + boff + n * 2048 + k * 1024); } while (0)
; #define PG8_MMA(ai, bj, At, Bt) do { __builtin_amdgcn_s_setprio(1); _Pragma("unroll") for (int m = 0; m < 4; ++m) _Pragma("unroll") for (int n = 0; n < 2; ++n) _Pragma("unroll") for (int k = 0; k < 2; ++k) \
;         acc[ai][bj][m][n] = __builtin_amdgcn_mfma_f32_16x16x32_bf16(Bt[n][k], At[m][k], acc[ai][bj][m][n], 0, 0, 0); __builtin_amdgcn_s_setprio(0); } while (0)
; #define PG8_WAIT_V(n) asm volatile("s_waitcnt vmcnt(" #n ")" ::: "memory")
; #define PG8_WAIT_L(n) asm volatile("s_waitcnt lgkmcnt(" #n ")" ::: "memory")
; template <class Epi, class Sched, bool ALIGN_EPI = false, bool SP2 = false>
; __device__ __forceinline__ void gemm_phase(PG8_LAS unsigned char* lds, const Gemm g, const Sched& S, const Epi& E) {
;     ...
;         for (int t = 0; t < nt; t += 2) {
;             if constexpr (Epi::MID) { if (t == (nt >> 1)) E.mid(acc, wr, fr, lds); }
;             const bool last = (t == nt - 2);
;             const char* a1 = cA + (size_t)(t + 1) * kstep;
;             const char* a2 = last ? nA : cA + (size_t)(t + 2) * kstep; const char* b2 = last ? nB : cB + (size_t)(t + 2) * kstep;
;             const char* a3 = a2 + kstep; const char* b3 = b2 + kstep;
;             if (last && has_next) S.a_ready(nxt);
;             if constexpr (SP2) {
;             PG8_LDB(B0, 0, 0); PG8_LDB(B1, 0, 1); PG8_SCHED; PG8_LDA(At, 0, 0); PG8_STAGE(PG8_SA(1, 1), a1 + hstep, voffA);
;             PG8_WAIT_V(8); PG8_WAIT_L(0); PG8_BAR; PG8_MMA(0, 0, At, B0); PG8_MMA(0, 1, At, B1); PG8_BAR; PG8_SCHED;
;             PG8_LDA(At, 0, 1); PG8_STAGE(PG8_SB(0, 0), b2, voffB); PG8_STAGE(PG8_SB(0, 1), b2 + hstep, voffB); PG8_STAGE(PG8_SA(0, 0), a2, voffA);
.LBB0_1853:
	s_add_i32 s22, s17, 2
	s_add_u32 s28, s34, 0x80
	s_addc_u32 s30, s35, 0
	s_add_i32 s33, 0, 0x10000
	s_cmp_eq_u32 s68, s17
	s_cselect_b32 s37, s3, s30
	s_cselect_b32 s36, s2, s28
	v_add_u32_e32 v150, s33, v153
	s_cselect_b32 s31, s59, s16
	s_cselect_b32 s30, s58, s4
	s_add_i32 s17, 0, 0x14000
	ds_read_b128 v[142:145], v150
	ds_read_b128 v[146:149], v150 offset:1024
	ds_read_b128 v[154:157], v150 offset:2048
	ds_read_b128 v[160:163], v150 offset:3072
	v_add_u32_e32 v150, s17, v153
	ds_read_b128 v[164:167], v150
	ds_read_b128 v[168:171], v150 offset:1024
	ds_read_b128 v[172:175], v150 offset:2048
	ds_read_b128 v[176:179], v150 offset:3072
	v_lshl_add_u64 v[150:151], s[34:35], 0, v[138:139]
	s_add_i32 m0, s62, 0xc000
	ds_read_b128 v[180:183], v159
	ds_read_b128 v[184:187], v159 offset:1024
	ds_read_b128 v[188:191], v159 offset:2048
	ds_read_b128 v[208:211], v159 offset:3072
	ds_read_b128 v[212:215], v159 offset:4096
	ds_read_b128 v[216:219], v159 offset:5120
	ds_read_b128 v[220:223], v159 offset:6144
	ds_read_b128 v[228:231], v159 offset:7168
	global_load_lds_dwordx4 v[150:151], off
	v_lshl_add_u64 v[150:151], s[34:35], 0, v[140:141]
	s_add_i32 m0, s62, 0xe000
	s_nop 0
	global_load_lds_dwordx4 v[150:151], off
	s_waitcnt vmcnt(8)
	s_waitcnt lgkmcnt(0)
	s_barrier
	s_setprio 1
	v_mfma_f32_16x16x32_bf16 v[124:127], v[142:145], v[180:183], v[124:127]
	v_mfma_f32_16x16x32_bf16 v[128:131], v[154:157], v[180:183], v[128:131]
	v_mfma_f32_16x16x32_bf16 v[112:115], v[142:145], v[188:191], v[112:115]
	v_mfma_f32_16x16x32_bf16 v[108:111], v[154:157], v[188:191], v[108:111]
	v_mfma_f32_16x16x32_bf16 v[94:97], v[142:145], v[212:215], v[94:97]
	v_mfma_f32_16x16x32_bf16 v[90:93], v[154:157], v[212:215], v[90:93]
	v_mfma_f32_16x16x32_bf16 v[78:81], v[142:145], v[220:223], v[78:81]
	v_mfma_f32_16x16x32_bf16 v[74:77], v[154:157], v[220:223], v[74:77]
	v_mfma_f32_16x16x32_bf16 v[124:127], v[146:149], v[184:187], v[124:127]
	v_mfma_f32_16x16x32_bf16 v[128:131], v[160:163], v[184:187], v[128:131]
	v_mfma_f32_16x16x32_bf16 v[112:115], v[146:149], v[208:211], v[112:115]
	v_mfma_f32_16x16x32_bf16 v[108:111], v[160:163], v[208:211], v[108:111]
	v_mfma_f32_16x16x32_bf16 v[94:97], v[146:149], v[216:219], v[94:97]
	v_mfma_f32_16x16x32_bf16 v[90:93], v[160:163], v[216:219], v[90:93]
	v_mfma_f32_16x16x32_bf16 v[78:81], v[146:149], v[228:231], v[78:81]
	v_mfma_f32_16x16x32_bf16 v[74:77], v[160:163], v[228:231], v[74:77]
	v_mfma_f32_16x16x32_bf16 v[120:123], v[164:167], v[180:183], v[120:123]
	v_mfma_f32_16x16x32_bf16 v[116:119], v[172:175], v[180:183], v[116:119]
	v_mfma_f32_16x16x32_bf16 v[104:107], v[164:167], v[188:191], v[104:107]
	v_mfma_f32_16x16x32_bf16 v[100:103], v[172:175], v[188:191], v[100:103]
	v_mfma_f32_16x16x32_bf16 v[86:89], v[164:167], v[212:215], v[86:89]
	v_mfma_f32_16x16x32_bf16 v[82:85], v[172:175], v[212:215], v[82:85]
	v_mfma_f32_16x16x32_bf16 v[70:73], v[164:167], v[220:223], v[70:73]
	v_mfma_f32_16x16x32_bf16 v[66:69], v[172:175], v[220:223], v[66:69]
	v_mfma_f32_16x16x32_bf16 v[120:123], v[168:171], v[184:187], v[120:123]
	v_mfma_f32_16x16x32_bf16 v[116:119], v[176:179], v[184:187], v[116:119]
	v_mfma_f32_16x16x32_bf16 v[104:107], v[168:171], v[208:211], v[104:107]
	v_mfma_f32_16x16x32_bf16 v[100:103], v[176:179], v[208:211], v[100:103]
	v_mfma_f32_16x16x32_bf16 v[86:89], v[168:171], v[216:219], v[86:89]
	v_mfma_f32_16x16x32_bf16 v[82:85], v[176:179], v[216:219], v[82:85]
	v_mfma_f32_16x16x32_bf16 v[70:73], v[168:171], v[228:231], v[70:73]
	v_mfma_f32_16x16x32_bf16 v[66:69], v[176:179], v[228:231], v[66:69]
	s_setprio 0
	s_barrier
	s_add_i32 s28, s33, s61
	v_lshl_add_u64 v[150:151], s[30:31], 0, v[98:99]
	s_mov_b32 m0, s28
	ds_read_b128 v[180:183], v159 offset:16384
	ds_read_b128 v[184:187], v159 offset:17408
	ds_read_b128 v[188:191], v159 offset:18432
	ds_read_b128 v[208:211], v159 offset:19456
	ds_read_b128 v[212:215], v159 offset:20480
	ds_read_b128 v[216:219], v159 offset:21504
	ds_read_b128 v[220:223], v159 offset:22528
	ds_read_b128 v[228:231], v159 offset:23552
	global_load_lds_dwordx4 v[150:151], off
	s_add_i32 m0, s28, 0x2000
	v_lshl_add_u64 v[192:193], s[30:31], 0, v[136:137]
	s_add_u32 s30, s30, s10
	s_addc_u32 s31, s31, s11
	s_add_i32 s17, s17, s61
	global_load_lds_dwordx4 v[192:193], off
	v_lshl_add_u64 v[224:225], s[30:31], 0, v[98:99]
	s_mov_b32 m0, s17
	v_lshl_add_u64 v[232:233], s[30:31], 0, v[136:137]
	global_load_lds_dwordx4 v[224:225], off
	s_add_i32 m0, s17, 0x2000
	v_lshl_add_u64 v[234:235], s[36:37], 0, v[132:133]
	global_load_lds_dwordx4 v[232:233], off
	s_mov_b32 m0, s62
	v_lshl_add_u64 v[236:237], s[36:37], 0, v[134:135]
	global_load_lds_dwordx4 v[234:235], off
	s_mov_b32 m0, s63
	s_nop 0
	global_load_lds_dwordx4 v[236:237], off
	s_waitcnt vmcnt(8)
	s_waitcnt lgkmcnt(0)
	s_barrier
; #define PG8_STAGE(bufoff, gbase, voff) do { _Pragma("unroll") for (int _i = 0; _i < 2; ++_i) \
;         __builtin_amdgcn_global_load_lds((const unsigned*)((const char*)(gbase) + (voff)[_i]), (PG8_LAS unsigned*)(lds + (bufoff) + ldsw + _i * 8192), 16, 0, 0); } while (0)
; #define PG8_LDA(dst, b, h) do { _Pragma("unroll") for (int m = 0; m < 4; ++m) _Pragma("unroll") for (int k = 0; k < 2; ++k) dst[m][k] = *(const PG8_LAS bf16x8*)(lds + PG8_SA(b, h) + aoff + m * 2048 + k * 1024); } while (0)
; #define PG8_LDB(dst, b, h) do { _Pragma("unroll") for (int n = 0; n < 2; ++n) _Pragma("unroll") for (int k = 0; k < 2; ++k) dst[n][k] = *(const PG8_LAS bf16x8*)(lds + PG8_SB(b, h) + boff + n * 2048 + k * 1024); } while (0)
; #define PG8_MMA(ai, bj, At, Bt) do { __builtin_amdgcn_s_setprio(1); _Pragma("unroll") for (int m = 0; m < 4; ++m) _Pragma("unroll") for (int n = 0; n < 2; ++n) _Pragma("unroll") for (int k = 0; k < 2; ++k) \
;         acc[ai][bj][m][n] = __builtin_amdgcn_mfma_f32_16x16x32_bf16(Bt[n][k], At[m][k], acc[ai][bj][m][n], 0, 0, 0); __builtin_amdgcn_s_setprio(0); } while (0)
; #define PG8_WAIT_V(n) asm volatile("s_waitcnt vmcnt(" #n ")" ::: "memory")
; #define PG8_WAIT_L(n) asm volatile("s_waitcnt lgkmcnt(" #n ")" ::: "memory")
; #define PG8_BAR __builtin_amdgcn_s_barrier()
; #define PG8_SCHED __builtin_amdgcn_sched_barrier(0)
; template <class Epi, class Sched, bool ALIGN_EPI = false, bool SP2 = false>
; __device__ __forceinline__ void gemm_phase(PG8_LAS unsigned char* lds, const Gemm g, const Sched& S, const Epi& E) {
;     ...
;             PG8_WAIT_V(8); PG8_WAIT_L(0); PG8_BAR; PG8_MMA(1, 0, At, B0); PG8_MMA(1, 1, At, B1); PG8_BAR; PG8_SCHED;
;             PG8_LDB(B0, 1, 0); PG8_LDB(B1, 1, 1); PG8_SCHED; PG8_LDA(At, 1, 0); PG8_STAGE(PG8_SA(0, 1), a2 + hstep, voffA);
;             PG8_WAIT_V(8); PG8_WAIT_L(0); PG8_BAR; PG8_MMA(0, 0, At, B0); PG8_MMA(0, 1, At, B1); PG8_BAR; PG8_SCHED;
	s_setprio 1
	v_mfma_f32_16x16x32_bf16 v[62:65], v[142:145], v[180:183], v[62:65]
	v_mfma_f32_16x16x32_bf16 v[58:61], v[154:157], v[180:183], v[58:61]
	v_mfma_f32_16x16x32_bf16 v[46:49], v[142:145], v[188:191], v[46:49]
	v_mfma_f32_16x16x32_bf16 v[42:45], v[154:157], v[188:191], v[42:45]
	v_mfma_f32_16x16x32_bf16 v[30:33], v[142:145], v[212:215], v[30:33]
	v_mfma_f32_16x16x32_bf16 v[26:29], v[154:157], v[212:215], v[26:29]
	v_mfma_f32_16x16x32_bf16 v[14:17], v[142:145], v[220:223], v[14:17]
	v_mfma_f32_16x16x32_bf16 v[10:13], v[154:157], v[220:223], v[10:13]
	v_mfma_f32_16x16x32_bf16 v[62:65], v[146:149], v[184:187], v[62:65]
	v_mfma_f32_16x16x32_bf16 v[58:61], v[160:163], v[184:187], v[58:61]
	v_mfma_f32_16x16x32_bf16 v[46:49], v[146:149], v[208:211], v[46:49]
	v_mfma_f32_16x16x32_bf16 v[42:45], v[160:163], v[208:211], v[42:45]
	v_mfma_f32_16x16x32_bf16 v[30:33], v[146:149], v[216:219], v[30:33]
	v_mfma_f32_16x16x32_bf16 v[26:29], v[160:163], v[216:219], v[26:29]
	v_mfma_f32_16x16x32_bf16 v[14:17], v[146:149], v[228:231], v[14:17]
	v_mfma_f32_16x16x32_bf16 v[10:13], v[160:163], v[228:231], v[10:13]
	v_mfma_f32_16x16x32_bf16 v[54:57], v[164:167], v[180:183], v[54:57]
	v_mfma_f32_16x16x32_bf16 v[50:53], v[172:175], v[180:183], v[50:53]
	v_mfma_f32_16x16x32_bf16 v[38:41], v[164:167], v[188:191], v[38:41]
	v_mfma_f32_16x16x32_bf16 v[34:37], v[172:175], v[188:191], v[34:37]
	v_mfma_f32_16x16x32_bf16 v[22:25], v[164:167], v[212:215], v[22:25]
	v_mfma_f32_16x16x32_bf16 v[18:21], v[172:175], v[212:215], v[18:21]
	v_mfma_f32_16x16x32_bf16 v[6:9], v[164:167], v[220:223], v[6:9]
	v_mfma_f32_16x16x32_bf16 v[2:5], v[172:175], v[220:223], v[2:5]
	v_mfma_f32_16x16x32_bf16 v[54:57], v[168:171], v[184:187], v[54:57]
	v_mfma_f32_16x16x32_bf16 v[50:53], v[176:179], v[184:187], v[50:53]
	v_mfma_f32_16x16x32_bf16 v[38:41], v[168:171], v[208:211], v[38:41]
	v_mfma_f32_16x16x32_bf16 v[34:37], v[176:179], v[208:211], v[34:37]
	v_mfma_f32_16x16x32_bf16 v[22:25], v[168:171], v[216:219], v[22:25]
	v_mfma_f32_16x16x32_bf16 v[18:21], v[176:179], v[216:219], v[18:21]
	v_mfma_f32_16x16x32_bf16 v[6:9], v[168:171], v[228:231], v[6:9]
	v_mfma_f32_16x16x32_bf16 v[2:5], v[176:179], v[228:231], v[2:5]
	s_setprio 0
	s_barrier
	s_add_i32 s17, 0, 0x18000
	v_add_u32_e32 v152, s17, v153
	s_add_i32 s28, 0, 0x1c000
	ds_read_b128 v[142:145], v152
	ds_read_b128 v[146:149], v152 offset:1024
	ds_read_b128 v[154:157], v152 offset:2048
	ds_read_b128 v[160:163], v152 offset:3072
	v_add_u32_e32 v152, s28, v153
	ds_read_b128 v[164:167], v152
	ds_read_b128 v[168:171], v152 offset:1024
	ds_read_b128 v[172:175], v152 offset:2048
	ds_read_b128 v[176:179], v152 offset:3072
	s_add_u32 s30, s36, s10
	s_addc_u32 s31, s37, s11
	s_mov_b32 m0, s64
	v_lshl_add_u64 v[238:239], s[30:31], 0, v[132:133]
	ds_read_b128 v[180:183], v159 offset:32768
	ds_read_b128 v[184:187], v159 offset:33792
	ds_read_b128 v[188:191], v159 offset:34816
	ds_read_b128 v[208:211], v159 offset:35840
	ds_read_b128 v[212:215], v159 offset:36864
	ds_read_b128 v[216:219], v159 offset:37888
	ds_read_b128 v[220:223], v159 offset:38912
	ds_read_b128 v[228:231], v159 offset:39936
	global_load_lds_dwordx4 v[238:239], off
	v_lshl_add_u64 v[238:239], s[30:31], 0, v[134:135]
	s_mov_b32 m0, s65
	s_nop 0
	global_load_lds_dwordx4 v[238:239], off
	s_waitcnt vmcnt(8)
	s_waitcnt lgkmcnt(0)
	s_barrier
	s_setprio 1
	v_mfma_f32_16x16x32_bf16 v[124:127], v[142:145], v[180:183], v[124:127]
	v_mfma_f32_16x16x32_bf16 v[128:131], v[154:157], v[180:183], v[128:131]
	v_mfma_f32_16x16x32_bf16 v[112:115], v[142:145], v[188:191], v[112:115]
	v_mfma_f32_16x16x32_bf16 v[108:111], v[154:157], v[188:191], v[108:111]
	v_mfma_f32_16x16x32_bf16 v[94:97], v[142:145], v[212:215], v[94:97]
	v_mfma_f32_16x16x32_bf16 v[90:93], v[154:157], v[212:215], v[90:93]
	v_mfma_f32_16x16x32_bf16 v[78:81], v[142:145], v[220:223], v[78:81]
	v_mfma_f32_16x16x32_bf16 v[74:77], v[154:157], v[220:223], v[74:77]
	v_mfma_f32_16x16x32_bf16 v[124:127], v[146:149], v[184:187], v[124:127]
	v_mfma_f32_16x16x32_bf16 v[128:131], v[160:163], v[184:187], v[128:131]
	v_mfma_f32_16x16x32_bf16 v[112:115], v[146:149], v[208:211], v[112:115]
	v_mfma_f32_16x16x32_bf16 v[108:111], v[160:163], v[208:211], v[108:111]
	v_mfma_f32_16x16x32_bf16 v[94:97], v[146:149], v[216:219], v[94:97]
	v_mfma_f32_16x16x32_bf16 v[90:93], v[160:163], v[216:219], v[90:93]
	v_mfma_f32_16x16x32_bf16 v[78:81], v[146:149], v[228:231], v[78:81]
	v_mfma_f32_16x16x32_bf16 v[74:77], v[160:163], v[228:231], v[74:77]
	v_mfma_f32_16x16x32_bf16 v[120:123], v[164:167], v[180:183], v[120:123]
	v_mfma_f32_16x16x32_bf16 v[116:119], v[172:175], v[180:183], v[116:119]
	v_mfma_f32_16x16x32_bf16 v[104:107], v[164:167], v[188:191], v[104:107]
	v_mfma_f32_16x16x32_bf16 v[100:103], v[172:175], v[188:191], v[100:103]
	v_mfma_f32_16x16x32_bf16 v[86:89], v[164:167], v[212:215], v[86:89]
	v_mfma_f32_16x16x32_bf16 v[82:85], v[172:175], v[212:215], v[82:85]
	v_mfma_f32_16x16x32_bf16 v[70:73], v[164:167], v[220:223], v[70:73]
	v_mfma_f32_16x16x32_bf16 v[66:69], v[172:175], v[220:223], v[66:69]
	v_mfma_f32_16x16x32_bf16 v[120:123], v[168:171], v[184:187], v[120:123]
	v_mfma_f32_16x16x32_bf16 v[116:119], v[176:179], v[184:187], v[116:119]
	v_mfma_f32_16x16x32_bf16 v[104:107], v[168:171], v[208:211], v[104:107]
	v_mfma_f32_16x16x32_bf16 v[100:103], v[176:179], v[208:211], v[100:103]
	v_mfma_f32_16x16x32_bf16 v[86:89], v[168:171], v[216:219], v[86:89]
	v_mfma_f32_16x16x32_bf16 v[82:85], v[176:179], v[216:219], v[82:85]
	v_mfma_f32_16x16x32_bf16 v[70:73], v[168:171], v[228:231], v[70:73]
	v_mfma_f32_16x16x32_bf16 v[66:69], v[176:179], v[228:231], v[66:69]
	s_setprio 0
	s_barrier
; #define PG8_STAGE(bufoff, gbase, voff) do { _Pragma("unroll") for (int _i = 0; _i < 2; ++_i) \
;         __builtin_amdgcn_global_load_lds((const unsigned*)((const char*)(gbase) + (voff)[_i]), (PG8_LAS unsigned*)(lds + (bufoff) + ldsw + _i * 8192), 16, 0, 0); } while (0)
; #define PG8_LDA(dst, b, h) do { _Pragma("unroll") for (int m = 0; m < 4; ++m) _Pragma("unroll") for (int k = 0; k < 2; ++k) dst[m][k] = *(const PG8_LAS bf16x8*)(lds + PG8_SA(b, h) + aoff + m * 2048 + k * 1024); } while (0)
; #define PG8_MMA(ai, bj, At, Bt) do { __builtin_amdgcn_s_setprio(1); _Pragma("unroll") for (int m = 0; m < 4; ++m) _Pragma("unroll") for (int n = 0; n < 2; ++n) _Pragma("unroll") for (int k = 0; k < 2; ++k) \
;         acc[ai][bj][m][n] = __builtin_amdgcn_mfma_f32_16x16x32_bf16(Bt[n][k], At[m][k], acc[ai][bj][m][n], 0, 0, 0); __builtin_amdgcn_s_setprio(0); } while (0)
; #define PG8_WAIT_V(n) asm volatile("s_waitcnt vmcnt(" #n ")" ::: "memory")
; #define PG8_WAIT_L(n) asm volatile("s_waitcnt lgkmcnt(" #n ")" ::: "memory")
; #define PG8_BAR __builtin_amdgcn_s_barrier()
; #define PG8_SCHED __builtin_amdgcn_sched_barrier(0)
; template <class Epi, class Sched, bool ALIGN_EPI = false, bool SP2 = false>
; __device__ __forceinline__ void gemm_phase(PG8_LAS unsigned char* lds, const Gemm g, const Sched& S, const Epi& E) {
;     ...
;         for (int t = 0; t < nt; t += 2) {
;     ...
;             PG8_LDA(At, 1, 1); PG8_STAGE(PG8_SB(1, 0), b3, voffB); PG8_STAGE(PG8_SB(1, 1), b3 + hstep, voffB); PG8_STAGE(PG8_SA(1, 0), a3, voffA);
;             PG8_WAIT_V(8); PG8_WAIT_L(0); PG8_BAR; PG8_MMA(1, 0, At, B0); PG8_MMA(1, 1, At, B1); PG8_BAR; PG8_SCHED;
	s_add_i32 s17, s17, s61
	v_lshl_add_u64 v[150:151], v[150:151], 0, s[24:25]
	s_mov_b32 m0, s17
	ds_read_b128 v[180:183], v159 offset:49152
	ds_read_b128 v[184:187], v159 offset:50176
	ds_read_b128 v[188:191], v159 offset:51200
	ds_read_b128 v[208:211], v159 offset:52224
	ds_read_b128 v[212:215], v159 offset:53248
	ds_read_b128 v[216:219], v159 offset:54272
	ds_read_b128 v[220:223], v159 offset:55296
	ds_read_b128 v[228:231], v159 offset:56320
	global_load_lds_dwordx4 v[150:151], off
	v_lshl_add_u64 v[150:151], v[192:193], 0, s[24:25]
	s_add_i32 m0, s17, 0x2000
	s_add_i32 s17, s28, s61
	global_load_lds_dwordx4 v[150:151], off
	v_lshl_add_u64 v[150:151], v[224:225], 0, s[24:25]
	s_mov_b32 m0, s17
	s_nop 0
	global_load_lds_dwordx4 v[150:151], off
	v_lshl_add_u64 v[150:151], v[232:233], 0, s[24:25]
	s_add_i32 m0, s17, 0x2000
	s_nop 0
	global_load_lds_dwordx4 v[150:151], off
	v_lshl_add_u64 v[150:151], v[234:235], 0, s[24:25]
	s_mov_b32 m0, s66
	s_nop 0
	global_load_lds_dwordx4 v[150:151], off
	v_lshl_add_u64 v[150:151], v[236:237], 0, s[24:25]
	s_mov_b32 m0, s67
	s_nop 0
	global_load_lds_dwordx4 v[150:151], off
	s_waitcnt vmcnt(8)
	s_waitcnt lgkmcnt(0)
	s_barrier
	s_setprio 1
	v_mfma_f32_16x16x32_bf16 v[62:65], v[142:145], v[180:183], v[62:65]
	v_mfma_f32_16x16x32_bf16 v[58:61], v[154:157], v[180:183], v[58:61]
	v_mfma_f32_16x16x32_bf16 v[46:49], v[142:145], v[188:191], v[46:49]
	v_mfma_f32_16x16x32_bf16 v[42:45], v[154:157], v[188:191], v[42:45]
	v_mfma_f32_16x16x32_bf16 v[30:33], v[142:145], v[212:215], v[30:33]
	v_mfma_f32_16x16x32_bf16 v[26:29], v[154:157], v[212:215], v[26:29]
	v_mfma_f32_16x16x32_bf16 v[14:17], v[142:145], v[220:223], v[14:17]
	v_mfma_f32_16x16x32_bf16 v[10:13], v[154:157], v[220:223], v[10:13]
	v_mfma_f32_16x16x32_bf16 v[62:65], v[146:149], v[184:187], v[62:65]
	v_mfma_f32_16x16x32_bf16 v[58:61], v[160:163], v[184:187], v[58:61]
	v_mfma_f32_16x16x32_bf16 v[46:49], v[146:149], v[208:211], v[46:49]
	v_mfma_f32_16x16x32_bf16 v[42:45], v[160:163], v[208:211], v[42:45]
	v_mfma_f32_16x16x32_bf16 v[30:33], v[146:149], v[216:219], v[30:33]
	v_mfma_f32_16x16x32_bf16 v[26:29], v[160:163], v[216:219], v[26:29]
	v_mfma_f32_16x16x32_bf16 v[14:17], v[146:149], v[228:231], v[14:17]
	v_mfma_f32_16x16x32_bf16 v[10:13], v[160:163], v[228:231], v[10:13]
	v_mfma_f32_16x16x32_bf16 v[54:57], v[164:167], v[180:183], v[54:57]
	v_mfma_f32_16x16x32_bf16 v[50:53], v[172:175], v[180:183], v[50:53]
	v_mfma_f32_16x16x32_bf16 v[38:41], v[164:167], v[188:191], v[38:41]
	v_mfma_f32_16x16x32_bf16 v[34:37], v[172:175], v[188:191], v[34:37]
	v_mfma_f32_16x16x32_bf16 v[22:25], v[164:167], v[212:215], v[22:25]
	v_mfma_f32_16x16x32_bf16 v[18:21], v[172:175], v[212:215], v[18:21]
	v_mfma_f32_16x16x32_bf16 v[6:9], v[164:167], v[220:223], v[6:9]
	v_mfma_f32_16x16x32_bf16 v[2:5], v[172:175], v[220:223], v[2:5]
	v_mfma_f32_16x16x32_bf16 v[54:57], v[168:171], v[184:187], v[54:57]
	v_mfma_f32_16x16x32_bf16 v[50:53], v[176:179], v[184:187], v[50:53]
	v_mfma_f32_16x16x32_bf16 v[38:41], v[168:171], v[208:211], v[38:41]
	v_mfma_f32_16x16x32_bf16 v[34:37], v[176:179], v[208:211], v[34:37]
	v_mfma_f32_16x16x32_bf16 v[22:25], v[168:171], v[216:219], v[22:25]
	v_mfma_f32_16x16x32_bf16 v[18:21], v[176:179], v[216:219], v[18:21]
	v_mfma_f32_16x16x32_bf16 v[6:9], v[168:171], v[228:231], v[6:9]
	v_mfma_f32_16x16x32_bf16 v[2:5], v[176:179], v[228:231], v[2:5]
	s_setprio 0
	s_barrier
	s_add_u32 s34, s34, 0x100
	s_addc_u32 s35, s35, 0
	s_add_u32 s4, s4, 0x100
	s_addc_u32 s16, s16, 0
	s_cmp_ge_i32 s22, s18
	s_mov_b32 s17, s22
	s_cbranch_scc0 .LBB0_1853
